# all 16-byte stores inside the layer loop made write-through (sc1) so the grid barrier's L2 writeback has less to flush
# baseline (speedup 1.0000x reference)
.LBB0_171:
	s_or_b64 exec, exec, s[12:13]
	v_mov_b32_e32 v49, s17
	s_waitcnt lgkmcnt(0)
	s_barrier
	ds_read_b96 v[50:52], v49
	v_mov_b32_e32 v49, s18
	s_waitcnt vmcnt(4)
	v_pk_add_f32 v[18:19], v[18:19], 1.0 op_sel_hi:[1,0]
	v_pk_add_f32 v[16:17], v[16:17], 1.0 op_sel_hi:[1,0]
	v_pk_add_f32 v[8:9], v[8:9], 1.0 op_sel_hi:[1,0]
	s_waitcnt lgkmcnt(0)
	v_mov_b32_e32 v54, v51
	ds_read_b32 v51, v49
	v_mov_b32_e32 v55, v52
	v_pk_add_f32 v[10:11], v[10:11], 1.0 op_sel_hi:[1,0]
	s_add_i32 s4, s10, 0x2000
	s_ashr_i32 s5, s4, 31
	s_waitcnt lgkmcnt(0)
	v_pk_add_f32 v[50:51], v[54:55], v[50:51]
	s_lshl_b64 s[4:5], s[4:5], 12
	v_add_f32_e32 v49, v50, v51
	v_fmamk_f32 v49, v49, 0x3a000000, v196
	v_rsq_f32_e32 v50, v49
	s_add_i32 s2, s2, s19
	s_cmpk_lt_i32 s2, 0x200
	v_pk_mul_f32 v[26:27], v[26:27], v[50:51] op_sel_hi:[1,0]
	v_pk_mul_f32 v[24:25], v[24:25], v[50:51] op_sel_hi:[1,0]
	v_pk_mul_f32 v[6:7], v[6:7], v[26:27]
	v_pk_mul_f32 v[4:5], v[4:5], v[24:25]
	s_waitcnt vmcnt(2)
	v_pk_fma_f32 v[6:7], v[18:19], v[6:7], v[22:23]
	v_pk_fma_f32 v[4:5], v[16:17], v[4:5], v[20:21]
	v_pk_mul_f32 v[16:17], v[30:31], v[50:51] op_sel_hi:[1,0]
	v_pk_mul_f32 v[18:19], v[28:29], v[50:51] op_sel_hi:[1,0]
	v_pk_mul_f32 v[2:3], v[2:3], v[16:17]
	v_pk_mul_f32 v[0:1], v[0:1], v[18:19]
	v_pk_fma_f32 v[10:11], v[10:11], v[2:3], v[14:15]
	v_pk_fma_f32 v[2:3], v[8:9], v[0:1], v[12:13]
	v_bfe_u32 v0, v4, 16, 1
	v_add3_u32 v0, v4, v0, s78
	v_bfe_u32 v1, v5, 16, 1
	v_lshrrev_b32_e32 v0, 16, v0
	v_add3_u32 v1, v5, v1, s78
	v_and_or_b32 v0, v1, s79, v0
	v_bfe_u32 v1, v6, 16, 1
	v_add3_u32 v1, v6, v1, s78
	v_bfe_u32 v4, v7, 16, 1
	v_lshrrev_b32_e32 v1, 16, v1
	v_add3_u32 v4, v7, v4, s78
	v_and_or_b32 v1, v4, s79, v1
	v_bfe_u32 v4, v2, 16, 1
	v_add3_u32 v2, v2, v4, s78
	v_bfe_u32 v4, v3, 16, 1
	v_lshrrev_b32_e32 v2, 16, v2
	v_add3_u32 v3, v3, v4, s78
	v_and_or_b32 v2, v3, s79, v2
	v_bfe_u32 v3, v10, 16, 1
	v_add3_u32 v3, v10, v3, s78
	v_bfe_u32 v4, v11, 16, 1
	v_lshrrev_b32_e32 v3, 16, v3
	v_add3_u32 v4, v11, v4, s78
	v_and_or_b32 v3, v4, s79, v3
	v_lshl_add_u64 v[4:5], v[34:35], 0, s[4:5]
	global_store_dwordx4 v[4:5], v[0:3], off sc1
	s_barrier
	s_cbranch_scc0 .LBB0_174
.LBB0_172:
	s_add_i32 s10, s93, s2
	s_ashr_i32 s11, s10, 31
	s_lshl_b64 s[12:13], s[10:11], 13
	v_lshl_add_u64 v[0:1], v[44:45], 0, s[12:13]
	v_add_co_u32_e32 v2, vcc, 0x400000, v0
	s_mov_b64 s[4:5], 0x400000
	s_nop 0
	v_addc_co_u32_e32 v3, vcc, 0, v1, vcc
	v_lshl_add_u64 v[14:15], v[0:1], 0, s[4:5]
	global_load_dwordx4 v[2:5], v[2:3], off
	s_nop 0
	global_load_dwordx4 v[6:9], v[0:1], off
	global_load_dwordx4 v[10:13], v[0:1], off offset:16
	v_add_co_u32_e32 v18, vcc, 0x800000, v0
	global_load_dwordx4 v[14:17], v[14:15], off offset:16
	s_nop 0
	v_addc_co_u32_e32 v19, vcc, 0, v1, vcc
	v_add_co_u32_e32 v22, vcc, 0xc00000, v0
	global_load_dwordx4 v[18:21], v[18:19], off
	s_nop 0
	v_addc_co_u32_e32 v23, vcc, 0, v1, vcc
	global_load_dwordx4 v[22:25], v[22:23], off
	s_mov_b64 s[4:5], 0x800000
	v_add_co_u32_e32 v54, vcc, 0x1000000, v0
	v_lshl_add_u64 v[26:27], v[0:1], 0, s[4:5]
	s_mov_b64 s[4:5], 0xc00000
	v_addc_co_u32_e32 v55, vcc, 0, v1, vcc
	v_lshl_add_u64 v[30:31], v[0:1], 0, s[4:5]
	s_mov_b64 s[4:5], 0x1000000
	v_add_co_u32_e32 v62, vcc, 0x1400000, v0
	global_load_dwordx4 v[26:29], v[26:27], off offset:16
	s_nop 0
	global_load_dwordx4 v[50:53], v[30:31], off offset:16
	v_lshl_add_u64 v[30:31], v[0:1], 0, s[4:5]
	v_addc_co_u32_e32 v63, vcc, 0, v1, vcc
	global_load_dwordx4 v[54:57], v[54:55], off
	s_nop 0
	global_load_dwordx4 v[58:61], v[30:31], off offset:16
	v_add_co_u32_e32 v30, vcc, 0x1800000, v0
	s_mov_b64 s[4:5], 0x1400000
	s_nop 0
	v_addc_co_u32_e32 v31, vcc, 0, v1, vcc
	v_add_co_u32_e32 v72, vcc, 0x1c00000, v0
	v_lshl_add_u64 v[66:67], v[0:1], 0, s[4:5]
	s_nop 0
	v_addc_co_u32_e32 v73, vcc, 0, v1, vcc
	global_load_dwordx4 v[62:65], v[62:63], off
	s_nop 0
	global_load_dwordx4 v[66:69], v[66:67], off offset:16
	s_mov_b64 s[4:5], 0x1800000
	s_waitcnt vmcnt(0)
	v_pk_add_f32 v[70:71], v[8:9], v[4:5]
	v_pk_add_f32 v[2:3], v[6:7], v[2:3]
	global_load_dwordx4 v[4:7], v[30:31], off
	s_waitcnt vmcnt(9)
	v_pk_add_f32 v[30:31], v[12:13], v[16:17]
	v_pk_add_f32 v[8:9], v[10:11], v[14:15]
	global_load_dwordx4 v[10:13], v[72:73], off
	v_add_co_u32_e32 v14, vcc, 0x2000000, v0
	s_waitcnt vmcnt(8)
	v_pk_add_f32 v[74:75], v[18:19], v[22:23]
	v_addc_co_u32_e32 v15, vcc, 0, v1, vcc
	v_add_co_u32_e32 v18, vcc, 0x2400000, v0
	v_pk_add_f32 v[72:73], v[20:21], v[24:25]
	s_nop 0
	v_addc_co_u32_e32 v19, vcc, 0, v1, vcc
	global_load_dwordx4 v[14:17], v[14:15], off
	v_lshl_add_u64 v[22:23], v[0:1], 0, s[4:5]
	global_load_dwordx4 v[18:21], v[18:19], off
	s_mov_b64 s[4:5], 0x1c00000
	s_waitcnt vmcnt(8)
	v_pk_add_f32 v[78:79], v[26:27], v[50:51]
	v_lshl_add_u64 v[26:27], v[0:1], 0, s[4:5]
	s_mov_b64 s[4:5], 0x2000000
	v_lshl_add_u64 v[50:51], v[0:1], 0, s[4:5]
	s_mov_b64 s[4:5], 0x2400000
	v_pk_add_f32 v[76:77], v[28:29], v[52:53]
	global_load_dwordx4 v[22:25], v[22:23], off offset:16
	s_nop 0
	global_load_dwordx4 v[26:29], v[26:27], off offset:16
	s_waitcnt vmcnt(7)
	v_pk_add_f32 v[64:65], v[56:57], v[64:65]
	s_waitcnt vmcnt(6)
	v_pk_add_f32 v[80:81], v[60:61], v[68:69]
	v_pk_add_f32 v[82:83], v[58:59], v[66:67]
	v_pk_add_f32 v[62:63], v[54:55], v[62:63]
	s_waitcnt vmcnt(4)
	v_pk_add_f32 v[60:61], v[4:5], v[10:11]
	v_lshl_add_u64 v[4:5], v[0:1], 0, s[4:5]
	v_pk_add_f32 v[58:59], v[6:7], v[12:13]
	global_load_dwordx4 v[10:13], v[50:51], off offset:16
	s_nop 0
	global_load_dwordx4 v[50:53], v[4:5], off offset:16
	v_add_co_u32_e32 v4, vcc, 0x2800000, v0
	s_mov_b64 s[4:5], 0x2800000
	s_nop 0
	v_addc_co_u32_e32 v5, vcc, 0, v1, vcc
	global_load_dwordx4 v[4:7], v[4:5], off
	v_lshl_add_u64 v[0:1], v[0:1], 0, s[4:5]
	global_load_dwordx4 v[54:57], v[0:1], off offset:16
	v_pk_add_f32 v[0:1], v[2:3], v[74:75]
	v_lshl_add_u64 v[2:3], v[46:47], 0, s[12:13]
	global_load_dwordx4 v[66:69], v[2:3], off offset:16
	s_waitcnt vmcnt(7)
	v_pk_add_f32 v[16:17], v[16:17], v[20:21]
	v_pk_add_f32 v[14:15], v[14:15], v[18:19]
	v_pk_add_f32 v[18:19], v[70:71], v[72:73]
	v_pk_add_f32 v[20:21], v[64:65], v[58:59]
	v_pk_add_f32 v[70:71], v[62:63], v[60:61]
	global_load_dwordx4 v[58:61], v[2:3], off
	global_load_dwordx4 v[62:65], v[36:37], off
	v_pk_add_f32 v[0:1], v[0:1], v[70:71]
	global_load_dwordx4 v[70:73], v[36:37], off offset:16
	s_waitcnt vmcnt(6)
	v_pk_add_f32 v[12:13], v[12:13], v[52:53]
	s_waitcnt vmcnt(5)
	v_pk_add_f32 v[6:7], v[16:17], v[6:7]
	v_pk_add_f32 v[4:5], v[14:15], v[4:5]
	v_pk_add_f32 v[14:15], v[18:19], v[20:21]
	v_pk_add_f32 v[16:17], v[24:25], v[28:29]
	v_pk_add_f32 v[74:75], v[14:15], v[6:7]
	v_pk_add_f32 v[14:15], v[30:31], v[76:77]
	v_pk_add_f32 v[20:21], v[22:23], v[26:27]
	v_pk_add_f32 v[22:23], v[80:81], v[16:17]
	v_pk_add_f32 v[84:85], v[0:1], v[4:5]
	global_load_dwordx4 v[0:3], v[38:39], off offset:16
	global_load_dwordx4 v[4:7], v[38:39], off
	v_pk_add_f32 v[24:25], v[8:9], v[78:79]
	v_pk_add_f32 v[26:27], v[10:11], v[50:51]
	global_load_dwordx4 v[8:11], v[40:41], off offset:16
	global_load_dwordx4 v[16:19], v[40:41], off
	v_pk_add_f32 v[28:29], v[82:83], v[20:21]
	v_pk_add_f32 v[30:31], v[14:15], v[22:23]
	s_waitcnt vmcnt(8)
	v_pk_add_f32 v[50:51], v[12:13], v[56:57]
	global_load_dwordx4 v[12:15], v[42:43], off offset:16
	global_load_dwordx4 v[20:23], v[42:43], off
	v_pk_add_f32 v[26:27], v[26:27], v[54:55]
	v_pk_add_f32 v[24:25], v[24:25], v[28:29]
	v_pk_add_f32 v[28:29], v[30:31], v[50:51]
	v_pk_add_f32 v[50:51], v[24:25], v[26:27]
	s_waitcnt vmcnt(7)
	v_pk_fma_f32 v[26:27], v[64:65], v[74:75], v[60:61]
	v_pk_fma_f32 v[24:25], v[62:63], v[84:85], v[58:59]
	v_mul_f32_e32 v31, v27, v27
	v_mul_f32_e32 v30, v25, v25
	v_fmac_f32_e32 v30, v24, v24
	v_fmac_f32_e32 v31, v26, v26
	v_add_f32_e32 v49, v30, v31
	s_waitcnt vmcnt(6)
	v_pk_fma_f32 v[30:31], v[72:73], v[28:29], v[68:69]
	v_pk_fma_f32 v[28:29], v[70:71], v[50:51], v[66:67]
	v_mul_f32_e32 v51, v31, v31
	v_mul_f32_e32 v50, v29, v29
	v_fmac_f32_e32 v50, v28, v28
	v_fmac_f32_e32 v51, v30, v30
	v_add_f32_e32 v50, v50, v51
	v_add_f32_e32 v49, v49, v50
	v_lshl_add_u64 v[50:51], v[32:33], 0, s[12:13]
	global_store_dwordx4 v[50:51], v[24:27], off sc1
	global_store_dwordx4 v[50:51], v[28:31], off offset:16 sc1
	v_add_f32_dpp v49, v49, v49 quad_perm:[1,0,3,2] row_mask:0xf bank_mask:0xf bound_ctrl:1
	s_nop 1
	v_add_f32_dpp v49, v49, v49 quad_perm:[2,3,0,1] row_mask:0xf bank_mask:0xf bound_ctrl:1
	s_nop 1
	v_add_f32_dpp v49, v49, v49 row_half_mirror row_mask:0xf bank_mask:0xf bound_ctrl:1
	s_nop 1
	v_add_f32_dpp v49, v49, v49 row_mirror row_mask:0xf bank_mask:0xf bound_ctrl:1
	v_cvt_i32_f32_e32 v49, v49
	s_nop 0
	v_readlane_b32 s3, v49, 0
	v_readlane_b32 s4, v49, 16
	v_readlane_b32 s5, v49, 32
	v_readlane_b32 s6, v49, 48
	s_and_saveexec_b64 s[12:13], s[0:1]
	s_cbranch_execz .LBB0_171
	s_add_i32 s3, s4, s3
	s_add_i32 s3, s3, s5
	s_add_i32 s3, s3, s6
	v_cvt_f32_i32_e32 v49, s3
	v_mov_b32_e32 v50, s20
	ds_write_b32 v50, v49
	s_branch .LBB0_171

.LBB0_249:
	v_readlane_b32 s2, v251, 29
	v_lshl_or_b32 v142, s46, 8, v146
	v_readlane_b32 s3, v251, 30
	v_ashrrev_i32_e32 v143, 31, v142
	v_lshl_add_u32 v150, s45, 8, v144
	v_mov_b64_e32 v[140:141], s[2:3]
	s_movk_i32 s6, 0x1e00
	v_mad_i64_i32 v[148:149], s[2:3], v150, s6, v[140:141]
	v_lshlrev_b64 v[142:143], 1, v[142:143]
	v_lshl_add_u64 v[148:149], v[148:149], 0, v[142:143]
	v_cvt_pk_bf16_f32 v126, v126, v127
	v_cvt_pk_bf16_f32 v127, v128, v129
	v_cvt_pk_bf16_f32 v128, v122, v123
	v_cvt_pk_bf16_f32 v129, v124, v125
	global_store_dwordx4 v[148:149], v[126:129], off sc1
	v_cvt_pk_bf16_f32 v114, v114, v115
	v_cvt_pk_bf16_f32 v115, v116, v117
	v_cvt_pk_bf16_f32 v116, v106, v107
	v_or_b32_e32 v106, 16, v150
	v_mad_i64_i32 v[106:107], s[2:3], v106, s6, v[140:141]
	v_cvt_pk_bf16_f32 v117, v108, v109
	global_store_dwordx4 v[148:149], v[114:117], off offset:256 sc1
	s_andn2_b64 vcc, exec, s[0:1]
	s_mov_b64 s[0:1], -1
	v_lshl_add_u64 v[114:115], v[106:107], 0, v[142:143]
	v_cvt_pk_bf16_f32 v106, v118, v119
	v_cvt_pk_bf16_f32 v107, v120, v121
	v_cvt_pk_bf16_f32 v108, v110, v111
	v_cvt_pk_bf16_f32 v109, v112, v113
	global_store_dwordx4 v[114:115], v[106:109], off sc1
	v_cvt_pk_bf16_f32 v98, v98, v99
	v_cvt_pk_bf16_f32 v99, v100, v101
	v_cvt_pk_bf16_f32 v100, v88, v89
	v_or_b32_e32 v88, 32, v150
	v_mad_i64_i32 v[88:89], s[2:3], v88, s6, v[140:141]
	v_cvt_pk_bf16_f32 v101, v90, v91
	global_store_dwordx4 v[114:115], v[98:101], off offset:256 sc1
	s_nop 1
	v_lshl_add_u64 v[98:99], v[88:89], 0, v[142:143]
	v_cvt_pk_bf16_f32 v88, v102, v103
	v_cvt_pk_bf16_f32 v89, v104, v105
	v_cvt_pk_bf16_f32 v90, v92, v93
	v_cvt_pk_bf16_f32 v91, v94, v95
	global_store_dwordx4 v[98:99], v[88:91], off sc1
	v_cvt_pk_bf16_f32 v80, v80, v81
	v_cvt_pk_bf16_f32 v81, v82, v83
	v_cvt_pk_bf16_f32 v82, v72, v73
	v_or_b32_e32 v72, 48, v150
	v_mad_i64_i32 v[72:73], s[2:3], v72, s6, v[140:141]
	v_cvt_pk_bf16_f32 v83, v74, v75
	global_store_dwordx4 v[98:99], v[80:83], off offset:256 sc1
	s_nop 1
	v_lshl_add_u64 v[80:81], v[72:73], 0, v[142:143]
	v_cvt_pk_bf16_f32 v72, v84, v85
	v_cvt_pk_bf16_f32 v73, v86, v87
	v_cvt_pk_bf16_f32 v74, v76, v77
	v_cvt_pk_bf16_f32 v75, v78, v79
	global_store_dwordx4 v[80:81], v[72:75], off sc1
	v_cvt_pk_bf16_f32 v68, v68, v69
	v_cvt_pk_bf16_f32 v69, v70, v71
	v_cvt_pk_bf16_f32 v70, v64, v65
	v_add_u32_e32 v64, 0x80, v150
	v_mad_i64_i32 v[64:65], s[2:3], v64, s6, v[140:141]
	v_lshl_add_u64 v[64:65], v[64:65], 0, v[142:143]
	v_cvt_pk_bf16_f32 v71, v66, v67
	global_store_dwordx4 v[80:81], v[68:71], off offset:256 sc1
	v_cvt_pk_bf16_f32 v60, v60, v61
	v_cvt_pk_bf16_f32 v61, v62, v63
	v_cvt_pk_bf16_f32 v62, v56, v57
	v_cvt_pk_bf16_f32 v63, v58, v59
	global_store_dwordx4 v[64:65], v[60:63], off sc1
	v_cvt_pk_bf16_f32 v48, v48, v49
	v_cvt_pk_bf16_f32 v49, v50, v51
	v_cvt_pk_bf16_f32 v50, v40, v41
	v_add_u32_e32 v40, 0x90, v150
	v_mad_i64_i32 v[40:41], s[2:3], v40, s6, v[140:141]
	v_cvt_pk_bf16_f32 v51, v42, v43
	global_store_dwordx4 v[64:65], v[48:51], off offset:256 sc1
	s_nop 1
	v_lshl_add_u64 v[48:49], v[40:41], 0, v[142:143]
	v_cvt_pk_bf16_f32 v40, v52, v53
	v_cvt_pk_bf16_f32 v41, v54, v55
	v_cvt_pk_bf16_f32 v42, v44, v45
	v_cvt_pk_bf16_f32 v43, v46, v47
	global_store_dwordx4 v[48:49], v[40:43], off sc1
	v_cvt_pk_bf16_f32 v32, v32, v33
	v_cvt_pk_bf16_f32 v33, v34, v35
	v_cvt_pk_bf16_f32 v34, v24, v25
	v_add_u32_e32 v24, 0xa0, v150
	v_mad_i64_i32 v[24:25], s[2:3], v24, s6, v[140:141]
	v_cvt_pk_bf16_f32 v35, v26, v27
	global_store_dwordx4 v[48:49], v[32:35], off offset:256 sc1
	s_nop 1
	v_lshl_add_u64 v[32:33], v[24:25], 0, v[142:143]
	v_cvt_pk_bf16_f32 v24, v36, v37
	v_cvt_pk_bf16_f32 v25, v38, v39
	v_cvt_pk_bf16_f32 v26, v28, v29
	v_cvt_pk_bf16_f32 v27, v30, v31
	global_store_dwordx4 v[32:33], v[24:27], off sc1
	v_cvt_pk_bf16_f32 v16, v16, v17
	v_cvt_pk_bf16_f32 v17, v18, v19
	v_cvt_pk_bf16_f32 v18, v8, v9
	v_add_u32_e32 v8, 0xb0, v150
	v_mad_i64_i32 v[8:9], s[2:3], v8, s6, v[140:141]
	v_cvt_pk_bf16_f32 v19, v10, v11
	global_store_dwordx4 v[32:33], v[16:19], off offset:256 sc1
	s_nop 1
	v_lshl_add_u64 v[16:17], v[8:9], 0, v[142:143]
	v_cvt_pk_bf16_f32 v8, v20, v21
	v_cvt_pk_bf16_f32 v9, v22, v23
	v_cvt_pk_bf16_f32 v10, v12, v13
	v_cvt_pk_bf16_f32 v11, v14, v15
	global_store_dwordx4 v[16:17], v[8:11], off sc1
	v_cvt_pk_bf16_f32 v4, v4, v5
	v_cvt_pk_bf16_f32 v5, v6, v7
	v_cvt_pk_bf16_f32 v6, v0, v1
	v_cvt_pk_bf16_f32 v7, v2, v3
	global_store_dwordx4 v[16:17], v[4:7], off offset:256 sc1
	s_cbranch_vccnz .LBB0_238
	s_andn2_b64 vcc, exec, s[8:9]
	s_cbranch_vccnz .LBB0_237
	s_barrier
	s_branch .LBB0_237

.LBB0_310:
	s_or_b64 exec, exec, s[8:9]
	v_lshlrev_b32_e32 v53, 16, v49
	v_lshlrev_b32_e32 v52, 16, v48
	v_and_b32_e32 v49, 0xffff0000, v49
	v_and_b32_e32 v48, 0xffff0000, v48
	v_mov_b32_e32 v54, v49
	v_mov_b32_e32 v55, v53
	v_mul_f32_e32 v62, v52, v52
	v_pk_mul_f32 v[54:55], v[54:55], v[54:55]
	v_lshlrev_b32_e32 v56, 16, v50
	v_and_b32_e32 v50, 0xffff0000, v50
	v_fmac_f32_e32 v62, v48, v48
	v_mov_b32_e32 v58, v50
	v_mov_b32_e32 v59, v56
	v_add_f32_e32 v55, v55, v62
	v_lshlrev_b32_e32 v57, 16, v51
	v_and_b32_e32 v51, 0xffff0000, v51
	v_pk_mul_f32 v[58:59], v[58:59], v[58:59]
	v_add_f32_e32 v54, v54, v55
	v_mov_b32_e32 v60, v51
	v_mov_b32_e32 v61, v57
	v_add_f32_e32 v54, v59, v54
	v_pk_mul_f32 v[60:61], v[60:61], v[60:61]
	v_add_f32_e32 v54, v58, v54
	v_add_f32_e32 v54, v61, v54
	v_add_f32_e32 v54, v60, v54
	v_lshlrev_b64 v[58:59], 6, v[72:73]
	v_lshlrev_b64 v[58:59], 1, v[58:59]
	v_add_f32_dpp v54, v54, v54 quad_perm:[1,0,3,2] row_mask:0xf bank_mask:0xf bound_ctrl:1
	v_readlane_b32 s2, v253, 47
	v_readlane_b32 s3, v253, 48
	v_add_f32_dpp v54, v54, v54 quad_perm:[2,3,0,1] row_mask:0xf bank_mask:0xf bound_ctrl:1
	v_readlane_b32 s6, v254, 9
	v_lshl_add_u64 v[150:151], v[150:151], 0, s[2:3]
	v_add_f32_dpp v54, v54, v54 row_half_mirror row_mask:0xf bank_mask:0xf bound_ctrl:1
	v_fmamk_f32 v54, v54, 0x3c800000, v196
	v_rsq_f32_e32 v54, v54
	v_readlane_b32 s2, v253, 51
	v_readlane_b32 s3, v253, 52
	s_add_i32 s4, s4, s92
	v_pk_mul_f32 v[50:51], v[54:55], v[50:51] op_sel_hi:[0,1]
	v_pk_mul_f32 v[52:53], v[54:55], v[52:53] op_sel_hi:[0,1]
	v_pk_mul_f32 v[48:49], v[54:55], v[48:49] op_sel_hi:[0,1]
	v_pk_mul_f32 v[50:51], v[14:15], v[50:51]
	v_pk_mul_f32 v[52:53], v[12:13], v[52:53]
	v_pk_mul_f32 v[48:49], v[2:3], v[48:49]
	v_pk_mul_f32 v[56:57], v[54:55], v[56:57] op_sel_hi:[0,1]
	v_bfe_u32 v54, v51, 16, 1
	v_bfe_u32 v55, v50, 16, 1
	v_pk_mul_f32 v[56:57], v[8:9], v[56:57]
	v_bfe_u32 v60, v49, 16, 1
	v_bfe_u32 v61, v48, 16, 1
	v_add3_u32 v50, v50, v55, s78
	v_add3_u32 v51, v51, v54, s78
	v_bfe_u32 v54, v52, 16, 1
	v_bfe_u32 v55, v53, 16, 1
	v_add3_u32 v48, v48, v61, s78
	v_add3_u32 v49, v49, v60, s78
	v_bfe_u32 v60, v56, 16, 1
	v_bfe_u32 v61, v57, 16, 1
	v_add3_u32 v53, v53, v55, s78
	v_add3_u32 v52, v52, v54, s78
	v_add3_u32 v57, v57, v61, s78
	v_add3_u32 v56, v56, v60, s78
	v_lshrrev_b32_e32 v52, 16, v52
	v_lshrrev_b32_e32 v53, 16, v53
	v_lshrrev_b32_e32 v54, 16, v56
	v_lshrrev_b32_e32 v55, 16, v57
	v_and_or_b32 v49, v49, s79, v53
	v_and_or_b32 v48, v48, s79, v52
	v_lshlrev_b32_e32 v53, 16, v45
	v_lshlrev_b32_e32 v52, 16, v44
	v_and_b32_e32 v45, 0xffff0000, v45
	v_and_or_b32 v51, v51, s79, v55
	v_and_or_b32 v50, v50, s79, v54
	v_and_b32_e32 v44, 0xffff0000, v44
	v_mov_b32_e32 v54, v45
	v_mov_b32_e32 v55, v53
	v_mul_f32_e32 v64, v52, v52
	v_pk_mul_f32 v[54:55], v[54:55], v[54:55]
	v_lshlrev_b32_e32 v56, 16, v46
	v_and_b32_e32 v46, 0xffff0000, v46
	v_fmac_f32_e32 v64, v44, v44
	v_mov_b32_e32 v60, v46
	v_mov_b32_e32 v61, v56
	v_add_f32_e32 v55, v55, v64
	v_lshlrev_b32_e32 v57, 16, v47
	v_and_b32_e32 v47, 0xffff0000, v47
	v_pk_mul_f32 v[60:61], v[60:61], v[60:61]
	v_add_f32_e32 v54, v54, v55
	v_mov_b32_e32 v62, v47
	v_mov_b32_e32 v63, v57
	v_add_f32_e32 v54, v61, v54
	v_pk_mul_f32 v[62:63], v[62:63], v[62:63]
	v_add_f32_e32 v54, v60, v54
	v_add_f32_e32 v54, v63, v54
	v_add_f32_e32 v54, v62, v54
	v_lshl_add_u64 v[60:61], v[142:143], 0, v[58:59]
	global_store_dwordx4 v[60:61], v[48:51], off sc1
	v_add_f32_dpp v54, v54, v54 quad_perm:[1,0,3,2] row_mask:0xf bank_mask:0xf bound_ctrl:1
	v_lshl_add_u64 v[152:153], v[152:153], 0, s[2:3]
	v_readlane_b32 s2, v253, 58
	v_add_f32_dpp v54, v54, v54 quad_perm:[2,3,0,1] row_mask:0xf bank_mask:0xf bound_ctrl:1
	v_readlane_b32 s7, v254, 10
	v_readlane_b32 s3, v253, 59
	v_add_f32_dpp v54, v54, v54 row_half_mirror row_mask:0xf bank_mask:0xf bound_ctrl:1
	v_fmamk_f32 v54, v54, 0x3c800000, v196
	v_rsq_f32_e32 v54, v54
	v_lshl_add_u64 v[26:27], v[26:27], 0, s[6:7]
	v_lshl_add_u64 v[154:155], v[154:155], 0, s[2:3]
	v_lshl_add_u64 v[156:157], v[156:157], 0, s[6:7]
	v_pk_mul_f32 v[44:45], v[54:55], v[44:45] op_sel_hi:[0,1]
	v_pk_mul_f32 v[46:47], v[54:55], v[46:47] op_sel_hi:[0,1]
	v_pk_mul_f32 v[48:49], v[54:55], v[52:53] op_sel_hi:[0,1]
	v_pk_mul_f32 v[44:45], v[148:149], v[44:45]
	v_pk_mul_f32 v[50:51], v[54:55], v[56:57] op_sel_hi:[0,1]
	v_pk_mul_f32 v[46:47], v[6:7], v[46:47]
	v_pk_mul_f32 v[48:49], v[4:5], v[48:49]
	v_pk_mul_f32 v[50:51], v[0:1], v[50:51]
	v_bfe_u32 v52, v47, 16, 1
	v_bfe_u32 v53, v46, 16, 1
	v_bfe_u32 v54, v45, 16, 1
	v_bfe_u32 v55, v44, 16, 1
	v_add3_u32 v44, v44, v55, s78
	v_add3_u32 v45, v45, v54, s78
	v_add3_u32 v46, v46, v53, s78
	v_add3_u32 v47, v47, v52, s78
	v_bfe_u32 v52, v48, 16, 1
	v_bfe_u32 v53, v49, 16, 1
	v_bfe_u32 v54, v50, 16, 1
	v_bfe_u32 v55, v51, 16, 1
	v_add3_u32 v51, v51, v55, s78
	v_add3_u32 v50, v50, v54, s78
	v_add3_u32 v49, v49, v53, s78
	v_add3_u32 v48, v48, v52, s78
	v_lshrrev_b32_e32 v48, 16, v48
	v_lshrrev_b32_e32 v49, 16, v49
	v_lshrrev_b32_e32 v50, 16, v50
	v_lshrrev_b32_e32 v51, 16, v51
	v_and_or_b32 v47, v47, s79, v51
	v_and_or_b32 v46, v46, s79, v50
	v_and_or_b32 v45, v45, s79, v49
	v_and_or_b32 v44, v44, s79, v48
	v_lshl_add_u64 v[48:49], v[144:145], 0, v[58:59]
	v_lshl_add_u64 v[158:159], v[158:159], 0, s[6:7]
	s_cmpk_gt_i32 s4, 0x21ff
	v_lshl_add_u64 v[160:161], v[160:161], 0, s[6:7]
	global_store_dwordx4 v[48:49], v[44:47], off sc1
	s_cbranch_scc1 .LBB0_330

.LBB0_322:
	s_add_i32 s6, s4, 0xffffe000
	s_ashr_i32 s5, s4, 12
	s_lshr_b32 s8, s6, 8
	v_add_u32_e32 v85, s2, v168
	s_and_b64 s[6:7], s[52:53], exec
	s_waitcnt vmcnt(3)
	v_lshlrev_b32_e32 v96, 16, v84
	v_sub_u32_e32 v84, s2, v168
	v_min_i32_e32 v183, s3, v85
	s_cselect_b32 s5, s8, s5
	s_or_b32 s8, s2, 0x1000
	v_max_i32_e32 v184, 0, v84
	v_add_u32_e32 v130, -1, v183
	s_and_b64 s[6:7], s[52:53], exec
	v_min_i32_e32 v84, v184, v130
	s_movk_i32 s3, 0x1e00
	s_cselect_b32 s40, s8, s2
	v_mad_i64_i32 v[84:85], s[6:7], v84, s3, 0
	s_mulk_i32 s2, 0x1e00
	v_subrev_co_u32_e32 v84, vcc, s2, v84
	s_mov_b32 s8, 0x1d300000
	s_nop 0
	v_subbrev_co_u32_e32 v85, vcc, 0, v85, vcc
	v_lshl_add_u64 v[84:85], v[26:27], 0, v[84:85]
	v_lshl_add_u64 v[84:85], s[70:71], 0, v[84:85]
	v_add_u32_e32 v185, 1, v184
	v_add_co_u32_e32 v84, vcc, s8, v84
	v_min_i32_e32 v86, v185, v130
	s_nop 0
	v_addc_co_u32_e32 v85, vcc, 0, v85, vcc
	v_mad_i64_i32 v[86:87], s[6:7], v86, s3, 0
	v_subrev_co_u32_e32 v86, vcc, s2, v86
	v_add_u32_e32 v198, 2, v184
	s_nop 0
	v_subbrev_co_u32_e32 v87, vcc, 0, v87, vcc
	v_lshl_add_u64 v[86:87], v[26:27], 0, v[86:87]
	v_lshl_add_u64 v[86:87], s[70:71], 0, v[86:87]
	v_add_co_u32_e32 v86, vcc, s8, v86
	v_add_u32_e32 v199, 3, v184
	s_nop 0
	v_addc_co_u32_e32 v87, vcc, 0, v87, vcc
	global_load_dwordx4 v[186:189], v[84:85], off offset:1664
	global_load_dwordx4 v[190:193], v[86:87], off offset:1664
	v_min_i32_e32 v84, v198, v130
	v_mad_i64_i32 v[84:85], s[6:7], v84, s3, 0
	v_subrev_co_u32_e32 v84, vcc, s2, v84
	v_min_i32_e32 v86, v199, v130
	s_nop 0
	v_subbrev_co_u32_e32 v85, vcc, 0, v85, vcc
	v_lshl_add_u64 v[84:85], v[26:27], 0, v[84:85]
	v_lshl_add_u64 v[84:85], s[70:71], 0, v[84:85]
	v_add_co_u32_e32 v84, vcc, s8, v84
	v_mad_i64_i32 v[86:87], s[6:7], v86, s3, 0
	s_nop 0
	v_addc_co_u32_e32 v85, vcc, 0, v85, vcc
	v_subrev_co_u32_e32 v86, vcc, s2, v86
	v_add_u32_e32 v200, 4, v184
	s_nop 0
	v_subbrev_co_u32_e32 v87, vcc, 0, v87, vcc
	v_lshl_add_u64 v[86:87], v[26:27], 0, v[86:87]
	v_lshl_add_u64 v[86:87], s[70:71], 0, v[86:87]
	v_add_co_u32_e32 v86, vcc, s8, v86
	v_add_u32_e32 v201, 5, v184
	s_nop 0
	v_addc_co_u32_e32 v87, vcc, 0, v87, vcc
	global_load_dwordx4 v[214:217], v[84:85], off offset:1664
	global_load_dwordx4 v[218:221], v[86:87], off offset:1664
	v_min_i32_e32 v84, v200, v130
	v_mad_i64_i32 v[84:85], s[6:7], v84, s3, 0
	v_subrev_co_u32_e32 v84, vcc, s2, v84
	v_min_i32_e32 v86, v201, v130
	s_nop 0
	v_subbrev_co_u32_e32 v85, vcc, 0, v85, vcc
	v_lshl_add_u64 v[84:85], v[26:27], 0, v[84:85]
	v_lshl_add_u64 v[84:85], s[70:71], 0, v[84:85]
	v_add_co_u32_e32 v84, vcc, s8, v84
	v_mad_i64_i32 v[86:87], s[6:7], v86, s3, 0
	s_nop 0
	v_addc_co_u32_e32 v85, vcc, 0, v85, vcc
	v_subrev_co_u32_e32 v86, vcc, s2, v86
	v_add_u32_e32 v223, 6, v184
	s_nop 0
	v_subbrev_co_u32_e32 v87, vcc, 0, v87, vcc
	v_lshl_add_u64 v[86:87], v[26:27], 0, v[86:87]
	v_lshl_add_u64 v[86:87], s[70:71], 0, v[86:87]
	v_add_co_u32_e32 v86, vcc, s8, v86
	v_min_i32_e32 v92, v223, v130
	s_nop 0
	v_addc_co_u32_e32 v87, vcc, 0, v87, vcc
	v_mad_i64_i32 v[92:93], s[6:7], v92, s3, 0
	v_subrev_co_u32_e32 v92, vcc, s2, v92
	v_add_u32_e32 v229, 7, v184
	s_nop 0
	v_subbrev_co_u32_e32 v93, vcc, 0, v93, vcc
	v_lshl_add_u64 v[92:93], v[26:27], 0, v[92:93]
	v_lshl_add_u64 v[92:93], s[70:71], 0, v[92:93]
	v_add_co_u32_e32 v92, vcc, s8, v92
	v_min_i32_e32 v94, v229, v130
	s_nop 0
	v_addc_co_u32_e32 v93, vcc, 0, v93, vcc
	v_mad_i64_i32 v[94:95], s[6:7], v94, s3, 0
	v_subrev_co_u32_e32 v94, vcc, s2, v94
	v_add_u32_e32 v231, 8, v184
	s_nop 0
	v_subbrev_co_u32_e32 v95, vcc, 0, v95, vcc
	v_lshl_add_u64 v[94:95], v[26:27], 0, v[94:95]
	v_lshl_add_u64 v[94:95], s[70:71], 0, v[94:95]
	v_add_co_u32_e32 v94, vcc, s8, v94
	global_load_dwordx4 v[88:91], v[84:85], off offset:1664
	s_nop 0
	global_load_dwordx4 v[84:87], v[86:87], off offset:1664
	v_addc_co_u32_e32 v95, vcc, 0, v95, vcc
	global_load_dwordx4 v[102:105], v[92:93], off offset:1664
	global_load_dwordx4 v[98:101], v[94:95], off offset:1664
	v_min_i32_e32 v92, v231, v130
	v_mad_i64_i32 v[92:93], s[6:7], v92, s3, 0
	v_subrev_co_u32_e32 v92, vcc, s2, v92
	v_add_u32_e32 v233, 9, v184
	s_nop 0
	v_subbrev_co_u32_e32 v93, vcc, 0, v93, vcc
	v_lshl_add_u64 v[92:93], v[26:27], 0, v[92:93]
	v_lshl_add_u64 v[92:93], s[70:71], 0, v[92:93]
	v_add_co_u32_e32 v92, vcc, s8, v92
	v_min_i32_e32 v94, v233, v130
	s_nop 0
	v_addc_co_u32_e32 v93, vcc, 0, v93, vcc
	v_mad_i64_i32 v[94:95], s[6:7], v94, s3, 0
	v_subrev_co_u32_e32 v94, vcc, s2, v94
	v_add_u32_e32 v235, 10, v184
	s_nop 0
	v_subbrev_co_u32_e32 v95, vcc, 0, v95, vcc
	v_lshl_add_u64 v[94:95], v[26:27], 0, v[94:95]
	v_lshl_add_u64 v[94:95], s[70:71], 0, v[94:95]
	v_add_co_u32_e32 v94, vcc, s8, v94
	v_add_u32_e32 v237, 11, v184
	s_nop 0
	v_addc_co_u32_e32 v95, vcc, 0, v95, vcc
	global_load_dwordx4 v[110:113], v[92:93], off offset:1664
	global_load_dwordx4 v[106:109], v[94:95], off offset:1664
	v_min_i32_e32 v92, v235, v130
	v_mad_i64_i32 v[92:93], s[6:7], v92, s3, 0
	v_subrev_co_u32_e32 v92, vcc, s2, v92
	v_min_i32_e32 v94, v237, v130
	s_nop 0
	v_subbrev_co_u32_e32 v93, vcc, 0, v93, vcc
	v_lshl_add_u64 v[92:93], v[26:27], 0, v[92:93]
	v_lshl_add_u64 v[92:93], s[70:71], 0, v[92:93]
	v_add_co_u32_e32 v92, vcc, s8, v92
	v_mad_i64_i32 v[94:95], s[6:7], v94, s3, 0
	s_nop 0
	v_addc_co_u32_e32 v93, vcc, 0, v93, vcc
	v_subrev_co_u32_e32 v94, vcc, s2, v94
	v_add_u32_e32 v239, 12, v184
	s_nop 0
	v_subbrev_co_u32_e32 v95, vcc, 0, v95, vcc
	v_lshl_add_u64 v[94:95], v[26:27], 0, v[94:95]
	v_lshl_add_u64 v[94:95], s[70:71], 0, v[94:95]
	v_add_co_u32_e32 v94, vcc, s8, v94
	v_add_u32_e32 v241, 13, v184
	s_nop 0
	v_addc_co_u32_e32 v95, vcc, 0, v95, vcc
	global_load_dwordx4 v[122:125], v[92:93], off offset:1664
	global_load_dwordx4 v[118:121], v[94:95], off offset:1664
	v_min_i32_e32 v92, v239, v130
	v_mad_i64_i32 v[92:93], s[6:7], v92, s3, 0
	v_subrev_co_u32_e32 v92, vcc, s2, v92
	v_min_i32_e32 v94, v241, v130
	s_nop 0
	v_subbrev_co_u32_e32 v93, vcc, 0, v93, vcc
	v_lshl_add_u64 v[92:93], v[26:27], 0, v[92:93]
	v_lshl_add_u64 v[92:93], s[70:71], 0, v[92:93]
	v_add_co_u32_e32 v92, vcc, s8, v92
	v_mad_i64_i32 v[94:95], s[6:7], v94, s3, 0
	s_nop 0
	v_addc_co_u32_e32 v93, vcc, 0, v93, vcc
	v_subrev_co_u32_e32 v94, vcc, s2, v94
	v_add_u32_e32 v243, 14, v184
	s_nop 0
	v_subbrev_co_u32_e32 v95, vcc, 0, v95, vcc
	v_lshl_add_u64 v[94:95], v[26:27], 0, v[94:95]
	v_lshl_add_u64 v[94:95], s[70:71], 0, v[94:95]
	v_add_co_u32_e32 v94, vcc, s8, v94
	v_add_u32_e32 v245, 15, v184
	s_nop 0
	v_addc_co_u32_e32 v95, vcc, 0, v95, vcc
	global_load_dwordx4 v[126:129], v[92:93], off offset:1664
	global_load_dwordx4 v[114:117], v[94:95], off offset:1664
	v_min_i32_e32 v92, v243, v130
	v_mad_i64_i32 v[92:93], s[6:7], v92, s3, 0
	v_subrev_co_u32_e32 v92, vcc, s2, v92
	v_min_i32_e32 v94, v245, v130
	s_nop 0
	v_subbrev_co_u32_e32 v93, vcc, 0, v93, vcc
	v_lshl_add_u64 v[92:93], v[26:27], 0, v[92:93]
	v_lshl_add_u64 v[92:93], s[70:71], 0, v[92:93]
	v_add_co_u32_e32 v92, vcc, s8, v92
	v_mad_i64_i32 v[94:95], s[6:7], v94, s3, 0
	s_nop 0
	v_addc_co_u32_e32 v93, vcc, 0, v93, vcc
	v_subrev_co_u32_e32 v94, vcc, s2, v94
	s_waitcnt vmcnt(13)
	v_lshlrev_b32_e32 v181, 16, v187
	v_subbrev_co_u32_e32 v95, vcc, 0, v95, vcc
	v_lshl_add_u64 v[94:95], v[26:27], 0, v[94:95]
	v_lshl_add_u64 v[94:95], s[70:71], 0, v[94:95]
	v_add_co_u32_e32 v94, vcc, s8, v94
	v_lshlrev_b32_e32 v180, 16, v186
	s_nop 0
	v_addc_co_u32_e32 v95, vcc, 0, v95, vcc
	global_load_dwordx4 v[130:133], v[92:93], off offset:1664
	s_nop 0
	global_load_dwordx4 v[92:95], v[94:95], off offset:1664
	v_cmp_gt_i32_e32 vcc, v183, v184
	v_and_b32_e32 v187, 0xffff0000, v187
	v_and_b32_e32 v186, 0xffff0000, v186
	v_cndmask_b32_e64 v178, 0, 1.0, vcc
	v_lshlrev_b32_e32 v195, 16, v189
	v_lshlrev_b32_e32 v194, 16, v188
	v_and_b32_e32 v189, 0xffff0000, v189
	v_and_b32_e32 v188, 0xffff0000, v188
	v_cmp_lt_i32_e32 vcc, v185, v183
	v_pk_fma_f32 v[180:181], v[178:179], v[180:181], 0 op_sel_hi:[0,1,0]
	v_pk_fma_f32 v[186:187], v[178:179], v[186:187], 0 op_sel_hi:[0,1,0]
	v_pk_fma_f32 v[194:195], v[178:179], v[194:195], 0 op_sel_hi:[0,1,0]
	v_pk_fma_f32 v[178:179], v[178:179], v[188:189], 0 op_sel_hi:[0,1,0]
	v_cndmask_b32_e64 v188, 0, 1.0, vcc
	s_waitcnt vmcnt(14)
	v_lshlrev_b32_e32 v203, 16, v191
	v_lshlrev_b32_e32 v202, 16, v190
	v_and_b32_e32 v191, 0xffff0000, v191
	v_and_b32_e32 v190, 0xffff0000, v190
	v_cmp_lt_i32_e32 vcc, v198, v183
	s_waitcnt vmcnt(13)
	v_lshlrev_b32_e32 v207, 16, v215
	v_lshlrev_b32_e32 v206, 16, v214
	v_and_b32_e32 v209, 0xffff0000, v215
	v_and_b32_e32 v208, 0xffff0000, v214
	v_cndmask_b32_e64 v222, 0, 1.0, vcc
	v_cmp_lt_i32_e32 vcc, v199, v183
	v_pk_fma_f32 v[180:181], v[188:189], v[202:203], v[180:181] op_sel_hi:[0,1,1]
	v_pk_fma_f32 v[186:187], v[188:189], v[190:191], v[186:187] op_sel_hi:[0,1,1]
	s_waitcnt vmcnt(12)
	v_lshlrev_b32_e32 v224, 16, v218
	v_and_b32_e32 v218, 0xffff0000, v218
	v_lshlrev_b32_e32 v225, 16, v219
	v_and_b32_e32 v219, 0xffff0000, v219
	v_cndmask_b32_e64 v228, 0, 1.0, vcc
	v_cmp_lt_i32_e32 vcc, v200, v183
	v_pk_fma_f32 v[180:181], v[222:223], v[206:207], v[180:181] op_sel_hi:[0,1,1]
	v_pk_fma_f32 v[186:187], v[222:223], v[208:209], v[186:187] op_sel_hi:[0,1,1]
	v_cndmask_b32_e64 v230, 0, 1.0, vcc
	v_cmp_lt_i32_e32 vcc, v201, v183
	v_pk_fma_f32 v[180:181], v[228:229], v[224:225], v[180:181] op_sel_hi:[0,1,1]
	s_waitcnt vmcnt(11)
	v_lshlrev_b32_e32 v203, 16, v89
	v_lshlrev_b32_e32 v202, 16, v88
	v_pk_fma_f32 v[186:187], v[228:229], v[218:219], v[186:187] op_sel_hi:[0,1,1]
	v_and_b32_e32 v89, 0xffff0000, v89
	v_and_b32_e32 v88, 0xffff0000, v88
	v_cndmask_b32_e64 v232, 0, 1.0, vcc
	v_cmp_lt_i32_e32 vcc, v223, v183
	v_pk_fma_f32 v[180:181], v[230:231], v[202:203], v[180:181] op_sel_hi:[0,1,1]
	s_waitcnt vmcnt(10)
	v_lshlrev_b32_e32 v203, 16, v85
	v_lshlrev_b32_e32 v202, 16, v84
	v_pk_fma_f32 v[88:89], v[230:231], v[88:89], v[186:187] op_sel_hi:[0,1,1]
	v_and_b32_e32 v85, 0xffff0000, v85
	v_and_b32_e32 v84, 0xffff0000, v84
	v_cndmask_b32_e64 v234, 0, 1.0, vcc
	v_cmp_lt_i32_e32 vcc, v229, v183
	v_pk_fma_f32 v[84:85], v[232:233], v[84:85], v[88:89] op_sel_hi:[0,1,1]
	s_waitcnt vmcnt(9)
	v_and_b32_e32 v89, 0xffff0000, v103
	v_and_b32_e32 v88, 0xffff0000, v102
	v_cndmask_b32_e64 v236, 0, 1.0, vcc
	v_cmp_lt_i32_e32 vcc, v231, v183
	v_pk_fma_f32 v[84:85], v[234:235], v[88:89], v[84:85] op_sel_hi:[0,1,1]
	s_waitcnt vmcnt(8)
	v_and_b32_e32 v89, 0xffff0000, v99
	v_and_b32_e32 v88, 0xffff0000, v98
	v_cndmask_b32_e64 v238, 0, 1.0, vcc
	v_cmp_lt_i32_e32 vcc, v233, v183
	v_pk_fma_f32 v[84:85], v[236:237], v[88:89], v[84:85] op_sel_hi:[0,1,1]
	s_waitcnt vmcnt(7)
	v_and_b32_e32 v89, 0xffff0000, v111
	v_and_b32_e32 v88, 0xffff0000, v110
	v_cndmask_b32_e64 v240, 0, 1.0, vcc
	v_cmp_lt_i32_e32 vcc, v235, v183
	v_pk_fma_f32 v[84:85], v[238:239], v[88:89], v[84:85] op_sel_hi:[0,1,1]
	s_waitcnt vmcnt(6)
	v_and_b32_e32 v89, 0xffff0000, v107
	v_and_b32_e32 v88, 0xffff0000, v106
	v_cndmask_b32_e64 v242, 0, 1.0, vcc
	v_cmp_lt_i32_e32 vcc, v237, v183
	v_pk_fma_f32 v[84:85], v[240:241], v[88:89], v[84:85] op_sel_hi:[0,1,1]
	s_waitcnt vmcnt(5)
	v_and_b32_e32 v89, 0xffff0000, v123
	v_and_b32_e32 v88, 0xffff0000, v122
	v_lshlrev_b32_e32 v205, 16, v193
	v_lshlrev_b32_e32 v204, 16, v192
	v_cndmask_b32_e64 v244, 0, 1.0, vcc
	v_pk_fma_f32 v[84:85], v[242:243], v[88:89], v[84:85] op_sel_hi:[0,1,1]
	s_waitcnt vmcnt(4)
	v_and_b32_e32 v89, 0xffff0000, v119
	v_and_b32_e32 v88, 0xffff0000, v118
	v_lshlrev_b32_e32 v215, 16, v217
	v_lshlrev_b32_e32 v214, 16, v216
	v_pk_fma_f32 v[84:85], v[244:245], v[88:89], v[84:85] op_sel_hi:[0,1,1]
	v_pk_fma_f32 v[88:89], v[188:189], v[204:205], v[194:195] op_sel_hi:[0,1,1]
	v_lshlrev_b32_e32 v226, 16, v220
	v_lshlrev_b32_e32 v227, 16, v221
	v_pk_fma_f32 v[180:181], v[232:233], v[202:203], v[180:181] op_sel_hi:[0,1,1]
	v_lshlrev_b32_e32 v203, 16, v103
	v_lshlrev_b32_e32 v202, 16, v102
	v_pk_fma_f32 v[88:89], v[222:223], v[214:215], v[88:89] op_sel_hi:[0,1,1]
	v_pk_fma_f32 v[180:181], v[234:235], v[202:203], v[180:181] op_sel_hi:[0,1,1]
	v_lshlrev_b32_e32 v203, 16, v99
	v_lshlrev_b32_e32 v202, 16, v98
	v_pk_fma_f32 v[88:89], v[228:229], v[226:227], v[88:89] op_sel_hi:[0,1,1]
	v_lshlrev_b32_e32 v99, 16, v91
	v_lshlrev_b32_e32 v98, 16, v90
	v_pk_fma_f32 v[88:89], v[230:231], v[98:99], v[88:89] op_sel_hi:[0,1,1]
	v_lshlrev_b32_e32 v99, 16, v87
	v_lshlrev_b32_e32 v98, 16, v86
	v_pk_fma_f32 v[88:89], v[232:233], v[98:99], v[88:89] op_sel_hi:[0,1,1]
	v_lshlrev_b32_e32 v99, 16, v105
	v_lshlrev_b32_e32 v98, 16, v104
	v_pk_fma_f32 v[88:89], v[234:235], v[98:99], v[88:89] op_sel_hi:[0,1,1]
	v_lshlrev_b32_e32 v99, 16, v101
	v_lshlrev_b32_e32 v98, 16, v100
	v_pk_fma_f32 v[88:89], v[236:237], v[98:99], v[88:89] op_sel_hi:[0,1,1]
	v_lshlrev_b32_e32 v99, 16, v113
	v_lshlrev_b32_e32 v98, 16, v112
	v_pk_fma_f32 v[88:89], v[238:239], v[98:99], v[88:89] op_sel_hi:[0,1,1]
	v_lshlrev_b32_e32 v99, 16, v109
	v_lshlrev_b32_e32 v98, 16, v108
	v_pk_fma_f32 v[88:89], v[240:241], v[98:99], v[88:89] op_sel_hi:[0,1,1]
	v_lshlrev_b32_e32 v99, 16, v125
	v_lshlrev_b32_e32 v98, 16, v124
	v_and_b32_e32 v193, 0xffff0000, v193
	v_and_b32_e32 v192, 0xffff0000, v192
	v_pk_fma_f32 v[88:89], v[242:243], v[98:99], v[88:89] op_sel_hi:[0,1,1]
	v_lshlrev_b32_e32 v99, 16, v121
	v_lshlrev_b32_e32 v98, 16, v120
	v_and_b32_e32 v217, 0xffff0000, v217
	v_and_b32_e32 v216, 0xffff0000, v216
	v_pk_fma_f32 v[88:89], v[244:245], v[98:99], v[88:89] op_sel_hi:[0,1,1]
	v_pk_fma_f32 v[98:99], v[188:189], v[192:193], v[178:179] op_sel_hi:[0,1,1]
	v_and_b32_e32 v220, 0xffff0000, v220
	v_and_b32_e32 v221, 0xffff0000, v221
	v_pk_fma_f32 v[98:99], v[222:223], v[216:217], v[98:99] op_sel_hi:[0,1,1]
	v_pk_fma_f32 v[98:99], v[228:229], v[220:221], v[98:99] op_sel_hi:[0,1,1]
	v_and_b32_e32 v91, 0xffff0000, v91
	v_and_b32_e32 v90, 0xffff0000, v90
	v_pk_fma_f32 v[90:91], v[230:231], v[90:91], v[98:99] op_sel_hi:[0,1,1]
	v_and_b32_e32 v87, 0xffff0000, v87
	v_and_b32_e32 v86, 0xffff0000, v86
	v_pk_fma_f32 v[86:87], v[232:233], v[86:87], v[90:91] op_sel_hi:[0,1,1]
	v_and_b32_e32 v91, 0xffff0000, v105
	v_and_b32_e32 v90, 0xffff0000, v104
	v_pk_fma_f32 v[86:87], v[234:235], v[90:91], v[86:87] op_sel_hi:[0,1,1]
	v_and_b32_e32 v91, 0xffff0000, v101
	v_and_b32_e32 v90, 0xffff0000, v100
	v_pk_fma_f32 v[86:87], v[236:237], v[90:91], v[86:87] op_sel_hi:[0,1,1]
	v_and_b32_e32 v91, 0xffff0000, v113
	v_and_b32_e32 v90, 0xffff0000, v112
	v_pk_fma_f32 v[86:87], v[238:239], v[90:91], v[86:87] op_sel_hi:[0,1,1]
	v_and_b32_e32 v91, 0xffff0000, v109
	v_and_b32_e32 v90, 0xffff0000, v108
	v_pk_fma_f32 v[86:87], v[240:241], v[90:91], v[86:87] op_sel_hi:[0,1,1]
	v_and_b32_e32 v91, 0xffff0000, v125
	v_and_b32_e32 v90, 0xffff0000, v124
	v_pk_fma_f32 v[86:87], v[242:243], v[90:91], v[86:87] op_sel_hi:[0,1,1]
	v_and_b32_e32 v91, 0xffff0000, v121
	v_and_b32_e32 v90, 0xffff0000, v120
	v_pk_fma_f32 v[86:87], v[244:245], v[90:91], v[86:87] op_sel_hi:[0,1,1]
	v_sub_u32_e32 v91, v183, v184
	v_cvt_f32_i32_e32 v91, v91
	v_pk_fma_f32 v[180:181], v[236:237], v[202:203], v[180:181] op_sel_hi:[0,1,1]
	v_lshlrev_b32_e32 v203, 16, v111
	v_lshlrev_b32_e32 v202, 16, v110
	v_cmp_lt_i32_e32 vcc, v239, v183
	v_pk_fma_f32 v[180:181], v[238:239], v[202:203], v[180:181] op_sel_hi:[0,1,1]
	v_lshlrev_b32_e32 v203, 16, v107
	v_lshlrev_b32_e32 v202, 16, v106
	v_cndmask_b32_e64 v90, 0, 1.0, vcc
	s_waitcnt vmcnt(3)
	v_and_b32_e32 v101, 0xffff0000, v127
	v_and_b32_e32 v100, 0xffff0000, v126
	v_cmp_lt_i32_e32 vcc, v241, v183
	v_pk_fma_f32 v[180:181], v[240:241], v[202:203], v[180:181] op_sel_hi:[0,1,1]
	v_lshlrev_b32_e32 v203, 16, v123
	v_lshlrev_b32_e32 v202, 16, v122
	v_lshlrev_b32_e32 v102, 16, v128
	v_and_b32_e32 v104, 0xffff0000, v128
	s_waitcnt vmcnt(2)
	v_lshlrev_b32_e32 v106, 16, v114
	v_and_b32_e32 v109, 0xffff0000, v115
	v_and_b32_e32 v108, 0xffff0000, v114
	v_cndmask_b32_e64 v114, 0, 1.0, vcc
	v_cmp_lt_i32_e32 vcc, v243, v183
	v_rcp_iflag_f32_e32 v128, v91
	v_pk_fma_f32 v[84:85], v[90:91], v[100:101], v[84:85] op_sel_hi:[0,1,1]
	v_pk_fma_f32 v[180:181], v[242:243], v[202:203], v[180:181] op_sel_hi:[0,1,1]
	v_lshlrev_b32_e32 v203, 16, v119
	v_lshlrev_b32_e32 v202, 16, v118
	s_waitcnt vmcnt(1)
	v_and_b32_e32 v118, 0xffff0000, v130
	v_and_b32_e32 v119, 0xffff0000, v131
	v_cndmask_b32_e64 v124, 0, 1.0, vcc
	v_cmp_lt_i32_e32 vcc, v245, v183
	v_pk_fma_f32 v[84:85], v[114:115], v[108:109], v[84:85] op_sel_hi:[0,1,1]
	v_lshlrev_b32_e32 v98, 16, v126
	v_cndmask_b32_e64 v126, 0, 1.0, vcc
	v_pk_fma_f32 v[84:85], v[124:125], v[118:119], v[84:85] op_sel_hi:[0,1,1]
	s_waitcnt vmcnt(0)
	v_lshlrev_b32_e32 v101, 16, v93
	v_lshlrev_b32_e32 v100, 16, v92
	v_and_b32_e32 v93, 0xffff0000, v93
	v_and_b32_e32 v92, 0xffff0000, v92
	v_pk_fma_f32 v[180:181], v[244:245], v[202:203], v[180:181] op_sel_hi:[0,1,1]
	v_lshlrev_b32_e32 v99, 16, v127
	v_lshlrev_b32_e32 v103, 16, v129
	v_and_b32_e32 v105, 0xffff0000, v129
	v_pk_fma_f32 v[84:85], v[126:127], v[92:93], v[84:85] op_sel_hi:[0,1,1]
	v_lshlrev_b32_e32 v93, 16, v81
	v_lshlrev_b32_e32 v92, 16, v80
	v_and_b32_e32 v81, 0xffff0000, v81
	v_and_b32_e32 v80, 0xffff0000, v80
	v_lshlrev_b32_e32 v107, 16, v115
	v_lshlrev_b32_e32 v111, 16, v117
	v_lshlrev_b32_e32 v110, 16, v116
	v_and_b32_e32 v113, 0xffff0000, v117
	v_and_b32_e32 v112, 0xffff0000, v116
	v_pk_fma_f32 v[98:99], v[90:91], v[98:99], v[180:181] op_sel_hi:[0,1,1]
	v_pk_fma_f32 v[80:81], v[128:129], v[84:85], v[80:81] op_sel_hi:[0,1,1] neg_lo:[0,0,1] neg_hi:[0,0,1]
	v_pk_fma_f32 v[84:85], v[90:91], v[102:103], v[88:89] op_sel_hi:[0,1,1]
	v_pk_fma_f32 v[86:87], v[90:91], v[104:105], v[86:87] op_sel_hi:[0,1,1]
	v_lshlrev_b32_e32 v116, 16, v130
	v_lshlrev_b32_e32 v117, 16, v131
	v_lshlrev_b32_e32 v120, 16, v132
	v_and_b32_e32 v122, 0xffff0000, v132
	v_lshlrev_b32_e32 v121, 16, v133
	v_and_b32_e32 v123, 0xffff0000, v133
	v_pk_fma_f32 v[98:99], v[114:115], v[106:107], v[98:99] op_sel_hi:[0,1,1]
	v_pk_fma_f32 v[84:85], v[114:115], v[110:111], v[84:85] op_sel_hi:[0,1,1]
	v_pk_fma_f32 v[86:87], v[114:115], v[112:113], v[86:87] op_sel_hi:[0,1,1]
	v_pk_fma_f32 v[98:99], v[124:125], v[116:117], v[98:99] op_sel_hi:[0,1,1]
	v_pk_fma_f32 v[84:85], v[124:125], v[120:121], v[84:85] op_sel_hi:[0,1,1]
	v_pk_fma_f32 v[86:87], v[124:125], v[122:123], v[86:87] op_sel_hi:[0,1,1]
	v_lshlrev_b32_e32 v89, 16, v95
	v_lshlrev_b32_e32 v88, 16, v94
	v_and_b32_e32 v91, 0xffff0000, v95
	v_and_b32_e32 v90, 0xffff0000, v94
	v_pk_fma_f32 v[98:99], v[126:127], v[100:101], v[98:99] op_sel_hi:[0,1,1]
	v_pk_fma_f32 v[84:85], v[126:127], v[88:89], v[84:85] op_sel_hi:[0,1,1]
	v_pk_fma_f32 v[86:87], v[126:127], v[90:91], v[86:87] op_sel_hi:[0,1,1]
	v_lshlrev_b32_e32 v89, 16, v83
	v_lshlrev_b32_e32 v88, 16, v82
	v_and_b32_e32 v83, 0xffff0000, v83
	v_and_b32_e32 v82, 0xffff0000, v82
	v_pk_fma_f32 v[92:93], v[128:129], v[98:99], v[92:93] op_sel_hi:[0,1,1] neg_lo:[0,0,1] neg_hi:[0,0,1]
	v_pk_fma_f32 v[84:85], v[128:129], v[84:85], v[88:89] op_sel_hi:[0,1,1] neg_lo:[0,0,1] neg_hi:[0,0,1]
	v_pk_fma_f32 v[82:83], v[128:129], v[86:87], v[82:83] op_sel_hi:[0,1,1] neg_lo:[0,0,1] neg_hi:[0,0,1]
	v_bfe_u32 v89, v80, 16, 1
	v_bfe_u32 v86, v83, 16, 1
	v_bfe_u32 v87, v82, 16, 1
	v_bfe_u32 v88, v81, 16, 1
	v_add3_u32 v94, v80, v89, s78
	v_bfe_u32 v80, v92, 16, 1
	v_add3_u32 v95, v81, v88, s78
	v_add3_u32 v98, v82, v87, s78
	v_add3_u32 v99, v83, v86, s78
	v_bfe_u32 v81, v93, 16, 1
	v_bfe_u32 v82, v84, 16, 1
	v_bfe_u32 v83, v85, 16, 1
	v_add3_u32 v80, v92, v80, s78
	v_add3_u32 v100, v85, v83, s78
	v_add3_u32 v101, v84, v82, s78
	v_add3_u32 v93, v93, v81, s78
	v_lshrrev_b32_e32 v92, 16, v80
	v_lshlrev_b32_e32 v81, 16, v77
	v_lshlrev_b32_e32 v80, 16, v76
	v_and_b32_e32 v83, 0xffff0000, v77
	v_and_b32_e32 v82, 0xffff0000, v76
	v_pk_mul_f32 v[76:77], v[80:81], v[80:81]
	v_pk_mul_f32 v[84:85], v[82:83], v[82:83]
	v_lshlrev_b32_e32 v87, 16, v79
	v_add_f32_e32 v76, v76, v84
	v_lshlrev_b32_e32 v86, 16, v78
	v_add_f32_e32 v76, v77, v76
	v_and_b32_e32 v89, 0xffff0000, v79
	v_and_b32_e32 v88, 0xffff0000, v78
	v_pk_mul_f32 v[78:79], v[86:87], v[86:87]
	v_add_f32_e32 v76, v85, v76
	v_pk_mul_f32 v[90:91], v[88:89], v[88:89]
	v_add_f32_e32 v76, v78, v76
	v_add_f32_e32 v76, v90, v76
	v_add_f32_e32 v76, v79, v76
	v_add_f32_e32 v76, v91, v76
	v_lshrrev_b32_e32 v77, 16, v93
	v_lshrrev_b32_e32 v78, 16, v101
	v_add_f32_dpp v76, v76, v76 quad_perm:[1,0,3,2] row_mask:0xf bank_mask:0xf bound_ctrl:1
	v_lshrrev_b32_e32 v79, 16, v100
	v_and_or_b32 v79, v99, s79, v79
	v_add_f32_dpp v76, v76, v76 quad_perm:[2,3,0,1] row_mask:0xf bank_mask:0xf bound_ctrl:1
	v_and_or_b32 v78, v98, s79, v78
	v_and_or_b32 v77, v95, s79, v77
	v_add_f32_dpp v76, v76, v76 row_half_mirror row_mask:0xf bank_mask:0xf bound_ctrl:1
	v_lshl_add_u64 v[90:91], s[70:71], 0, v[154:155]
	s_nop 0
	v_add_f32_dpp v76, v76, v76 row_mirror row_mask:0xf bank_mask:0xf bound_ctrl:1
	v_cvt_i32_f32_e32 v76, v76
	s_nop 0
	v_readlane_b32 s2, v76, 0
	v_readlane_b32 s3, v76, 16
	v_readlane_b32 s6, v76, 32
	s_add_i32 s2, s3, s2
	v_readlane_b32 s7, v76, 48
	s_add_i32 s2, s2, s6
	s_add_i32 s2, s2, s7
	v_cvt_f32_i32_e32 v76, s2
	v_fmamk_f32 v76, v76, 0x3b000000, v196
	v_rsq_f32_e32 v84, v76
	v_and_or_b32 v76, v94, s79, v92
	global_store_dwordx4 v[90:91], v[76:79], off sc1
	s_nop 1
	v_pk_mul_f32 v[78:79], v[84:85], v[82:83] op_sel_hi:[0,1]
	v_pk_mul_f32 v[82:83], v[84:85], v[88:89] op_sel_hi:[0,1]
	v_pk_mul_f32 v[76:77], v[84:85], v[80:81] op_sel_hi:[0,1]
	v_pk_mul_f32 v[78:79], v[10:11], v[78:79]
	v_pk_mul_f32 v[80:81], v[84:85], v[86:87] op_sel_hi:[0,1]
	v_pk_mul_f32 v[82:83], v[22:23], v[82:83]
	v_pk_mul_f32 v[76:77], v[20:21], v[76:77]
	v_pk_mul_f32 v[80:81], v[16:17], v[80:81]
	v_bfe_u32 v84, v83, 16, 1
	v_bfe_u32 v85, v82, 16, 1
	v_bfe_u32 v87, v78, 16, 1
	v_bfe_u32 v86, v79, 16, 1
	v_add3_u32 v87, v78, v87, s78
	v_add3_u32 v85, v82, v85, s78
	v_add3_u32 v84, v83, v84, s78
	v_bfe_u32 v78, v76, 16, 1
	v_bfe_u32 v82, v80, 16, 1
	v_bfe_u32 v83, v81, 16, 1
	v_add3_u32 v86, v79, v86, s78
	v_bfe_u32 v79, v77, 16, 1
	v_add3_u32 v88, v81, v83, s78
	v_add3_u32 v89, v80, v82, s78
	v_add3_u32 v76, v76, v78, s78
	v_lshlrev_b32_e32 v81, 16, v165
	v_lshlrev_b32_e32 v80, 16, v164
	v_and_b32_e32 v83, 0xffff0000, v165
	v_and_b32_e32 v82, 0xffff0000, v164
	v_add3_u32 v90, v77, v79, s78
	v_lshrrev_b32_e32 v91, 16, v76
	v_pk_mul_f32 v[76:77], v[80:81], v[80:81]
	v_pk_mul_f32 v[78:79], v[82:83], v[82:83]
	s_nop 0
	v_add_f32_e32 v76, v76, v78
	v_add_f32_e32 v76, v77, v76
	v_add_f32_e32 v76, v79, v76
	v_lshrrev_b32_e32 v77, 16, v90
	v_lshrrev_b32_e32 v78, 16, v89
	v_add_f32_dpp v76, v76, v76 quad_perm:[1,0,3,2] row_mask:0xf bank_mask:0xf bound_ctrl:1
	v_lshrrev_b32_e32 v79, 16, v88
	v_and_or_b32 v79, v84, s79, v79
	v_add_f32_dpp v76, v76, v76 quad_perm:[2,3,0,1] row_mask:0xf bank_mask:0xf bound_ctrl:1
	v_and_or_b32 v78, v85, s79, v78
	v_and_or_b32 v77, v86, s79, v77
	v_add_f32_dpp v76, v76, v76 row_half_mirror row_mask:0xf bank_mask:0xf bound_ctrl:1
	s_nop 1
	v_add_f32_dpp v76, v76, v76 row_mirror row_mask:0xf bank_mask:0xf bound_ctrl:1
	v_cvt_i32_f32_e32 v76, v76
	s_nop 0
	v_readlane_b32 s2, v76, 0
	v_readlane_b32 s3, v76, 16
	v_readlane_b32 s6, v76, 32
	s_add_i32 s2, s3, s2
	v_readlane_b32 s7, v76, 48
	s_add_i32 s2, s2, s6
	s_add_i32 s2, s2, s7
	v_cvt_f32_i32_e32 v76, s2
	v_fmamk_f32 v76, v76, 0x3b800000, v196
	v_rsq_f32_e32 v84, v76
	v_and_or_b32 v76, v87, s79, v91
	v_lshl_add_u64 v[86:87], s[70:71], 0, v[152:153]
	global_store_dwordx4 v[86:87], v[76:79], off sc1
	s_nop 1
	v_mul_f32_e32 v78, v96, v96
	v_mov_b32_e32 v79, v97
	v_pk_mul_f32 v[76:77], v[84:85], v[80:81] op_sel_hi:[0,1]
	v_pk_mul_f32 v[76:77], v[24:25], v[76:77]
	v_mov_b32_dpp v79, v78 quad_perm:[1,0,3,2] row_mask:0xf bank_mask:0xf
	v_fmac_f32_e32 v79, v96, v96
	v_and_b32_sdwa v81, v77, v197 dst_sel:DWORD dst_unused:UNUSED_PAD src0_sel:WORD_1 src1_sel:DWORD
	s_nop 0
	v_add_f32_dpp v78, v79, v79 quad_perm:[2,3,0,1] row_mask:0xf bank_mask:0xf bound_ctrl:1
	s_nop 1
	v_add_f32_dpp v78, v78, v78 row_half_mirror row_mask:0xf bank_mask:0xf bound_ctrl:1
	s_nop 1
	v_add_f32_dpp v78, v78, v78 row_mirror row_mask:0xf bank_mask:0xf bound_ctrl:1
	v_cvt_i32_f32_e32 v80, v78
	v_pk_mul_f32 v[78:79], v[84:85], v[82:83] op_sel_hi:[0,1]
	v_and_b32_sdwa v82, v76, v197 dst_sel:DWORD dst_unused:UNUSED_PAD src0_sel:WORD_1 src1_sel:DWORD
	v_add3_u32 v84, v76, v82, s78
	v_readlane_b32 s2, v80, 0
	v_readlane_b32 s3, v80, 16
	v_readlane_b32 s6, v80, 32
	s_add_i32 s2, s3, s2
	v_readlane_b32 s7, v80, 48
	s_add_i32 s2, s2, s6
	s_add_i32 s2, s2, s7
	v_cvt_f32_i32_e32 v80, s2
	v_add3_u32 v85, v77, v81, s78
	v_pk_mul_f32 v[78:79], v[18:19], v[78:79]
	v_fmamk_f32 v76, v80, 0x3c800000, v196
	v_rsq_f32_e32 v76, v76
	v_and_b32_sdwa v77, v79, v197 dst_sel:DWORD dst_unused:UNUSED_PAD src0_sel:WORD_1 src1_sel:DWORD
	v_add3_u32 v77, v79, v77, s78
	v_and_b32_e32 v86, 0xffff0000, v77
	v_mul_f32_e32 v76, v76, v96
	v_mul_f32_e32 v76, v135, v76
	ds_bpermute_b32 v81, v169, v76
	v_and_b32_sdwa v80, v78, v197 dst_sel:DWORD dst_unused:UNUSED_PAD src0_sel:WORD_1 src1_sel:DWORD
	v_add3_u32 v78, v78, v80, s78
	v_and_b32_e32 v87, 0xffff0000, v78
	v_or_b32_sdwa v85, v86, v85 dst_sel:DWORD dst_unused:UNUSED_PAD src0_sel:DWORD src1_sel:WORD_1
	s_waitcnt lgkmcnt(0)
	v_mul_f32_e32 v77, v163, v81
	v_cndmask_b32_e64 v77, v77, -v77, s[44:45]
	v_fmac_f32_e32 v77, v162, v76
	v_cndmask_b32_e64 v76, v77, v76, s[52:53]
	ds_bpermute_b32 v83, v171, v76
	ds_bpermute_b32 v82, v173, v76
	ds_bpermute_b32 v81, v174, v76
	ds_bpermute_b32 v80, v175, v76
	ds_bpermute_b32 v79, v176, v76
	ds_bpermute_b32 v78, v177, v76
	ds_bpermute_b32 v77, v182, v76
	ds_bpermute_b32 v76, v172, v76
	v_or_b32_sdwa v84, v87, v84 dst_sel:DWORD dst_unused:UNUSED_PAD src0_sel:DWORD src1_sel:WORD_1
	v_lshl_add_u64 v[86:87], s[70:71], 0, v[150:151]
	global_store_dwordx2 v[86:87], v[84:85], off
	s_and_saveexec_b64 s[8:9], s[46:47]
	s_cbranch_execz .LBB0_324
	s_waitcnt lgkmcnt(7)
	v_bfe_u32 v84, v83, 16, 1
	v_add3_u32 v83, v83, v84, s78
	s_waitcnt lgkmcnt(6)
	v_bfe_u32 v84, v82, 16, 1
	v_lshrrev_b32_e32 v83, 16, v83
	v_add3_u32 v82, v82, v84, s78
	v_and_or_b32 v82, v82, s79, v83
	s_waitcnt lgkmcnt(5)
	v_bfe_u32 v83, v81, 16, 1
	v_add3_u32 v81, v81, v83, s78
	s_waitcnt lgkmcnt(4)
	v_bfe_u32 v83, v80, 16, 1
	v_lshrrev_b32_e32 v81, 16, v81
	v_add3_u32 v80, v80, v83, s78
	v_and_or_b32 v83, v80, s79, v81
	s_waitcnt lgkmcnt(3)
	v_bfe_u32 v80, v79, 16, 1
	v_add3_u32 v79, v79, v80, s78
	s_waitcnt lgkmcnt(2)
	v_bfe_u32 v80, v78, 16, 1
	v_lshrrev_b32_e32 v79, 16, v79
	v_add3_u32 v78, v78, v80, s78
	v_and_or_b32 v84, v78, s79, v79
	s_waitcnt lgkmcnt(1)
	v_bfe_u32 v78, v77, 16, 1
	v_add3_u32 v77, v77, v78, s78
	s_waitcnt lgkmcnt(0)
	v_bfe_u32 v78, v76, 16, 1
	v_lshrrev_b32_e32 v77, 16, v77
	v_add3_u32 v76, v76, v78, s78
	v_and_or_b32 v85, v76, s79, v77
	s_lshl_b32 s7, s40, 1
	v_and_or_b32 v76, s40, 19, v170
	s_lshr_b32 s2, s40, 5
	s_lshr_b32 s10, s40, 1
	v_and_or_b32 v76, s7, 8, v76
	s_mulk_i32 s2, 0x3000
	s_mov_b32 s3, s41
	v_and_or_b32 v76, s10, 4, v76
	v_lshlrev_b32_e32 v96, 4, v76
	v_lshl_add_u64 v[76:77], v[146:147], 0, s[2:3]
	s_lshl_b32 s6, s5, 2
	v_lshl_add_u64 v[76:77], v[76:77], 0, v[96:97]
	v_mov_b32_e32 v80, 0x198000
	v_mad_i64_i32 v[78:79], s[2:3], s6, v80, v[76:77]
	s_or_b32 s2, s6, 1
	global_store_dwordx4 v[78:79], v[82:85], off sc1
	v_mad_i64_i32 v[78:79], s[2:3], s2, v80, v[76:77]
	s_or_b32 s2, s6, 2
	global_store_dwordx4 v[78:79], v[82:85], off sc1
	v_mad_i64_i32 v[78:79], s[2:3], s2, v80, v[76:77]
	s_or_b32 s2, s6, 3
	s_nop 0
	v_mad_i64_i32 v[76:77], s[2:3], s2, v80, v[76:77]
	global_store_dwordx4 v[78:79], v[82:85], off sc1
	global_store_dwordx4 v[76:77], v[82:85], off sc1

.LBB0_326:
	v_bfe_u32 v80, v78, 16, 1
	v_add3_u32 v78, v78, v80, s78
	v_bfe_u32 v80, v79, 16, 1
	v_lshrrev_b32_e32 v78, 16, v78
	v_add3_u32 v79, v79, v80, s78
	v_and_or_b32 v78, v79, s79, v78
	v_bfe_u32 v79, v76, 16, 1
	v_add3_u32 v76, v76, v79, s78
	v_bfe_u32 v79, v77, 16, 1
	v_lshrrev_b32_e32 v76, 16, v76
	v_add3_u32 v77, v77, v79, s78
	v_and_or_b32 v79, v77, s79, v76
	v_bfe_u32 v76, v74, 16, 1
	v_add3_u32 v74, v74, v76, s78
	v_bfe_u32 v76, v75, 16, 1
	v_lshrrev_b32_e32 v74, 16, v74
	v_add3_u32 v75, v75, v76, s78
	v_and_or_b32 v80, v75, s79, v74
	v_bfe_u32 v74, v72, 16, 1
	v_add3_u32 v72, v72, v74, s78
	v_bfe_u32 v74, v73, 16, 1
	v_lshrrev_b32_e32 v72, 16, v72
	v_add3_u32 v73, v73, v74, s78
	v_and_or_b32 v81, v73, s79, v72
	v_lshl_add_u32 v74, s5, 3, v167
	v_mov_b64_e32 v[72:73], s[40:41]
	v_mad_i64_i32 v[72:73], s[2:3], v74, s33, v[72:73]
	v_lshlrev_b64 v[76:77], 7, v[72:73]
	v_lshl_add_u64 v[76:77], v[138:139], 0, v[76:77]
	global_store_dwordx4 v[76:77], v[78:81], off sc1
	v_and_b32_e32 v82, 0xffff0000, v63
	v_lshlrev_b32_e32 v83, 16, v63
	v_lshlrev_b32_e32 v78, 16, v60
	v_and_b32_e32 v79, 0xffff0000, v60
	v_pk_mul_f32 v[84:85], v[78:79], v[78:79]
	v_lshlrev_b32_e32 v60, 16, v61
	v_and_b32_e32 v61, 0xffff0000, v61
	v_pk_mul_f32 v[86:87], v[60:61], v[60:61]
	v_add_f32_e32 v75, v84, v85
	v_and_b32_e32 v80, 0xffff0000, v62
	v_lshlrev_b32_e32 v81, 16, v62
	v_add_f32_e32 v75, v86, v75
	v_pk_mul_f32 v[76:77], v[80:81], v[80:81]
	v_add_f32_e32 v75, v87, v75
	v_add_f32_e32 v75, v77, v75
	v_pk_mul_f32 v[62:63], v[82:83], v[82:83]
	v_add_f32_e32 v75, v76, v75
	v_add_f32_e32 v63, v63, v75
	v_add_f32_e32 v62, v62, v63
	s_and_b64 vcc, exec, s[50:51]
	s_nop 0
	v_add_f32_dpp v62, v62, v62 quad_perm:[1,0,3,2] row_mask:0xf bank_mask:0xf bound_ctrl:1
	s_nop 1
	v_add_f32_dpp v62, v62, v62 quad_perm:[2,3,0,1] row_mask:0xf bank_mask:0xf bound_ctrl:1
	s_nop 1
	v_add_f32_dpp v62, v62, v62 row_half_mirror row_mask:0xf bank_mask:0xf bound_ctrl:1
	v_fmamk_f32 v62, v62, 0x3c800000, v196
	v_rsq_f32_e32 v84, v62
	s_nop 0
	v_pk_mul_f32 v[60:61], v[84:85], v[60:61] op_sel_hi:[0,1]
	v_pk_mul_f32 v[62:63], v[84:85], v[78:79] op_sel_hi:[0,1]
	v_pk_mul_f32 v[76:77], v[42:43], v[60:61]
	v_pk_mul_f32 v[60:61], v[84:85], v[80:81] op_sel_hi:[0,1]
	v_pk_mul_f32 v[78:79], v[40:41], v[62:63]
	v_pk_mul_f32 v[62:63], v[36:37], v[60:61] op_sel:[0,1] op_sel_hi:[1,0]
	v_pk_mul_f32 v[60:61], v[84:85], v[82:83] op_sel_hi:[0,1]
	v_pk_mul_f32 v[60:61], v[38:39], v[60:61] op_sel:[0,1] op_sel_hi:[1,0]
	s_cbranch_vccnz .LBB0_328
	v_mov_b32_e32 v80, v97
	v_mov_b32_e32 v81, v97
	v_mov_b32_e32 v83, v54
	v_mov_b32_dpp v80, v78 quad_perm:[2,3,0,1] row_mask:0xf bank_mask:0xf
	v_mov_b32_dpp v81, v79 quad_perm:[2,3,0,1] row_mask:0xf bank_mask:0xf
	v_mov_b32_e32 v54, v53
	v_mov_b32_e32 v82, v52
	v_pk_mul_f32 v[52:53], v[54:55], v[80:81]
	v_mov_b32_e32 v55, v66
	v_cndmask_b32_e64 v53, v53, -v53, s[48:49]
	v_cndmask_b32_e64 v52, v52, -v52, s[48:49]
	v_pk_fma_f32 v[78:79], v[82:83], v[78:79], v[52:53]
	v_mov_b32_e32 v52, v97
	v_mov_b32_e32 v53, v97
	v_mov_b32_e32 v66, v65
	v_mov_b32_dpp v52, v76 quad_perm:[2,3,0,1] row_mask:0xf bank_mask:0xf
	v_mov_b32_dpp v53, v77 quad_perm:[2,3,0,1] row_mask:0xf bank_mask:0xf
	v_pk_mul_f32 v[52:53], v[66:67], v[52:53]
	v_mov_b32_e32 v54, v64
	v_cndmask_b32_e64 v53, v53, -v53, s[48:49]
	v_cndmask_b32_e64 v52, v52, -v52, s[48:49]
	v_pk_fma_f32 v[76:77], v[54:55], v[76:77], v[52:53]
	v_mov_b32_e32 v52, v97
	v_mov_b32_e32 v53, v97
	v_mov_b32_e32 v55, v58
	v_mov_b32_dpp v52, v62 quad_perm:[2,3,0,1] row_mask:0xf bank_mask:0xf
	v_mov_b32_dpp v53, v63 quad_perm:[2,3,0,1] row_mask:0xf bank_mask:0xf
	v_mov_b32_e32 v58, v57
	v_pk_mul_f32 v[52:53], v[58:59], v[52:53]
	v_mov_b32_e32 v54, v56
	v_cndmask_b32_e64 v53, v53, -v53, s[48:49]
	v_cndmask_b32_e64 v52, v52, -v52, s[48:49]
	v_pk_fma_f32 v[62:63], v[54:55], v[62:63], v[52:53]
	v_mov_b32_e32 v52, v97
	v_mov_b32_e32 v53, v97
	v_mov_b32_e32 v55, v70
	v_mov_b32_dpp v52, v60 quad_perm:[2,3,0,1] row_mask:0xf bank_mask:0xf
	v_mov_b32_dpp v53, v61 quad_perm:[2,3,0,1] row_mask:0xf bank_mask:0xf
	v_mov_b32_e32 v70, v69
	v_pk_mul_f32 v[52:53], v[70:71], v[52:53]
	v_mov_b32_e32 v54, v68
	v_cndmask_b32_e64 v53, v53, -v53, s[48:49]
	v_cndmask_b32_e64 v52, v52, -v52, s[48:49]
	v_pk_fma_f32 v[60:61], v[54:55], v[60:61], v[52:53]
.LBB0_328:
	s_and_saveexec_b64 s[8:9], s[0:1]
	s_cbranch_execz .LBB0_310
	v_bfe_u32 v52, v78, 16, 1
	v_add3_u32 v52, v78, v52, s78
	v_bfe_u32 v53, v79, 16, 1
	v_lshrrev_b32_e32 v52, 16, v52
	v_add3_u32 v53, v79, v53, s78
	v_and_or_b32 v52, v53, s79, v52
	v_bfe_u32 v53, v76, 16, 1
	v_add3_u32 v53, v76, v53, s78
	v_bfe_u32 v54, v77, 16, 1
	v_lshrrev_b32_e32 v53, 16, v53
	v_add3_u32 v54, v77, v54, s78
	v_and_or_b32 v53, v54, s79, v53
	v_bfe_u32 v54, v62, 16, 1
	v_add3_u32 v54, v62, v54, s78
	v_bfe_u32 v55, v63, 16, 1
	v_lshrrev_b32_e32 v54, 16, v54
	v_add3_u32 v55, v63, v55, s78
	v_and_or_b32 v54, v55, s79, v54
	v_bfe_u32 v55, v60, 16, 1
	v_add3_u32 v55, v60, v55, s78
	v_bfe_u32 v56, v61, 16, 1
	v_lshrrev_b32_e32 v55, 16, v55
	v_add3_u32 v56, v61, v56, s78
	v_and_or_b32 v55, v56, s79, v55
	v_mad_u64_u32 v[56:57], s[2:3], s5, -6, v[74:75]
	v_mov_b64_e32 v[58:59], s[40:41]
	v_mad_i64_i32 v[56:57], s[2:3], v56, s33, v[58:59]
	v_lshlrev_b64 v[56:57], 7, v[56:57]
	v_lshl_add_u64 v[56:57], v[140:141], 0, v[56:57]
	global_store_dwordx4 v[56:57], v[52:55], off sc1
	s_branch .LBB0_310

.LBB0_332:
	s_and_b64 s[12:13], s[0:1], exec
	s_movk_i32 s6, 0xff8
	s_cselect_b32 s6, s6, 0xf8
	s_and_b32 s6, s6, s7
	s_or_b32 s7, s6, 0x1000
	s_and_b64 s[0:1], s[0:1], exec
	s_waitcnt vmcnt(0)
	v_lshlrev_b32_e32 v5, 16, v6
	s_mov_b32 s0, 0xffff
	v_and_or_b32 v24, v3, s0, v5
	v_lshlrev_b32_e32 v5, 16, v8
	v_and_or_b32 v25, v7, s0, v5
	v_lshlrev_b32_e32 v5, 16, v11
	v_lshrrev_b32_e32 v3, 16, v3
	v_and_or_b32 v26, v9, s0, v5
	v_lshlrev_b32_e32 v5, 16, v14
	v_and_or_b32 v6, v6, s79, v3
	v_lshrrev_b32_e32 v3, 16, v7
	s_cselect_b32 s6, s6, s7
	v_and_or_b32 v27, v13, s0, v5
	v_and_or_b32 v7, v8, s79, v3
	v_lshrrev_b32_e32 v3, 16, v9
	s_add_u32 s0, s70, s10
	v_ashrrev_i32_e32 v5, 31, v4
	v_and_or_b32 v8, v11, s79, v3
	v_lshrrev_b32_e32 v3, 16, v13
	s_addc_u32 s1, s71, s11
	v_lshlrev_b64 v[4:5], 6, v[4:5]
	v_and_or_b32 v9, v14, s79, v3
	v_or_b32_e32 v3, v4, v2
	v_mov_b64_e32 v[28:29], s[0:1]
	s_movk_i32 s7, 0x2200
	v_mad_u64_u32 v[28:29], s[0:1], v3, s7, v[28:29]
	v_mad_i32_i24 v29, v5, s7, v29
	s_lshl_b32 s40, s6, 1
	v_lshl_add_u64 v[4:5], v[28:29], 0, s[40:41]
	global_store_dwordx4 v[4:5], v[24:27], off sc1
	v_add_co_u32_e32 v4, vcc, 0x2000, v4
	v_add_u32_e32 v12, s2, v12
	s_nop 0
	v_addc_co_u32_e32 v5, vcc, 0, v5, vcc
	global_store_dwordx4 v[4:5], v[6:9], off offset:512 sc1
	s_add_i32 s3, s3, s4
	s_andn2_b64 vcc, exec, s[8:9]
	v_mov_b32_e32 v14, v22
	v_mov_b32_e32 v13, v20
	v_mov_b32_e32 v11, v21
	v_mov_b32_e32 v9, v18
	v_mov_b32_e32 v8, v19
	v_mov_b32_e32 v7, v16
	v_mov_b32_e32 v6, v17
	v_mov_b32_e32 v3, v15
	s_mov_b32 s6, s5
	s_cbranch_vccz .LBB0_353

.LBB0_470:
	v_add_u32_e32 v96, s4, v184
	s_waitcnt lgkmcnt(0)
	v_add_u32_e32 v155, 0xffffe000, v96
	v_ashrrev_i32_e32 v154, 12, v96
	v_lshrrev_b32_e32 v155, 8, v155
	v_cmp_gt_i32_e32 vcc, s77, v96
	s_lshl_b32 s5, s12, 1
	v_ashrrev_i32_e32 v173, 31, v172
	v_cndmask_b32_e32 v154, v155, v154, vcc
	v_cndmask_b32_e32 v155, v246, v210, vcc
	v_and_b32_e32 v96, v155, v96
	v_or_b32_e32 v155, 0x1000, v96
	v_cndmask_b32_e32 v96, v155, v96, vcc
	v_fma_f32 v155, s2, v171, v196
	v_rsq_f32_e32 v178, v155
	v_lshlrev_b32_e32 v171, 2, v154
	v_add_u32_e32 v185, s5, v171
	s_mov_b64 s[12:13], -1
	v_pk_mul_f32 v[134:135], v[134:135], v[178:179] op_sel_hi:[1,0]
	v_pk_mul_f32 v[136:137], v[136:137], v[178:179] op_sel_hi:[1,0]
	v_pk_mul_f32 v[156:157], v[56:57], v[134:135]
	v_pk_mul_f32 v[134:135], v[130:131], v[178:179] op_sel_hi:[1,0]
	v_pk_mul_f32 v[130:131], v[132:133], v[178:179] op_sel_hi:[1,0]
	v_pk_mul_f32 v[154:155], v[58:59], v[136:137]
	v_pk_mul_f32 v[130:131], v[62:63], v[130:131]
	v_pk_mul_f32 v[132:133], v[60:61], v[134:135]
	s_and_b64 vcc, exec, s[22:23]
	s_cbranch_vccz .LBB0_472
	v_mad_i64_i32 v[178:179], s[2:3], v185, s33, v[96:97]
	v_mov_b64_e32 v[180:181], s[36:37]
	v_mad_u64_u32 v[180:181], s[2:3], v178, s21, v[180:181]
	v_mad_i32_i24 v181, v179, s21, v181
	v_lshl_add_u64 v[178:179], v[172:173], 1, v[180:181]
	v_cvt_pk_bf16_f32 v134, v156, v157
	v_cvt_pk_bf16_f32 v135, v154, v155
	v_cvt_pk_bf16_f32 v136, v132, v133
	v_cvt_pk_bf16_f32 v137, v130, v131
	global_store_dwordx4 v[178:179], v[134:137], off sc1
	s_mov_b64 s[12:13], 0

.LBB0_482:
	s_waitcnt lgkmcnt(0)
	v_fma_f32 v130, s2, v148, v196
	v_rsq_f32_e32 v130, v130
	s_and_b64 vcc, exec, s[44:45]
	s_mov_b64 s[12:13], -1
	v_pk_mul_f32 v[126:127], v[126:127], v[130:131] op_sel_hi:[1,0]
	v_pk_mul_f32 v[128:129], v[128:129], v[130:131] op_sel_hi:[1,0]
	v_pk_mul_f32 v[132:133], v[122:123], v[130:131] op_sel_hi:[1,0]
	v_pk_mul_f32 v[124:125], v[124:125], v[130:131] op_sel_hi:[1,0]
	v_pk_mul_f32 v[122:123], v[58:59], v[128:129]
	v_pk_mul_f32 v[126:127], v[56:57], v[126:127]
	v_pk_mul_f32 v[124:125], v[62:63], v[124:125]
	v_pk_mul_f32 v[128:129], v[60:61], v[132:133]
	s_cbranch_vccnz .LBB0_484
	v_or_b32_e32 v148, 1, v185
	v_mad_i64_i32 v[152:153], s[2:3], v148, s33, v[96:97]
	v_mov_b64_e32 v[154:155], s[36:37]
	v_mad_u64_u32 v[154:155], s[2:3], v152, s21, v[154:155]
	v_mad_i32_i24 v155, v153, s21, v155
	v_lshl_add_u64 v[152:153], v[172:173], 1, v[154:155]
	s_mov_b64 s[12:13], 0
	v_cvt_pk_bf16_f32 v130, v126, v127
	v_cvt_pk_bf16_f32 v131, v122, v123
	v_cvt_pk_bf16_f32 v132, v128, v129
	v_cvt_pk_bf16_f32 v133, v124, v125
	global_store_dwordx4 v[152:153], v[130:133], off sc1

.LBB0_496:
	v_add_u32_e32 v96, s4, v96
	s_waitcnt lgkmcnt(0)
	v_add_u32_e32 v131, 0xffffe000, v96
	v_ashrrev_i32_e32 v130, 12, v96
	v_lshrrev_b32_e32 v131, 8, v131
	v_cmp_gt_i32_e32 vcc, s77, v96
	s_mov_b64 s[12:13], -1
	s_nop 0
	v_cndmask_b32_e32 v131, v131, v130, vcc
	v_cndmask_b32_e32 v130, v213, v247, vcc
	v_and_b32_e32 v96, v130, v96
	v_fma_f32 v130, s2, v134, v196
	v_rsq_f32_e32 v130, v130
	v_or_b32_e32 v132, 0x1000, v96
	v_lshlrev_b32_e32 v147, 2, v131
	v_cndmask_b32_e32 v96, v132, v96, vcc
	v_pk_mul_f32 v[118:119], v[118:119], v[130:131] op_sel_hi:[1,0]
	v_pk_mul_f32 v[120:121], v[120:121], v[130:131] op_sel_hi:[1,0]
	v_pk_mul_f32 v[134:135], v[56:57], v[118:119]
	v_pk_mul_f32 v[118:119], v[114:115], v[130:131] op_sel_hi:[1,0]
	v_pk_mul_f32 v[114:115], v[116:117], v[130:131] op_sel_hi:[1,0]
	v_add_u32_e32 v137, s5, v147
	v_pk_mul_f32 v[132:133], v[58:59], v[120:121]
	v_pk_mul_f32 v[114:115], v[62:63], v[114:115]
	v_pk_mul_f32 v[116:117], v[60:61], v[118:119]
	s_and_b64 vcc, exec, s[44:45]
	s_cbranch_vccnz .LBB0_498
	v_mad_i64_i32 v[130:131], s[2:3], v137, s33, v[96:97]
	v_mov_b64_e32 v[148:149], s[36:37]
	v_mad_u64_u32 v[148:149], s[2:3], v130, s21, v[148:149]
	v_mad_i32_i24 v149, v131, s21, v149
	v_lshl_add_u64 v[130:131], v[172:173], 1, v[148:149]
	s_mov_b64 s[12:13], 0
	v_cvt_pk_bf16_f32 v118, v134, v135
	v_cvt_pk_bf16_f32 v119, v132, v133
	v_cvt_pk_bf16_f32 v120, v116, v117
	v_cvt_pk_bf16_f32 v121, v114, v115
	global_store_dwordx4 v[130:131], v[118:121], off sc1

.LBB0_508:
	s_waitcnt lgkmcnt(0)
	v_fma_f32 v114, s2, v132, v196
	v_rsq_f32_e32 v114, v114
	s_and_b64 vcc, exec, s[44:45]
	s_mov_b64 s[12:13], -1
	v_pk_mul_f32 v[110:111], v[110:111], v[114:115] op_sel_hi:[1,0]
	v_pk_mul_f32 v[112:113], v[112:113], v[114:115] op_sel_hi:[1,0]
	v_pk_mul_f32 v[116:117], v[106:107], v[114:115] op_sel_hi:[1,0]
	v_pk_mul_f32 v[108:109], v[108:109], v[114:115] op_sel_hi:[1,0]
	v_pk_mul_f32 v[106:107], v[58:59], v[112:113]
	v_pk_mul_f32 v[110:111], v[56:57], v[110:111]
	v_pk_mul_f32 v[108:109], v[62:63], v[108:109]
	v_pk_mul_f32 v[112:113], v[60:61], v[116:117]
	s_cbranch_vccnz .LBB0_510
	v_or_b32_e32 v132, 1, v137
	v_mad_i64_i32 v[132:133], s[2:3], v132, s33, v[96:97]
	v_mov_b64_e32 v[134:135], s[36:37]
	v_mad_u64_u32 v[134:135], s[2:3], v132, s21, v[134:135]
	v_mad_i32_i24 v135, v133, s21, v135
	v_lshl_add_u64 v[132:133], v[172:173], 1, v[134:135]
	s_mov_b64 s[12:13], 0
	v_cvt_pk_bf16_f32 v114, v110, v111
	v_cvt_pk_bf16_f32 v115, v106, v107
	v_cvt_pk_bf16_f32 v116, v112, v113
	v_cvt_pk_bf16_f32 v117, v108, v109
	global_store_dwordx4 v[132:133], v[114:117], off sc1

.LBB0_522:
	v_add_u32_e32 v96, s4, v96
	s_waitcnt lgkmcnt(0)
	v_add_u32_e32 v115, 0xffffe000, v96
	v_ashrrev_i32_e32 v114, 12, v96
	v_lshrrev_b32_e32 v115, 8, v115
	v_cmp_gt_i32_e32 vcc, s77, v96
	s_mov_b64 s[12:13], -1
	s_nop 0
	v_cndmask_b32_e32 v115, v115, v114, vcc
	v_cndmask_b32_e32 v114, v248, v249, vcc
	v_and_b32_e32 v96, v114, v96
	v_fma_f32 v114, s2, v118, v196
	v_rsq_f32_e32 v114, v114
	v_or_b32_e32 v116, 0x1000, v96
	v_lshlrev_b32_e32 v131, 2, v115
	v_cndmask_b32_e32 v96, v116, v96, vcc
	v_pk_mul_f32 v[102:103], v[102:103], v[114:115] op_sel_hi:[1,0]
	v_pk_mul_f32 v[104:105], v[104:105], v[114:115] op_sel_hi:[1,0]
	v_pk_mul_f32 v[118:119], v[56:57], v[102:103]
	v_pk_mul_f32 v[102:103], v[98:99], v[114:115] op_sel_hi:[1,0]
	v_pk_mul_f32 v[98:99], v[100:101], v[114:115] op_sel_hi:[1,0]
	v_add_u32_e32 v121, s5, v131
	v_pk_mul_f32 v[116:117], v[58:59], v[104:105]
	v_pk_mul_f32 v[98:99], v[62:63], v[98:99]
	v_pk_mul_f32 v[100:101], v[60:61], v[102:103]
	s_and_b64 vcc, exec, s[44:45]
	s_cbranch_vccnz .LBB0_524
	v_mad_i64_i32 v[114:115], s[2:3], v121, s33, v[96:97]
	v_mov_b64_e32 v[132:133], s[36:37]
	v_mad_u64_u32 v[132:133], s[2:3], v114, s21, v[132:133]
	v_mad_i32_i24 v133, v115, s21, v133
	v_lshl_add_u64 v[114:115], v[172:173], 1, v[132:133]
	s_mov_b64 s[12:13], 0
	v_cvt_pk_bf16_f32 v102, v118, v119
	v_cvt_pk_bf16_f32 v103, v116, v117
	v_cvt_pk_bf16_f32 v104, v100, v101
	v_cvt_pk_bf16_f32 v105, v98, v99
	global_store_dwordx4 v[114:115], v[102:105], off sc1

.LBB0_534:
	s_waitcnt lgkmcnt(0)
	v_fma_f32 v98, s2, v116, v196
	v_rsq_f32_e32 v98, v98
	s_and_b64 vcc, exec, s[44:45]
	s_mov_b64 s[12:13], -1
	v_pk_mul_f32 v[92:93], v[92:93], v[98:99] op_sel_hi:[1,0]
	v_pk_mul_f32 v[94:95], v[94:95], v[98:99] op_sel_hi:[1,0]
	v_pk_mul_f32 v[100:101], v[88:89], v[98:99] op_sel_hi:[1,0]
	v_pk_mul_f32 v[90:91], v[90:91], v[98:99] op_sel_hi:[1,0]
	v_pk_mul_f32 v[88:89], v[58:59], v[94:95]
	v_pk_mul_f32 v[92:93], v[56:57], v[92:93]
	v_pk_mul_f32 v[90:91], v[62:63], v[90:91]
	v_pk_mul_f32 v[94:95], v[60:61], v[100:101]
	s_cbranch_vccnz .LBB0_536
	v_or_b32_e32 v116, 1, v121
	v_mad_i64_i32 v[116:117], s[2:3], v116, s33, v[96:97]
	v_mov_b64_e32 v[118:119], s[36:37]
	v_mad_u64_u32 v[118:119], s[2:3], v116, s21, v[118:119]
	v_mad_i32_i24 v119, v117, s21, v119
	v_lshl_add_u64 v[116:117], v[172:173], 1, v[118:119]
	s_mov_b64 s[12:13], 0
	v_cvt_pk_bf16_f32 v98, v92, v93
	v_cvt_pk_bf16_f32 v99, v88, v89
	v_cvt_pk_bf16_f32 v100, v94, v95
	v_cvt_pk_bf16_f32 v101, v90, v91
	global_store_dwordx4 v[116:117], v[98:101], off sc1

.LBB0_548:
	v_add_u32_e32 v96, s4, v96
	s_waitcnt lgkmcnt(0)
	v_add_u32_e32 v99, 0xffffe000, v96
	v_ashrrev_i32_e32 v98, 12, v96
	v_lshrrev_b32_e32 v99, 8, v99
	v_cmp_gt_i32_e32 vcc, s77, v96
	v_mov_b32_e32 v100, 0xfff
	s_mov_b64 s[12:13], -1
	v_cndmask_b32_e32 v99, v99, v98, vcc
	v_mov_b32_e32 v98, 0xff
	v_cndmask_b32_e32 v98, v98, v100, vcc
	v_and_b32_e32 v96, v98, v96
	v_fma_f32 v98, s2, v102, v196
	v_rsq_f32_e32 v98, v98
	v_or_b32_e32 v100, 0x1000, v96
	v_lshlrev_b32_e32 v105, 2, v99
	v_cndmask_b32_e32 v96, v100, v96, vcc
	v_pk_mul_f32 v[84:85], v[84:85], v[98:99] op_sel_hi:[1,0]
	v_pk_mul_f32 v[86:87], v[86:87], v[98:99] op_sel_hi:[1,0]
	v_pk_mul_f32 v[102:103], v[56:57], v[84:85]
	v_pk_mul_f32 v[84:85], v[80:81], v[98:99] op_sel_hi:[1,0]
	v_pk_mul_f32 v[80:81], v[82:83], v[98:99] op_sel_hi:[1,0]
	v_add_u32_e32 v104, s5, v105
	v_pk_mul_f32 v[100:101], v[58:59], v[86:87]
	v_pk_mul_f32 v[80:81], v[62:63], v[80:81]
	v_pk_mul_f32 v[82:83], v[60:61], v[84:85]
	s_and_b64 vcc, exec, s[44:45]
	s_cbranch_vccnz .LBB0_550
	v_mad_i64_i32 v[98:99], s[2:3], v104, s33, v[96:97]
	v_mov_b64_e32 v[116:117], s[36:37]
	v_mad_u64_u32 v[116:117], s[2:3], v98, s21, v[116:117]
	v_mad_i32_i24 v117, v99, s21, v117
	v_lshl_add_u64 v[98:99], v[172:173], 1, v[116:117]
	s_mov_b64 s[12:13], 0
	v_cvt_pk_bf16_f32 v84, v102, v103
	v_cvt_pk_bf16_f32 v85, v100, v101
	v_cvt_pk_bf16_f32 v86, v82, v83
	v_cvt_pk_bf16_f32 v87, v80, v81
	global_store_dwordx4 v[98:99], v[84:87], off sc1

.LBB0_560:
	s_waitcnt lgkmcnt(0)
	v_fma_f32 v80, s2, v100, v196
	v_rsq_f32_e32 v80, v80
	s_and_b64 vcc, exec, s[44:45]
	s_mov_b64 s[12:13], -1
	v_pk_mul_f32 v[76:77], v[76:77], v[80:81] op_sel_hi:[1,0]
	v_pk_mul_f32 v[78:79], v[78:79], v[80:81] op_sel_hi:[1,0]
	v_pk_mul_f32 v[82:83], v[72:73], v[80:81] op_sel_hi:[1,0]
	v_pk_mul_f32 v[74:75], v[74:75], v[80:81] op_sel_hi:[1,0]
	v_pk_mul_f32 v[72:73], v[58:59], v[78:79]
	v_pk_mul_f32 v[76:77], v[56:57], v[76:77]
	v_pk_mul_f32 v[74:75], v[62:63], v[74:75]
	v_pk_mul_f32 v[78:79], v[60:61], v[82:83]
	s_cbranch_vccnz .LBB0_562
	v_or_b32_e32 v100, 1, v104
	v_mad_i64_i32 v[100:101], s[2:3], v100, s33, v[96:97]
	v_mov_b64_e32 v[102:103], s[36:37]
	v_mad_u64_u32 v[102:103], s[2:3], v100, s21, v[102:103]
	v_mad_i32_i24 v103, v101, s21, v103
	v_lshl_add_u64 v[100:101], v[172:173], 1, v[102:103]
	s_mov_b64 s[12:13], 0
	v_cvt_pk_bf16_f32 v80, v76, v77
	v_cvt_pk_bf16_f32 v81, v72, v73
	v_cvt_pk_bf16_f32 v82, v78, v79
	v_cvt_pk_bf16_f32 v83, v74, v75
	global_store_dwordx4 v[100:101], v[80:83], off sc1

.LBB0_574:
	s_waitcnt lgkmcnt(0)
	v_add_u32_e32 v80, s4, v86
	v_add_u32_e32 v82, 0xffffe000, v80
	v_ashrrev_i32_e32 v81, 12, v80
	v_lshrrev_b32_e32 v82, 8, v82
	v_cmp_gt_i32_e32 vcc, s77, v80
	s_mov_b64 s[12:13], -1
	s_nop 0
	v_cndmask_b32_e32 v81, v82, v81, vcc
	v_cndmask_b32_e32 v82, v246, v210, vcc
	v_and_b32_e32 v82, v82, v80
	v_fma_f32 v80, s2, v84, v196
	v_rsq_f32_e32 v80, v80
	v_or_b32_e32 v83, 0x1000, v82
	v_lshlrev_b32_e32 v99, 2, v81
	v_cndmask_b32_e32 v96, v83, v82, vcc
	v_pk_mul_f32 v[68:69], v[68:69], v[80:81] op_sel_hi:[1,0]
	v_pk_mul_f32 v[70:71], v[70:71], v[80:81] op_sel_hi:[1,0]
	v_pk_mul_f32 v[84:85], v[56:57], v[68:69]
	v_pk_mul_f32 v[68:69], v[64:65], v[80:81] op_sel_hi:[1,0]
	v_pk_mul_f32 v[64:65], v[66:67], v[80:81] op_sel_hi:[1,0]
	v_add_u32_e32 v87, s5, v99
	v_pk_mul_f32 v[82:83], v[58:59], v[70:71]
	v_pk_mul_f32 v[64:65], v[62:63], v[64:65]
	v_pk_mul_f32 v[66:67], v[60:61], v[68:69]
	s_and_b64 vcc, exec, s[44:45]
	s_cbranch_vccnz .LBB0_576
	v_mad_i64_i32 v[80:81], s[2:3], v87, s33, v[96:97]
	v_mov_b64_e32 v[100:101], s[36:37]
	v_mad_u64_u32 v[100:101], s[2:3], v80, s21, v[100:101]
	v_mad_i32_i24 v101, v81, s21, v101
	v_lshl_add_u64 v[80:81], v[172:173], 1, v[100:101]
	s_mov_b64 s[12:13], 0
	v_cvt_pk_bf16_f32 v68, v84, v85
	v_cvt_pk_bf16_f32 v69, v82, v83
	v_cvt_pk_bf16_f32 v70, v66, v67
	v_cvt_pk_bf16_f32 v71, v64, v65
	global_store_dwordx4 v[80:81], v[68:71], off sc1

.LBB0_586:
	s_waitcnt lgkmcnt(0)
	v_fma_f32 v64, s2, v82, v196
	v_rsq_f32_e32 v64, v64
	s_and_b64 vcc, exec, s[44:45]
	s_mov_b64 s[12:13], -1
	v_pk_mul_f32 v[52:53], v[52:53], v[64:65] op_sel_hi:[1,0]
	v_pk_mul_f32 v[54:55], v[54:55], v[64:65] op_sel_hi:[1,0]
	v_pk_mul_f32 v[66:67], v[48:49], v[64:65] op_sel_hi:[1,0]
	v_pk_mul_f32 v[50:51], v[50:51], v[64:65] op_sel_hi:[1,0]
	v_pk_mul_f32 v[48:49], v[58:59], v[54:55]
	v_pk_mul_f32 v[52:53], v[56:57], v[52:53]
	v_pk_mul_f32 v[50:51], v[62:63], v[50:51]
	v_pk_mul_f32 v[54:55], v[60:61], v[66:67]
	s_cbranch_vccnz .LBB0_588
	v_or_b32_e32 v82, 1, v87
	v_mad_i64_i32 v[82:83], s[2:3], v82, s33, v[96:97]
	v_mov_b64_e32 v[84:85], s[36:37]
	v_mad_u64_u32 v[84:85], s[2:3], v82, s21, v[84:85]
	v_mad_i32_i24 v85, v83, s21, v85
	v_lshl_add_u64 v[82:83], v[172:173], 1, v[84:85]
	s_mov_b64 s[12:13], 0
	v_cvt_pk_bf16_f32 v64, v52, v53
	v_cvt_pk_bf16_f32 v65, v48, v49
	v_cvt_pk_bf16_f32 v66, v54, v55
	v_cvt_pk_bf16_f32 v67, v50, v51
	global_store_dwordx4 v[82:83], v[64:67], off sc1

.LBB0_600:
	s_waitcnt lgkmcnt(0)
	v_add_u32_e32 v64, s4, v68
	v_add_u32_e32 v66, 0xffffe000, v64
	v_ashrrev_i32_e32 v65, 12, v64
	v_lshrrev_b32_e32 v66, 8, v66
	v_cmp_gt_i32_e32 vcc, s77, v64
	s_mov_b64 s[12:13], -1
	s_nop 0
	v_cndmask_b32_e32 v65, v66, v65, vcc
	v_cndmask_b32_e32 v66, v213, v247, vcc
	v_and_b32_e32 v66, v66, v64
	v_fma_f32 v64, s2, v69, v196
	v_rsq_f32_e32 v64, v64
	v_or_b32_e32 v67, 0x1000, v66
	v_lshlrev_b32_e32 v71, 2, v65
	v_cndmask_b32_e32 v96, v67, v66, vcc
	v_pk_mul_f32 v[44:45], v[44:45], v[64:65] op_sel_hi:[1,0]
	v_pk_mul_f32 v[46:47], v[46:47], v[64:65] op_sel_hi:[1,0]
	v_pk_mul_f32 v[68:69], v[56:57], v[44:45]
	v_pk_mul_f32 v[44:45], v[40:41], v[64:65] op_sel_hi:[1,0]
	v_pk_mul_f32 v[40:41], v[42:43], v[64:65] op_sel_hi:[1,0]
	v_add_u32_e32 v70, s5, v71
	v_pk_mul_f32 v[66:67], v[58:59], v[46:47]
	v_pk_mul_f32 v[40:41], v[62:63], v[40:41]
	v_pk_mul_f32 v[42:43], v[60:61], v[44:45]
	s_and_b64 vcc, exec, s[44:45]
	s_cbranch_vccnz .LBB0_602
	v_mad_i64_i32 v[64:65], s[2:3], v70, s33, v[96:97]
	v_mov_b64_e32 v[82:83], s[36:37]
	v_mad_u64_u32 v[82:83], s[2:3], v64, s21, v[82:83]
	v_mad_i32_i24 v83, v65, s21, v83
	v_lshl_add_u64 v[64:65], v[172:173], 1, v[82:83]
	s_mov_b64 s[12:13], 0
	v_cvt_pk_bf16_f32 v44, v68, v69
	v_cvt_pk_bf16_f32 v45, v66, v67
	v_cvt_pk_bf16_f32 v46, v42, v43
	v_cvt_pk_bf16_f32 v47, v40, v41
	global_store_dwordx4 v[64:65], v[44:47], off sc1

.LBB0_612:
	s_waitcnt lgkmcnt(0)
	v_fma_f32 v40, s2, v66, v196
	v_rsq_f32_e32 v40, v40
	s_and_b64 vcc, exec, s[44:45]
	s_mov_b64 s[12:13], -1
	v_pk_mul_f32 v[36:37], v[36:37], v[40:41] op_sel_hi:[1,0]
	v_pk_mul_f32 v[38:39], v[38:39], v[40:41] op_sel_hi:[1,0]
	v_pk_mul_f32 v[42:43], v[32:33], v[40:41] op_sel_hi:[1,0]
	v_pk_mul_f32 v[34:35], v[34:35], v[40:41] op_sel_hi:[1,0]
	v_pk_mul_f32 v[32:33], v[58:59], v[38:39]
	v_pk_mul_f32 v[36:37], v[56:57], v[36:37]
	v_pk_mul_f32 v[34:35], v[62:63], v[34:35]
	v_pk_mul_f32 v[38:39], v[60:61], v[42:43]
	s_cbranch_vccnz .LBB0_614
	v_or_b32_e32 v66, 1, v70
	v_mad_i64_i32 v[66:67], s[2:3], v66, s33, v[96:97]
	v_mov_b64_e32 v[68:69], s[36:37]
	v_mad_u64_u32 v[68:69], s[2:3], v66, s21, v[68:69]
	v_mad_i32_i24 v69, v67, s21, v69
	v_lshl_add_u64 v[66:67], v[172:173], 1, v[68:69]
	s_mov_b64 s[12:13], 0
	v_cvt_pk_bf16_f32 v40, v36, v37
	v_cvt_pk_bf16_f32 v41, v32, v33
	v_cvt_pk_bf16_f32 v42, v38, v39
	v_cvt_pk_bf16_f32 v43, v34, v35
	global_store_dwordx4 v[66:67], v[40:43], off sc1

.LBB0_626:
	s_waitcnt lgkmcnt(0)
	v_add_u32_e32 v40, s4, v44
	v_add_u32_e32 v42, 0xffffe000, v40
	v_ashrrev_i32_e32 v41, 12, v40
	v_lshrrev_b32_e32 v42, 8, v42
	v_cmp_gt_i32_e32 vcc, s77, v40
	s_mov_b64 s[12:13], -1
	s_nop 0
	v_cndmask_b32_e32 v41, v42, v41, vcc
	v_cndmask_b32_e32 v42, v248, v249, vcc
	v_and_b32_e32 v42, v42, v40
	v_fma_f32 v40, s2, v45, v196
	v_rsq_f32_e32 v40, v40
	v_or_b32_e32 v43, 0x1000, v42
	v_lshlrev_b32_e32 v47, 2, v41
	v_cndmask_b32_e32 v96, v43, v42, vcc
	v_pk_mul_f32 v[28:29], v[28:29], v[40:41] op_sel_hi:[1,0]
	v_pk_mul_f32 v[30:31], v[30:31], v[40:41] op_sel_hi:[1,0]
	v_pk_mul_f32 v[44:45], v[56:57], v[28:29]
	v_pk_mul_f32 v[28:29], v[24:25], v[40:41] op_sel_hi:[1,0]
	v_pk_mul_f32 v[24:25], v[26:27], v[40:41] op_sel_hi:[1,0]
	v_add_u32_e32 v46, s5, v47
	v_pk_mul_f32 v[42:43], v[58:59], v[30:31]
	v_pk_mul_f32 v[24:25], v[62:63], v[24:25]
	v_pk_mul_f32 v[26:27], v[60:61], v[28:29]
	s_and_b64 vcc, exec, s[44:45]
	s_cbranch_vccnz .LBB0_628
	v_mad_i64_i32 v[40:41], s[2:3], v46, s33, v[96:97]
	v_mov_b64_e32 v[66:67], s[36:37]
	v_mad_u64_u32 v[66:67], s[2:3], v40, s21, v[66:67]
	v_mad_i32_i24 v67, v41, s21, v67
	v_lshl_add_u64 v[40:41], v[172:173], 1, v[66:67]
	s_mov_b64 s[12:13], 0
	v_cvt_pk_bf16_f32 v28, v44, v45
	v_cvt_pk_bf16_f32 v29, v42, v43
	v_cvt_pk_bf16_f32 v30, v26, v27
	v_cvt_pk_bf16_f32 v31, v24, v25
	global_store_dwordx4 v[40:41], v[28:31], off sc1

.LBB0_638:
	s_waitcnt lgkmcnt(0)
	v_fma_f32 v24, s2, v42, v196
	v_rsq_f32_e32 v24, v24
	s_and_b64 vcc, exec, s[44:45]
	s_mov_b64 s[12:13], -1
	v_pk_mul_f32 v[20:21], v[20:21], v[24:25] op_sel_hi:[1,0]
	v_pk_mul_f32 v[22:23], v[22:23], v[24:25] op_sel_hi:[1,0]
	v_pk_mul_f32 v[26:27], v[16:17], v[24:25] op_sel_hi:[1,0]
	v_pk_mul_f32 v[18:19], v[18:19], v[24:25] op_sel_hi:[1,0]
	v_pk_mul_f32 v[16:17], v[58:59], v[22:23]
	v_pk_mul_f32 v[20:21], v[56:57], v[20:21]
	v_pk_mul_f32 v[18:19], v[62:63], v[18:19]
	v_pk_mul_f32 v[22:23], v[60:61], v[26:27]
	s_cbranch_vccnz .LBB0_640
	v_or_b32_e32 v42, 1, v46
	v_mad_i64_i32 v[42:43], s[2:3], v42, s33, v[96:97]
	v_mov_b64_e32 v[44:45], s[36:37]
	v_mad_u64_u32 v[44:45], s[2:3], v42, s21, v[44:45]
	v_mad_i32_i24 v45, v43, s21, v45
	v_lshl_add_u64 v[42:43], v[172:173], 1, v[44:45]
	s_mov_b64 s[12:13], 0
	v_cvt_pk_bf16_f32 v24, v20, v21
	v_cvt_pk_bf16_f32 v25, v16, v17
	v_cvt_pk_bf16_f32 v26, v22, v23
	v_cvt_pk_bf16_f32 v27, v18, v19
	global_store_dwordx4 v[42:43], v[24:27], off sc1

.LBB0_650:
	s_waitcnt lgkmcnt(0)
	v_add_u32_e32 v16, s4, v20
	v_add_u32_e32 v18, 0xffffe000, v16
	v_ashrrev_i32_e32 v17, 12, v16
	v_lshrrev_b32_e32 v18, 8, v18
	v_cmp_gt_i32_e32 vcc, s77, v16
	v_mov_b32_e32 v19, 0xfff
	s_mov_b64 s[12:13], -1
	v_cndmask_b32_e32 v17, v18, v17, vcc
	v_mov_b32_e32 v18, 0xff
	v_cndmask_b32_e32 v18, v18, v19, vcc
	v_and_b32_e32 v18, v18, v16
	v_fma_f32 v16, s2, v21, v196
	v_rsq_f32_e32 v16, v16
	v_or_b32_e32 v19, 0x1000, v18
	v_lshlrev_b32_e32 v23, 2, v17
	v_cndmask_b32_e32 v96, v19, v18, vcc
	v_pk_mul_f32 v[12:13], v[12:13], v[16:17] op_sel_hi:[1,0]
	v_pk_mul_f32 v[14:15], v[14:15], v[16:17] op_sel_hi:[1,0]
	v_pk_mul_f32 v[20:21], v[56:57], v[12:13]
	v_pk_mul_f32 v[12:13], v[8:9], v[16:17] op_sel_hi:[1,0]
	v_pk_mul_f32 v[8:9], v[10:11], v[16:17] op_sel_hi:[1,0]
	v_add_u32_e32 v22, s5, v23
	v_pk_mul_f32 v[18:19], v[58:59], v[14:15]
	v_pk_mul_f32 v[8:9], v[62:63], v[8:9]
	v_pk_mul_f32 v[10:11], v[60:61], v[12:13]
	s_and_b64 vcc, exec, s[44:45]
	s_cbranch_vccnz .LBB0_652
	v_mad_i64_i32 v[16:17], s[2:3], v22, s33, v[96:97]
	v_mov_b64_e32 v[26:27], s[36:37]
	v_mad_u64_u32 v[26:27], s[2:3], v16, s21, v[26:27]
	v_mad_i32_i24 v27, v17, s21, v27
	v_lshl_add_u64 v[16:17], v[172:173], 1, v[26:27]
	s_mov_b64 s[12:13], 0
	v_cvt_pk_bf16_f32 v12, v20, v21
	v_cvt_pk_bf16_f32 v13, v18, v19
	v_cvt_pk_bf16_f32 v14, v10, v11
	v_cvt_pk_bf16_f32 v15, v8, v9
	global_store_dwordx4 v[16:17], v[12:15], off sc1

.LBB0_662:
	s_waitcnt lgkmcnt(0)
	v_fma_f32 v8, s2, v18, v196
	v_rsq_f32_e32 v8, v8
	s_and_b64 vcc, exec, s[44:45]
	s_mov_b64 s[12:13], -1
	v_pk_mul_f32 v[4:5], v[4:5], v[8:9] op_sel_hi:[1,0]
	v_pk_mul_f32 v[6:7], v[6:7], v[8:9] op_sel_hi:[1,0]
	v_pk_mul_f32 v[10:11], v[0:1], v[8:9] op_sel_hi:[1,0]
	v_pk_mul_f32 v[2:3], v[2:3], v[8:9] op_sel_hi:[1,0]
	v_pk_mul_f32 v[0:1], v[58:59], v[6:7]
	v_pk_mul_f32 v[4:5], v[56:57], v[4:5]
	v_pk_mul_f32 v[2:3], v[62:63], v[2:3]
	v_pk_mul_f32 v[6:7], v[60:61], v[10:11]
	s_cbranch_vccnz .LBB0_665
	v_or_b32_e32 v18, 1, v22
	v_mad_i64_i32 v[18:19], s[2:3], v18, s33, v[96:97]
	v_mov_b64_e32 v[20:21], s[36:37]
	v_mad_u64_u32 v[20:21], s[2:3], v18, s21, v[20:21]
	v_mad_i32_i24 v21, v19, s21, v21
	v_lshl_add_u64 v[18:19], v[172:173], 1, v[20:21]
	v_cvt_pk_bf16_f32 v8, v4, v5
	v_cvt_pk_bf16_f32 v9, v0, v1
	v_cvt_pk_bf16_f32 v10, v6, v7
	v_cvt_pk_bf16_f32 v11, v2, v3
	global_store_dwordx4 v[18:19], v[8:11], off sc1
	s_cbranch_execz .LBB0_666

.LBB0_698:
	s_or_b64 exec, exec, s[48:49]
	v_ashrrev_i32_e32 v96, 4, v152
	v_lshlrev_b32_e32 v153, 3, v96
	v_add_u32_e32 v158, s40, v153
	v_ashrrev_i32_e32 v159, 31, v158
	s_waitcnt lgkmcnt(0)
	s_barrier
	s_waitcnt lgkmcnt(0)
	v_lshl_add_u64 v[106:107], v[158:159], 2, s[12:13]
	global_load_dwordx4 v[110:113], v[106:107], off
	s_nop 0
	global_load_dwordx4 v[106:109], v[106:107], off offset:16
	s_lshl_b32 s2, s46, 8
	v_and_b32_e32 v159, 60, v151
	s_add_i32 s7, s2, s37
	v_and_b32_e32 v147, 16, v151
	v_or_b32_e32 v150, s37, v159
	v_add_u32_e32 v146, s54, v96
	v_lshlrev_b32_e32 v96, 5, v96
	s_add_i32 s3, s7, 0x80
	v_and_or_b32 v162, v96, 32, v147
	v_lshl_add_u32 v96, v150, 4, 0
	s_cmpk_lt_i32 s3, 0x2000
	s_movk_i32 s35, 0xfc0
	v_add_u32_e32 v150, 0x20400, v96
	s_cselect_b32 s2, s35, 0xc0
	ds_read_b128 v[154:157], v150
	s_and_b32 s2, s2, s3
	s_or_b32 s6, s2, 0x1000
	s_cmpk_lt_i32 s3, 0x2000
	s_cselect_b32 s2, s2, s6
	s_add_i32 s25, s7, 0xffffe080
	s_ashr_i32 s6, s3, 12
	s_lshr_b32 s25, s25, 8
	s_waitcnt lgkmcnt(0)
	v_mov_b32_e32 v160, v155
	v_mov_b32_e32 v161, v156
	v_mov_b32_e32 v155, v157
	s_cmpk_lt_i32 s3, 0x2000
	v_pk_add_f32 v[154:155], v[160:161], v[154:155]
	s_cselect_b32 s3, s6, s25
	s_cmpk_lt_i32 s7, 0x2000
	v_add_f32_e32 v96, v154, v155
	s_cselect_b32 s6, s35, 0xc0
	v_fmamk_f32 v96, v96, 0x3c000000, v196
	s_and_b32 s6, s6, s7
	v_rsq_f32_e32 v96, v96
	s_or_b32 s25, s6, 0x1000
	s_cmpk_lt_i32 s7, 0x2000
	s_cselect_b32 s6, s6, s25
	v_or_b32_e32 v154, s6, v159
	s_add_i32 s35, s7, 0xffffe000
	v_pk_mul_f32 v[134:135], v[134:135], v[96:97] op_sel_hi:[1,0]
	v_pk_mul_f32 v[136:137], v[136:137], v[96:97] op_sel_hi:[1,0]
	v_pk_mul_f32 v[130:131], v[130:131], v[96:97] op_sel_hi:[1,0]
	v_pk_mul_f32 v[132:133], v[132:133], v[96:97] op_sel_hi:[1,0]
	v_lshrrev_b32_e32 v96, 5, v154
	v_lshlrev_b32_e32 v155, 1, v154
	v_lshrrev_b32_e32 v154, 1, v154
	s_ashr_i32 s25, s7, 12
	s_lshr_b32 s35, s35, 8
	v_and_b32_e32 v155, 8, v155
	v_and_b32_e32 v154, 4, v154
	s_cmpk_lt_i32 s7, 0x2000
	v_or3_b32 v160, v155, v154, v162
	s_cselect_b32 s7, s25, s35
	s_lshl_b32 s7, s7, 2
	s_add_i32 s7, s7, s44
	v_ashrrev_i32_e32 v146, 1, v146
	s_mul_i32 s35, s7, 0x198000
	v_readlane_b32 s46, v252, 3
	v_ashrrev_i32_e32 v147, 31, v146
	s_mul_hi_i32 s25, s7, 0x198000
	s_add_u32 s48, s46, s35
	v_readlane_b32 s35, v252, 4
	v_lshlrev_b64 v[146:147], 10, v[146:147]
	s_addc_u32 s49, s35, s25
	v_mul_u32_u24_e32 v96, 0x3000, v96
	s_mul_hi_i32 s25, s7, 0x110000
	s_mul_i32 s7, s7, 0x110000
	v_readlane_b32 s50, v252, 5
	v_readlane_b32 s51, v252, 6
	s_waitcnt vmcnt(0)
	v_pk_mul_f32 v[136:137], v[112:113], v[136:137]
	v_pk_mul_f32 v[134:135], v[110:111], v[134:135]
	v_pk_mul_f32 v[154:155], v[108:109], v[132:133]
	v_pk_mul_f32 v[132:133], v[106:107], v[130:131]
	v_cvt_pk_bf16_f32 v130, v134, v135
	v_cvt_pk_bf16_f32 v131, v136, v137
	s_nop 0
	v_cvt_pk_bf16_f32 v132, v132, v133
	v_cvt_pk_bf16_f32 v133, v154, v155
	ds_read_b128 v[134:137], v150 offset:16
	v_lshl_add_u64 v[154:155], s[48:49], 0, v[146:147]
	v_lshl_add_u64 v[154:155], v[154:155], 0, v[96:97]
	s_add_u32 s48, s50, s7
	s_addc_u32 s49, s51, s25
	s_waitcnt lgkmcnt(0)
	v_mov_b32_e32 v156, v135
	v_mov_b32_e32 v157, v136
	v_mov_b32_e32 v135, v137
	v_pk_add_f32 v[134:135], v[156:157], v[134:135]
	s_lshl_b32 s3, s3, 2
	v_add_f32_e32 v96, v134, v135
	v_fmamk_f32 v96, v96, 0x3c000000, v196
	v_rsq_f32_e32 v134, v96
	v_lshlrev_b32_e32 v96, 4, v160
	v_lshl_add_u64 v[136:137], v[154:155], 0, v[96:97]
	global_store_dwordx4 v[136:137], v[130:133], off sc1
	v_pk_mul_f32 v[126:127], v[126:127], v[134:135] op_sel_hi:[1,0]
	v_pk_mul_f32 v[128:129], v[128:129], v[134:135] op_sel_hi:[1,0]
	v_pk_mul_f32 v[122:123], v[122:123], v[134:135] op_sel_hi:[1,0]
	v_pk_mul_f32 v[124:125], v[124:125], v[134:135] op_sel_hi:[1,0]
	v_pk_mul_f32 v[128:129], v[112:113], v[128:129]
	v_pk_mul_f32 v[126:127], v[110:111], v[126:127]
	v_pk_mul_f32 v[130:131], v[108:109], v[124:125]
	v_pk_mul_f32 v[124:125], v[106:107], v[122:123]
	v_cvt_pk_bf16_f32 v122, v126, v127
	v_cvt_pk_bf16_f32 v123, v128, v129
	s_add_i32 s3, s3, s44
	v_cvt_pk_bf16_f32 v124, v124, v125
	v_cvt_pk_bf16_f32 v125, v130, v131
	ds_read_b128 v[126:129], v150 offset:32
	global_store_dwordx4 v[136:137], v[122:125], off offset:16 sc1
	s_mul_hi_i32 s7, s3, 0x198000
	s_waitcnt lgkmcnt(0)
	v_mov_b32_e32 v130, v127
	v_mov_b32_e32 v131, v128
	v_mov_b32_e32 v127, v129
	v_pk_add_f32 v[126:127], v[130:131], v[126:127]
	v_and_b32_e32 v124, 56, v151
	v_add_f32_e32 v96, v126, v127
	v_fmamk_f32 v96, v96, 0x3c000000, v196
	v_rsq_f32_e32 v96, v96
	v_and_b32_e32 v126, 1, v152
	v_ashrrev_i32_e32 v125, 5, v158
	v_cmp_eq_u32_e32 vcc, 0, v126
	v_pk_mul_f32 v[118:119], v[118:119], v[96:97] op_sel_hi:[1,0]
	v_pk_mul_f32 v[120:121], v[120:121], v[96:97] op_sel_hi:[1,0]
	v_pk_mul_f32 v[114:115], v[114:115], v[96:97] op_sel_hi:[1,0]
	v_pk_mul_f32 v[116:117], v[116:117], v[96:97] op_sel_hi:[1,0]
	v_pk_mul_f32 v[120:121], v[112:113], v[120:121]
	v_pk_mul_f32 v[118:119], v[110:111], v[118:119]
	v_pk_mul_f32 v[122:123], v[108:109], v[116:117]
	v_pk_mul_f32 v[116:117], v[106:107], v[114:115]
	v_cvt_pk_bf16_f32 v114, v118, v119
	v_cvt_pk_bf16_f32 v115, v120, v121
	v_lshlrev_b32_e32 v96, 2, v126
	v_cvt_pk_bf16_f32 v116, v116, v117
	v_cvt_pk_bf16_f32 v117, v122, v123
	ds_read_b128 v[118:121], v150 offset:48
	v_and_or_b32 v127, v153, 24, v96
	global_store_dwordx4 v[136:137], v[114:117], off offset:32 sc1
	s_waitcnt lgkmcnt(0)
	v_mov_b32_e32 v122, v119
	v_mov_b32_e32 v123, v120
	v_mov_b32_e32 v119, v121
	v_pk_add_f32 v[118:119], v[122:123], v[118:119]
	s_nop 0
	v_add_f32_e32 v96, v118, v119
	v_fmamk_f32 v96, v96, 0x3c000000, v196
	v_rsq_f32_e32 v96, v96
	s_nop 0
	v_pk_mul_f32 v[102:103], v[102:103], v[96:97] op_sel_hi:[1,0]
	v_pk_mul_f32 v[98:99], v[98:99], v[96:97] op_sel_hi:[1,0]
	v_pk_mul_f32 v[100:101], v[100:101], v[96:97] op_sel_hi:[1,0]
	v_pk_mul_f32 v[104:105], v[104:105], v[96:97] op_sel_hi:[1,0]
	v_pk_mul_f32 v[102:103], v[110:111], v[102:103]
	v_pk_mul_f32 v[114:115], v[108:109], v[100:101]
	v_pk_mul_f32 v[100:101], v[106:107], v[98:99]
	v_cvt_pk_bf16_f32 v98, v102, v103
	v_pk_mul_f32 v[104:105], v[112:113], v[104:105]
	s_nop 0
	v_cvt_pk_bf16_f32 v99, v104, v105
	v_cvt_pk_bf16_f32 v100, v100, v101
	v_cvt_pk_bf16_f32 v101, v114, v115
	global_store_dwordx4 v[136:137], v[98:101], off offset:48 sc1
	v_cvt_pk_bf16_f32 v68, v68, v80
	v_cvt_pk_bf16_f32 v80, v84, v92
	v_cvt_pk_bf16_f32 v64, v64, v72
	v_cvt_pk_bf16_f32 v72, v76, v88
	v_mov_b32_e32 v88, v97
	s_nop 0
	v_or_b32_e32 v98, s6, v124
	v_lshrrev_b32_e32 v99, 2, v98
	v_lshlrev_b32_e32 v96, 8, v98
	v_and_b32_e32 v99, 4, v99
	v_lshlrev_b32_e32 v98, 2, v98
	v_add_lshl_u32 v99, v99, v125, 6
	v_and_b32_e32 v98, 32, v98
	v_or3_b32 v104, v99, v98, v127
	v_cndmask_b32_e32 v76, v68, v64, vcc
	v_and_b32_e32 v96, 0x1fe000, v96
	v_cndmask_b32_e32 v84, v80, v72, vcc
	v_mov_b32_dpp v88, v76 quad_perm:[1,0,3,2] row_mask:0xf bank_mask:0xf
	v_mov_b32_e32 v76, v97
	v_lshlrev_b32_e32 v104, 4, v104
	v_lshl_add_u64 v[102:103], s[48:49], 0, v[96:97]
	v_mov_b32_dpp v76, v84 quad_perm:[1,0,3,2] row_mask:0xf bank_mask:0xf
	v_ashrrev_i32_e32 v105, 31, v104
	v_cndmask_b32_e32 v100, v64, v88, vcc
	v_cndmask_b32_e32 v98, v88, v68, vcc
	v_cndmask_b32_e32 v101, v72, v76, vcc
	v_cndmask_b32_e32 v99, v76, v80, vcc
	v_lshl_add_u64 v[102:103], v[102:103], 0, v[104:105]
	global_store_dwordx4 v[102:103], v[98:101], off sc1
	v_cvt_pk_bf16_f32 v64, v69, v81
	v_cvt_pk_bf16_f32 v68, v85, v93
	v_cvt_pk_bf16_f32 v65, v65, v73
	v_mov_b32_e32 v76, v97
	v_cndmask_b32_e32 v72, v64, v65, vcc
	v_cvt_pk_bf16_f32 v69, v77, v89
	s_mul_i32 s6, s3, 0x198000
	v_cndmask_b32_e32 v73, v68, v69, vcc
	v_mov_b32_dpp v76, v72 quad_perm:[1,0,3,2] row_mask:0xf bank_mask:0xf
	v_mov_b32_e32 v72, v97
	v_cndmask_b32_e32 v100, v65, v76, vcc
	v_cndmask_b32_e32 v98, v76, v64, vcc
	v_mov_b32_dpp v72, v73 quad_perm:[1,0,3,2] row_mask:0xf bank_mask:0xf
	v_cndmask_b32_e32 v101, v69, v72, vcc
	v_cndmask_b32_e32 v99, v72, v68, vcc
	global_store_dwordx4 v[102:103], v[98:101], off offset:16 sc1
	v_cvt_pk_bf16_f32 v64, v70, v82
	v_cvt_pk_bf16_f32 v65, v86, v94
	v_cvt_pk_bf16_f32 v66, v66, v74
	v_mov_b32_e32 v72, v97
	v_cndmask_b32_e32 v69, v64, v66, vcc
	v_cvt_pk_bf16_f32 v68, v78, v90
	s_add_u32 s6, s46, s6
	v_cndmask_b32_e32 v70, v65, v68, vcc
	v_mov_b32_dpp v72, v69 quad_perm:[1,0,3,2] row_mask:0xf bank_mask:0xf
	v_mov_b32_e32 v69, v97
	v_cndmask_b32_e32 v100, v66, v72, vcc
	v_cndmask_b32_e32 v98, v72, v64, vcc
	v_mov_b32_dpp v69, v70 quad_perm:[1,0,3,2] row_mask:0xf bank_mask:0xf
	v_cndmask_b32_e32 v101, v68, v69, vcc
	v_cndmask_b32_e32 v99, v69, v65, vcc
	global_store_dwordx4 v[102:103], v[98:101], off offset:32 sc1
	v_cvt_pk_bf16_f32 v64, v71, v83
	v_cvt_pk_bf16_f32 v65, v87, v95
	v_cvt_pk_bf16_f32 v66, v67, v75
	v_mov_b32_e32 v70, v97
	v_cndmask_b32_e32 v68, v64, v66, vcc
	v_cvt_pk_bf16_f32 v67, v79, v91
	s_addc_u32 s7, s35, s7
	v_cndmask_b32_e32 v69, v65, v67, vcc
	v_mov_b32_dpp v70, v68 quad_perm:[1,0,3,2] row_mask:0xf bank_mask:0xf
	v_mov_b32_e32 v68, v97
	v_cndmask_b32_e32 v66, v66, v70, vcc
	v_cndmask_b32_e32 v64, v70, v64, vcc
	v_mov_b32_dpp v68, v69 quad_perm:[1,0,3,2] row_mask:0xf bank_mask:0xf
	v_cndmask_b32_e32 v67, v67, v68, vcc
	v_cndmask_b32_e32 v65, v68, v65, vcc
	global_store_dwordx4 v[102:103], v[64:67], off offset:48 sc1
	ds_read_b128 v[64:67], v150 offset:2048
	v_or_b32_e32 v70, s2, v159
	v_lshrrev_b32_e32 v68, 5, v70
	v_mul_u32_u24_e32 v96, 0x3000, v68
	s_waitcnt lgkmcnt(0)
	v_mov_b32_e32 v68, v65
	v_mov_b32_e32 v69, v66
	v_mov_b32_e32 v65, v67
	v_pk_add_f32 v[64:65], v[68:69], v[64:65]
	v_lshrrev_b32_e32 v67, 1, v70
	v_add_f32_e32 v64, v64, v65
	v_fmamk_f32 v64, v64, 0x3c000000, v196
	v_rsq_f32_e32 v64, v64
	v_lshlrev_b32_e32 v65, 1, v70
	v_and_b32_e32 v66, 8, v65
	v_pk_mul_f32 v[60:61], v[60:61], v[64:65] op_sel_hi:[1,0]
	v_pk_mul_f32 v[62:63], v[62:63], v[64:65] op_sel_hi:[1,0]
	v_pk_mul_f32 v[56:57], v[56:57], v[64:65] op_sel_hi:[1,0]
	v_pk_mul_f32 v[58:59], v[58:59], v[64:65] op_sel_hi:[1,0]
	v_pk_mul_f32 v[62:63], v[112:113], v[62:63]
	v_pk_mul_f32 v[60:61], v[110:111], v[60:61]
	v_pk_mul_f32 v[64:65], v[108:109], v[58:59]
	v_pk_mul_f32 v[58:59], v[106:107], v[56:57]
	v_cvt_pk_bf16_f32 v56, v60, v61
	v_cvt_pk_bf16_f32 v57, v62, v63
	s_nop 0
	v_cvt_pk_bf16_f32 v58, v58, v59
	v_cvt_pk_bf16_f32 v59, v64, v65
	ds_read_b128 v[60:63], v150 offset:2064
	v_and_b32_e32 v64, 4, v67
	v_or3_b32 v68, v66, v64, v162
	v_lshl_add_u64 v[64:65], s[6:7], 0, v[146:147]
	v_lshl_add_u64 v[64:65], v[64:65], 0, v[96:97]
	s_waitcnt lgkmcnt(0)
	v_mov_b32_e32 v66, v61
	v_mov_b32_e32 v67, v62
	v_mov_b32_e32 v61, v63
	v_pk_add_f32 v[60:61], v[66:67], v[60:61]
	v_lshlrev_b32_e32 v96, 4, v68
	v_add_f32_e32 v60, v60, v61
	v_fmamk_f32 v60, v60, 0x3c000000, v196
	v_rsq_f32_e32 v60, v60
	v_lshl_add_u64 v[62:63], v[64:65], 0, v[96:97]
	global_store_dwordx4 v[62:63], v[56:59], off sc1
	s_mul_hi_i32 s7, s3, 0x110000
	v_pk_mul_f32 v[52:53], v[52:53], v[60:61] op_sel_hi:[1,0]
	v_pk_mul_f32 v[54:55], v[54:55], v[60:61] op_sel_hi:[1,0]
	v_pk_mul_f32 v[48:49], v[48:49], v[60:61] op_sel_hi:[1,0]
	v_pk_mul_f32 v[50:51], v[50:51], v[60:61] op_sel_hi:[1,0]
	v_pk_mul_f32 v[54:55], v[112:113], v[54:55]
	v_pk_mul_f32 v[52:53], v[110:111], v[52:53]
	v_pk_mul_f32 v[56:57], v[108:109], v[50:51]
	v_pk_mul_f32 v[50:51], v[106:107], v[48:49]
	v_cvt_pk_bf16_f32 v48, v52, v53
	v_cvt_pk_bf16_f32 v49, v54, v55
	s_mul_i32 s3, s3, 0x110000
	v_cvt_pk_bf16_f32 v50, v50, v51
	v_cvt_pk_bf16_f32 v51, v56, v57
	ds_read_b128 v[52:55], v150 offset:2080
	global_store_dwordx4 v[62:63], v[48:51], off offset:16 sc1
	s_add_u32 s6, s50, s3
	s_addc_u32 s7, s51, s7
	s_waitcnt lgkmcnt(0)
	v_mov_b32_e32 v56, v53
	v_mov_b32_e32 v57, v54
	v_mov_b32_e32 v53, v55
	v_pk_add_f32 v[52:53], v[56:57], v[52:53]
	s_nop 0
	v_add_f32_e32 v52, v52, v53
	v_fmamk_f32 v52, v52, 0x3c000000, v196
	v_rsq_f32_e32 v52, v52
	s_nop 0
	v_pk_mul_f32 v[44:45], v[44:45], v[52:53] op_sel_hi:[1,0]
	v_pk_mul_f32 v[46:47], v[46:47], v[52:53] op_sel_hi:[1,0]
	v_pk_mul_f32 v[40:41], v[40:41], v[52:53] op_sel_hi:[1,0]
	v_pk_mul_f32 v[42:43], v[42:43], v[52:53] op_sel_hi:[1,0]
	v_pk_mul_f32 v[46:47], v[112:113], v[46:47]
	v_pk_mul_f32 v[44:45], v[110:111], v[44:45]
	v_pk_mul_f32 v[48:49], v[108:109], v[42:43]
	v_pk_mul_f32 v[42:43], v[106:107], v[40:41]
	v_cvt_pk_bf16_f32 v40, v44, v45
	v_cvt_pk_bf16_f32 v41, v46, v47
	s_nop 0
	v_cvt_pk_bf16_f32 v42, v42, v43
	v_cvt_pk_bf16_f32 v43, v48, v49
	ds_read_b128 v[44:47], v150 offset:2096
	global_store_dwordx4 v[62:63], v[40:43], off offset:32 sc1
	s_waitcnt lgkmcnt(0)
	v_mov_b32_e32 v48, v45
	v_mov_b32_e32 v49, v46
	v_mov_b32_e32 v45, v47
	v_pk_add_f32 v[44:45], v[48:49], v[44:45]
	s_nop 0
	v_add_f32_e32 v44, v44, v45
	v_fmamk_f32 v44, v44, 0x3c000000, v196
	v_rsq_f32_e32 v44, v44
	s_nop 0
	v_pk_mul_f32 v[36:37], v[36:37], v[44:45] op_sel_hi:[1,0]
	v_pk_mul_f32 v[32:33], v[32:33], v[44:45] op_sel_hi:[1,0]
	v_pk_mul_f32 v[34:35], v[34:35], v[44:45] op_sel_hi:[1,0]
	v_pk_mul_f32 v[38:39], v[38:39], v[44:45] op_sel_hi:[1,0]
	v_pk_mul_f32 v[36:37], v[110:111], v[36:37]
	v_pk_mul_f32 v[40:41], v[108:109], v[34:35]
	v_pk_mul_f32 v[34:35], v[106:107], v[32:33]
	v_cvt_pk_bf16_f32 v32, v36, v37
	v_pk_mul_f32 v[38:39], v[112:113], v[38:39]
	s_nop 0
	v_cvt_pk_bf16_f32 v33, v38, v39
	v_cvt_pk_bf16_f32 v34, v34, v35
	v_cvt_pk_bf16_f32 v35, v40, v41
	global_store_dwordx4 v[62:63], v[32:35], off offset:48 sc1
	v_cvt_pk_bf16_f32 v4, v4, v16
	v_cvt_pk_bf16_f32 v16, v20, v28
	v_cvt_pk_bf16_f32 v0, v0, v8
	v_cvt_pk_bf16_f32 v8, v12, v24
	v_mov_b32_e32 v24, v97
	s_nop 0
	v_or_b32_e32 v32, s2, v124
	v_lshlrev_b32_e32 v33, 8, v32
	v_and_b32_e32 v96, 0x1fe000, v33
	v_lshrrev_b32_e32 v33, 2, v32
	v_and_b32_e32 v33, 4, v33
	v_lshlrev_b32_e32 v32, 2, v32
	v_add_lshl_u32 v33, v33, v125, 6
	v_and_b32_e32 v32, 32, v32
	v_or3_b32 v38, v33, v32, v127
	v_cndmask_b32_e32 v12, v4, v0, vcc
	v_cndmask_b32_e32 v20, v16, v8, vcc
	v_lshlrev_b32_e32 v38, 4, v38
	v_mov_b32_dpp v24, v12 quad_perm:[1,0,3,2] row_mask:0xf bank_mask:0xf
	v_mov_b32_e32 v12, v97
	v_lshl_add_u64 v[36:37], s[6:7], 0, v[96:97]
	v_ashrrev_i32_e32 v39, 31, v38
	v_mov_b32_dpp v12, v20 quad_perm:[1,0,3,2] row_mask:0xf bank_mask:0xf
	v_cndmask_b32_e32 v34, v0, v24, vcc
	v_cndmask_b32_e32 v32, v24, v4, vcc
	v_cndmask_b32_e32 v35, v8, v12, vcc
	v_cndmask_b32_e32 v33, v12, v16, vcc
	v_lshl_add_u64 v[36:37], v[36:37], 0, v[38:39]
	global_store_dwordx4 v[36:37], v[32:35], off sc1
	v_cvt_pk_bf16_f32 v0, v5, v17
	v_cvt_pk_bf16_f32 v4, v21, v29
	v_cvt_pk_bf16_f32 v1, v1, v9
	v_mov_b32_e32 v12, v97
	v_cndmask_b32_e32 v8, v0, v1, vcc
	v_cvt_pk_bf16_f32 v5, v13, v25
	s_nop 0
	v_cndmask_b32_e32 v9, v4, v5, vcc
	v_mov_b32_dpp v12, v8 quad_perm:[1,0,3,2] row_mask:0xf bank_mask:0xf
	v_mov_b32_e32 v8, v97
	v_cndmask_b32_e32 v34, v1, v12, vcc
	v_cndmask_b32_e32 v32, v12, v0, vcc
	v_mov_b32_dpp v8, v9 quad_perm:[1,0,3,2] row_mask:0xf bank_mask:0xf
	v_cndmask_b32_e32 v35, v5, v8, vcc
	v_cndmask_b32_e32 v33, v8, v4, vcc
	global_store_dwordx4 v[36:37], v[32:35], off offset:16 sc1
	v_cvt_pk_bf16_f32 v0, v6, v18
	v_cvt_pk_bf16_f32 v1, v22, v30
	v_cvt_pk_bf16_f32 v2, v2, v10
	v_mov_b32_e32 v8, v97
	v_cndmask_b32_e32 v5, v0, v2, vcc
	v_cvt_pk_bf16_f32 v4, v14, v26
	s_nop 0
	v_cndmask_b32_e32 v6, v1, v4, vcc
	v_mov_b32_dpp v8, v5 quad_perm:[1,0,3,2] row_mask:0xf bank_mask:0xf
	v_mov_b32_e32 v5, v97
	v_cndmask_b32_e32 v34, v2, v8, vcc
	v_cndmask_b32_e32 v32, v8, v0, vcc
	v_mov_b32_dpp v5, v6 quad_perm:[1,0,3,2] row_mask:0xf bank_mask:0xf
	v_cndmask_b32_e32 v35, v4, v5, vcc
	v_cndmask_b32_e32 v33, v5, v1, vcc
	global_store_dwordx4 v[36:37], v[32:35], off offset:32 sc1
	v_cvt_pk_bf16_f32 v0, v7, v19
	v_cvt_pk_bf16_f32 v1, v23, v31
	v_cvt_pk_bf16_f32 v2, v3, v11
	v_mov_b32_e32 v6, v97
	v_cndmask_b32_e32 v4, v0, v2, vcc
	v_cvt_pk_bf16_f32 v3, v15, v27
	s_nop 0
	v_cndmask_b32_e32 v5, v1, v3, vcc
	v_mov_b32_dpp v6, v4 quad_perm:[1,0,3,2] row_mask:0xf bank_mask:0xf
	v_mov_b32_e32 v4, v97
	v_cndmask_b32_e32 v2, v2, v6, vcc
	v_cndmask_b32_e32 v0, v6, v0, vcc
	v_mov_b32_dpp v4, v5 quad_perm:[1,0,3,2] row_mask:0xf bank_mask:0xf
	v_cndmask_b32_e32 v3, v3, v4, vcc
	v_cndmask_b32_e32 v1, v4, v1, vcc
	s_andn2_b64 vcc, exec, s[0:1]
	s_mov_b64 s[0:1], -1
	global_store_dwordx4 v[36:37], v[0:3], off offset:48 sc1
	s_cbranch_vccnz .LBB0_677
	s_andn2_b64 vcc, exec, s[10:11]
	s_cbranch_vccnz .LBB0_676
	s_barrier
	s_branch .LBB0_676

.LBB0_720:
	v_lshl_add_u32 v146, s24, 8, v142
	v_lshl_or_b32 v140, s50, 8, v144
	v_ashrrev_i32_e32 v147, 31, v146
	v_ashrrev_i32_e32 v141, 31, v140
	v_lshlrev_b64 v[148:149], 12, v[146:147]
	v_lshl_add_u64 v[148:149], s[8:9], 0, v[148:149]
	v_lshlrev_b64 v[150:151], 1, v[140:141]
	v_lshl_add_u64 v[140:141], v[148:149], 0, v[150:151]
	v_cvt_pk_bf16_f32 v126, v126, v127
	v_cvt_pk_bf16_f32 v127, v128, v129
	v_cvt_pk_bf16_f32 v128, v122, v123
	v_cvt_pk_bf16_f32 v129, v124, v125
	global_store_dwordx4 v[140:141], v[126:129], off offset:1024 sc1
	v_cvt_pk_bf16_f32 v114, v114, v115
	v_cvt_pk_bf16_f32 v115, v116, v117
	v_cvt_pk_bf16_f32 v116, v106, v107
	v_or_b32_e32 v106, 16, v146
	v_ashrrev_i32_e32 v107, 31, v106
	v_lshlrev_b64 v[106:107], 12, v[106:107]
	v_lshl_add_u64 v[106:107], s[8:9], 0, v[106:107]
	v_cvt_pk_bf16_f32 v117, v108, v109
	global_store_dwordx4 v[140:141], v[114:117], off offset:1280 sc1
	s_mov_b64 s[2:3], 0x80000
	s_andn2_b64 vcc, exec, s[12:13]
	v_lshl_add_u64 v[114:115], v[106:107], 0, v[150:151]
	v_cvt_pk_bf16_f32 v106, v118, v119
	v_cvt_pk_bf16_f32 v107, v120, v121
	v_cvt_pk_bf16_f32 v108, v110, v111
	v_cvt_pk_bf16_f32 v109, v112, v113
	global_store_dwordx4 v[114:115], v[106:109], off offset:1024 sc1
	v_cvt_pk_bf16_f32 v98, v98, v99
	v_cvt_pk_bf16_f32 v99, v100, v101
	v_cvt_pk_bf16_f32 v100, v88, v89
	v_or_b32_e32 v88, 32, v146
	v_ashrrev_i32_e32 v89, 31, v88
	v_lshlrev_b64 v[88:89], 12, v[88:89]
	v_lshl_add_u64 v[88:89], s[8:9], 0, v[88:89]
	v_cvt_pk_bf16_f32 v101, v90, v91
	global_store_dwordx4 v[114:115], v[98:101], off offset:1280 sc1
	s_mov_b64 s[12:13], -1
	s_nop 0
	v_lshl_add_u64 v[98:99], v[88:89], 0, v[150:151]
	v_cvt_pk_bf16_f32 v88, v102, v103
	v_cvt_pk_bf16_f32 v89, v104, v105
	v_cvt_pk_bf16_f32 v90, v92, v93
	v_cvt_pk_bf16_f32 v91, v94, v95
	global_store_dwordx4 v[98:99], v[88:91], off offset:1024 sc1
	v_cvt_pk_bf16_f32 v80, v80, v81
	v_cvt_pk_bf16_f32 v81, v82, v83
	v_cvt_pk_bf16_f32 v82, v72, v73
	v_or_b32_e32 v72, 48, v146
	v_ashrrev_i32_e32 v73, 31, v72
	v_lshlrev_b64 v[72:73], 12, v[72:73]
	v_lshl_add_u64 v[72:73], s[8:9], 0, v[72:73]
	v_cvt_pk_bf16_f32 v83, v74, v75
	global_store_dwordx4 v[98:99], v[80:83], off offset:1280 sc1
	s_nop 1
	v_lshl_add_u64 v[80:81], v[72:73], 0, v[150:151]
	v_cvt_pk_bf16_f32 v72, v84, v85
	v_cvt_pk_bf16_f32 v73, v86, v87
	v_cvt_pk_bf16_f32 v74, v76, v77
	v_cvt_pk_bf16_f32 v75, v78, v79
	global_store_dwordx4 v[80:81], v[72:75], off offset:1024 sc1
	v_cvt_pk_bf16_f32 v68, v68, v69
	v_cvt_pk_bf16_f32 v69, v70, v71
	v_cvt_pk_bf16_f32 v70, v64, v65
	v_lshl_add_u64 v[64:65], v[140:141], 0, s[2:3]
	v_cvt_pk_bf16_f32 v71, v66, v67
	global_store_dwordx4 v[80:81], v[68:71], off offset:1280 sc1
	v_cvt_pk_bf16_f32 v60, v60, v61
	v_cvt_pk_bf16_f32 v61, v62, v63
	v_cvt_pk_bf16_f32 v62, v56, v57
	v_cvt_pk_bf16_f32 v63, v58, v59
	global_store_dwordx4 v[64:65], v[60:63], off offset:1024 sc1
	v_cvt_pk_bf16_f32 v48, v48, v49
	v_cvt_pk_bf16_f32 v49, v50, v51
	s_mov_b64 s[2:3], 0x90000
	v_cvt_pk_bf16_f32 v50, v40, v41
	v_cvt_pk_bf16_f32 v51, v42, v43
	global_store_dwordx4 v[64:65], v[48:51], off offset:1280 sc1
	v_cvt_pk_bf16_f32 v40, v52, v53
	v_cvt_pk_bf16_f32 v41, v54, v55
	v_cvt_pk_bf16_f32 v42, v44, v45
	v_cvt_pk_bf16_f32 v43, v46, v47
	s_nop 1
	v_lshl_add_u64 v[48:49], v[140:141], 0, s[2:3]
	global_store_dwordx4 v[48:49], v[40:43], off offset:1024 sc1
	v_cvt_pk_bf16_f32 v32, v32, v33
	v_cvt_pk_bf16_f32 v33, v34, v35
	s_mov_b64 s[2:3], 0xa0000
	v_cvt_pk_bf16_f32 v34, v24, v25
	v_cvt_pk_bf16_f32 v35, v26, v27
	global_store_dwordx4 v[48:49], v[32:35], off offset:1280 sc1
	v_cvt_pk_bf16_f32 v24, v36, v37
	v_cvt_pk_bf16_f32 v25, v38, v39
	v_cvt_pk_bf16_f32 v26, v28, v29
	v_cvt_pk_bf16_f32 v27, v30, v31
	s_nop 1
	v_lshl_add_u64 v[32:33], v[140:141], 0, s[2:3]
	global_store_dwordx4 v[32:33], v[24:27], off offset:1024 sc1
	v_cvt_pk_bf16_f32 v16, v16, v17
	v_cvt_pk_bf16_f32 v17, v18, v19
	s_mov_b64 s[2:3], 0xb0000
	v_cvt_pk_bf16_f32 v18, v8, v9
	v_cvt_pk_bf16_f32 v19, v10, v11
	global_store_dwordx4 v[32:33], v[16:19], off offset:1280 sc1
	v_cvt_pk_bf16_f32 v8, v20, v21
	v_cvt_pk_bf16_f32 v9, v22, v23
	v_cvt_pk_bf16_f32 v10, v12, v13
	v_cvt_pk_bf16_f32 v11, v14, v15
	s_nop 1
	v_lshl_add_u64 v[16:17], v[140:141], 0, s[2:3]
	global_store_dwordx4 v[16:17], v[8:11], off offset:1024 sc1
	v_cvt_pk_bf16_f32 v4, v4, v5
	v_cvt_pk_bf16_f32 v5, v6, v7
	v_cvt_pk_bf16_f32 v6, v0, v1
	v_cvt_pk_bf16_f32 v7, v2, v3
	global_store_dwordx4 v[16:17], v[4:7], off offset:1280 sc1
	s_cbranch_vccnz .LBB0_709
	s_andn2_b64 vcc, exec, s[0:1]
	s_cbranch_vccnz .LBB0_708
	s_barrier
	s_branch .LBB0_708

.LBB0_800:
	v_add_co_u32_e32 v64, vcc, 0x4000, v134
	s_waitcnt vmcnt(0)
	s_waitcnt vmcnt(0)
	s_nop 0
	v_addc_co_u32_e32 v65, vcc, 0, v135, vcc
	s_barrier
	flat_load_dwordx4 v[138:141], v[64:65]
	flat_load_dwordx4 v[130:133], v[134:135]
	flat_load_dwordx4 v[126:129], v[134:135] offset:1024
	flat_load_dwordx4 v[122:125], v[134:135] offset:2048
	flat_load_dwordx4 v[118:121], v[134:135] offset:3072
	v_max_f32_e32 v65, v80, v80
	s_movk_i32 s2, 0x2000
	s_mov_b64 s[8:9], 0
	s_waitcnt vmcnt(0) lgkmcnt(0)
	v_max_f32_e32 v64, v138, v138
	v_max_f32_e32 v64, v65, v64
	v_sub_f32_e32 v65, v80, v64
	v_sub_f32_e32 v64, v138, v64
	v_exp_f32_e32 v137, v64
	v_add_co_u32_e32 v64, vcc, s86, v134
	v_exp_f32_e32 v136, v65
	s_nop 0
	v_addc_co_u32_e32 v65, vcc, 0, v135, vcc
	flat_load_dwordx4 v[114:117], v[64:65]
	flat_load_dwordx4 v[110:113], v[64:65] offset:1024
	flat_load_dwordx4 v[106:109], v[64:65] offset:2048
	flat_load_dwordx4 v[102:105], v[64:65] offset:3072
	v_add_co_u32_e32 v64, vcc, s2, v134
	v_mov_b32_e32 v138, v81
	s_lshl_b32 s2, s4, 10
	v_addc_co_u32_e32 v65, vcc, 0, v135, vcc
	v_pk_mul_f32 v[138:139], v[138:139], v[136:137]
	s_and_b32 s2, s2, 0x1000
	flat_load_dwordx4 v[98:101], v[64:65]
	flat_load_dwordx4 v[90:93], v[64:65] offset:1024
	flat_load_dwordx4 v[86:89], v[64:65] offset:2048
	flat_load_dwordx4 v[82:85], v[64:65] offset:3072
	v_add_f32_e32 v96, v138, v139
	v_add_u32_e32 v138, s2, v158
	v_ashrrev_i32_e32 v139, 31, v138
	v_lshlrev_b64 v[138:139], 12, v[138:139]
	s_lshl_b32 s2, s4, 8
	v_lshl_add_u64 v[138:139], s[36:37], 0, v[138:139]
	s_and_b32 s40, s2, 0x300
	v_lshl_add_u64 v[140:141], v[138:139], 0, s[40:41]
	v_div_scale_f32 v138, s[2:3], v96, v96, 1.0
	v_rcp_f32_e32 v139, v138
	v_add_co_u32_e32 v64, vcc, s87, v134
	v_fma_f32 v142, -v138, v139, 1.0
	s_nop 0
	v_addc_co_u32_e32 v65, vcc, 0, v135, vcc
	v_fmac_f32_e32 v139, v142, v139
	v_div_scale_f32 v142, vcc, 1.0, v96, 1.0
	v_mul_f32_e32 v143, v142, v139
	v_fma_f32 v144, -v138, v143, v142
	v_fmac_f32_e32 v143, v144, v139
	v_fma_f32 v138, -v138, v143, v142
	v_div_fmas_f32 v138, v138, v139, v143
	v_div_fixup_f32 v96, v138, v96, 1.0
	v_pk_mul_f32 v[142:143], v[48:49], v[136:137] op_sel_hi:[1,0]
	v_mov_b32_e32 v138, v137
	v_pk_fma_f32 v[130:131], v[130:131], v[138:139], v[142:143] op_sel_hi:[1,0,1]
	flat_load_dwordx4 v[76:79], v[64:65]
	flat_load_dwordx4 v[72:75], v[64:65] offset:1024
	flat_load_dwordx4 v[68:71], v[64:65] offset:2048
	s_nop 0
	flat_load_dwordx4 v[64:67], v[64:65] offset:3072
	v_pk_mul_f32 v[130:131], v[130:131], v[96:97] op_sel_hi:[1,0]
	s_nop 0
	v_and_b32_sdwa v137, v131, v197 dst_sel:DWORD dst_unused:UNUSED_PAD src0_sel:WORD_1 src1_sel:DWORD
	v_and_b32_sdwa v139, v130, v197 dst_sel:DWORD dst_unused:UNUSED_PAD src0_sel:WORD_1 src1_sel:DWORD
	v_pk_mul_f32 v[142:143], v[50:51], v[136:137] op_sel_hi:[1,0]
	v_add3_u32 v130, v130, v139, s78
	v_pk_fma_f32 v[132:133], v[132:133], v[138:139], v[142:143] op_sel_hi:[1,0,1]
	v_add3_u32 v131, v131, v137, s78
	v_pk_mul_f32 v[132:133], v[132:133], v[96:97] op_sel_hi:[1,0]
	v_lshrrev_b32_e32 v130, 16, v130
	v_and_b32_sdwa v137, v132, v197 dst_sel:DWORD dst_unused:UNUSED_PAD src0_sel:WORD_1 src1_sel:DWORD
	v_and_or_b32 v130, v131, s79, v130
	v_and_b32_sdwa v131, v133, v197 dst_sel:DWORD dst_unused:UNUSED_PAD src0_sel:WORD_1 src1_sel:DWORD
	v_add3_u32 v132, v132, v137, s78
	v_add3_u32 v131, v133, v131, s78
	v_lshrrev_b32_e32 v132, 16, v132
	v_and_or_b32 v131, v131, s79, v132
	v_pk_mul_f32 v[132:133], v[52:53], v[136:137] op_sel_hi:[1,0]
	v_pk_mul_f32 v[118:119], v[138:139], v[118:119] op_sel_hi:[0,1]
	v_pk_fma_f32 v[126:127], v[126:127], v[138:139], v[132:133] op_sel_hi:[1,0,1]
	v_pk_fma_f32 v[118:119], v[60:61], v[136:137], v[118:119] op_sel_hi:[1,0,1]
	v_pk_mul_f32 v[126:127], v[126:127], v[96:97] op_sel_hi:[1,0]
	v_pk_mul_f32 v[118:119], v[96:97], v[118:119] op_sel_hi:[0,1]
	v_and_b32_sdwa v133, v126, v197 dst_sel:DWORD dst_unused:UNUSED_PAD src0_sel:WORD_1 src1_sel:DWORD
	v_and_b32_sdwa v132, v127, v197 dst_sel:DWORD dst_unused:UNUSED_PAD src0_sel:WORD_1 src1_sel:DWORD
	v_add3_u32 v126, v126, v133, s78
	v_add3_u32 v127, v127, v132, s78
	v_lshrrev_b32_e32 v126, 16, v126
	v_and_or_b32 v132, v127, s79, v126
	v_pk_mul_f32 v[126:127], v[54:55], v[136:137] op_sel_hi:[1,0]
	s_nop 0
	v_permlane32_swap_b32_e32 v130, v132
	v_pk_fma_f32 v[126:127], v[128:129], v[138:139], v[126:127] op_sel_hi:[1,0,1]
	s_waitcnt vmcnt(0) lgkmcnt(0)
	v_pk_mul_f32 v[114:115], v[138:139], v[114:115] op_sel_hi:[0,1]
	v_pk_mul_f32 v[126:127], v[126:127], v[96:97] op_sel_hi:[1,0]
	v_pk_fma_f32 v[114:115], v[32:33], v[136:137], v[114:115] op_sel_hi:[1,0,1]
	v_and_b32_sdwa v128, v127, v197 dst_sel:DWORD dst_unused:UNUSED_PAD src0_sel:WORD_1 src1_sel:DWORD
	v_and_b32_sdwa v129, v126, v197 dst_sel:DWORD dst_unused:UNUSED_PAD src0_sel:WORD_1 src1_sel:DWORD
	v_add3_u32 v127, v127, v128, s78
	v_add3_u32 v126, v126, v129, s78
	v_pk_mul_f32 v[128:129], v[56:57], v[136:137] op_sel_hi:[1,0]
	v_pk_mul_f32 v[114:115], v[96:97], v[114:115] op_sel_hi:[0,1]
	v_pk_fma_f32 v[122:123], v[138:139], v[122:123], v[128:129] op_sel_hi:[0,1,1]
	v_pk_mul_f32 v[122:123], v[122:123], v[96:97] op_sel_hi:[1,0]
	v_pk_mul_f32 v[116:117], v[138:139], v[116:117] op_sel_hi:[0,1]
	v_and_b32_sdwa v128, v123, v197 dst_sel:DWORD dst_unused:UNUSED_PAD src0_sel:WORD_1 src1_sel:DWORD
	v_and_b32_sdwa v129, v122, v197 dst_sel:DWORD dst_unused:UNUSED_PAD src0_sel:WORD_1 src1_sel:DWORD
	v_add3_u32 v123, v123, v128, s78
	v_add3_u32 v122, v122, v129, s78
	v_pk_mul_f32 v[128:129], v[58:59], v[136:137] op_sel_hi:[1,0]
	v_lshrrev_b32_e32 v122, 16, v122
	v_pk_fma_f32 v[124:125], v[138:139], v[124:125], v[128:129] op_sel_hi:[0,1,1]
	v_pk_mul_f32 v[124:125], v[124:125], v[96:97] op_sel_hi:[1,0]
	v_and_or_b32 v122, v123, s79, v122
	v_and_b32_sdwa v128, v124, v197 dst_sel:DWORD dst_unused:UNUSED_PAD src0_sel:WORD_1 src1_sel:DWORD
	v_and_b32_sdwa v123, v125, v197 dst_sel:DWORD dst_unused:UNUSED_PAD src0_sel:WORD_1 src1_sel:DWORD
	v_add3_u32 v124, v124, v128, s78
	v_add3_u32 v123, v125, v123, s78
	v_lshrrev_b32_e32 v124, 16, v124
	v_and_b32_sdwa v125, v118, v197 dst_sel:DWORD dst_unused:UNUSED_PAD src0_sel:WORD_1 src1_sel:DWORD
	v_and_or_b32 v123, v123, s79, v124
	v_and_b32_sdwa v124, v119, v197 dst_sel:DWORD dst_unused:UNUSED_PAD src0_sel:WORD_1 src1_sel:DWORD
	v_add3_u32 v118, v118, v125, s78
	v_add3_u32 v119, v119, v124, s78
	v_lshrrev_b32_e32 v118, 16, v118
	v_and_or_b32 v124, v119, s79, v118
	v_pk_mul_f32 v[118:119], v[138:139], v[120:121] op_sel_hi:[0,1]
	v_pk_fma_f32 v[118:119], v[62:63], v[136:137], v[118:119] op_sel_hi:[1,0,1]
	v_pk_fma_f32 v[116:117], v[34:35], v[136:137], v[116:117] op_sel_hi:[1,0,1]
	v_pk_mul_f32 v[118:119], v[96:97], v[118:119] op_sel_hi:[0,1]
	v_and_b32_sdwa v121, v118, v197 dst_sel:DWORD dst_unused:UNUSED_PAD src0_sel:WORD_1 src1_sel:DWORD
	v_and_b32_sdwa v120, v119, v197 dst_sel:DWORD dst_unused:UNUSED_PAD src0_sel:WORD_1 src1_sel:DWORD
	v_add3_u32 v118, v118, v121, s78
	v_add3_u32 v119, v119, v120, s78
	v_lshrrev_b32_e32 v118, 16, v118
	v_and_or_b32 v125, v119, s79, v118
	v_and_b32_sdwa v119, v114, v197 dst_sel:DWORD dst_unused:UNUSED_PAD src0_sel:WORD_1 src1_sel:DWORD
	v_and_b32_sdwa v118, v115, v197 dst_sel:DWORD dst_unused:UNUSED_PAD src0_sel:WORD_1 src1_sel:DWORD
	v_add3_u32 v114, v114, v119, s78
	v_pk_mul_f32 v[116:117], v[96:97], v[116:117] op_sel_hi:[0,1]
	v_pk_mul_f32 v[110:111], v[138:139], v[110:111] op_sel_hi:[0,1]
	v_add3_u32 v115, v115, v118, s78
	v_lshrrev_b32_e32 v114, 16, v114
	v_and_b32_sdwa v118, v116, v197 dst_sel:DWORD dst_unused:UNUSED_PAD src0_sel:WORD_1 src1_sel:DWORD
	v_pk_fma_f32 v[110:111], v[36:37], v[136:137], v[110:111] op_sel_hi:[1,0,1]
	v_and_or_b32 v114, v115, s79, v114
	v_and_b32_sdwa v115, v117, v197 dst_sel:DWORD dst_unused:UNUSED_PAD src0_sel:WORD_1 src1_sel:DWORD
	v_add3_u32 v116, v116, v118, s78
	v_pk_mul_f32 v[110:111], v[96:97], v[110:111] op_sel_hi:[0,1]
	v_add3_u32 v115, v117, v115, s78
	v_lshrrev_b32_e32 v116, 16, v116
	v_and_b32_sdwa v117, v110, v197 dst_sel:DWORD dst_unused:UNUSED_PAD src0_sel:WORD_1 src1_sel:DWORD
	v_and_or_b32 v115, v115, s79, v116
	v_and_b32_sdwa v116, v111, v197 dst_sel:DWORD dst_unused:UNUSED_PAD src0_sel:WORD_1 src1_sel:DWORD
	v_add3_u32 v110, v110, v117, s78
	v_add3_u32 v111, v111, v116, s78
	v_lshrrev_b32_e32 v110, 16, v110
	v_and_or_b32 v116, v111, s79, v110
	v_pk_mul_f32 v[110:111], v[138:139], v[112:113] op_sel_hi:[0,1]
	v_pk_fma_f32 v[110:111], v[38:39], v[136:137], v[110:111] op_sel_hi:[1,0,1]
	v_pk_mul_f32 v[106:107], v[138:139], v[106:107] op_sel_hi:[0,1]
	v_pk_mul_f32 v[110:111], v[96:97], v[110:111] op_sel_hi:[0,1]
	v_and_b32_sdwa v113, v110, v197 dst_sel:DWORD dst_unused:UNUSED_PAD src0_sel:WORD_1 src1_sel:DWORD
	v_and_b32_sdwa v112, v111, v197 dst_sel:DWORD dst_unused:UNUSED_PAD src0_sel:WORD_1 src1_sel:DWORD
	v_add3_u32 v110, v110, v113, s78
	v_pk_fma_f32 v[106:107], v[40:41], v[136:137], v[106:107] op_sel_hi:[1,0,1]
	v_add3_u32 v111, v111, v112, s78
	v_lshrrev_b32_e32 v110, 16, v110
	v_pk_mul_f32 v[106:107], v[96:97], v[106:107] op_sel_hi:[0,1]
	v_pk_mul_f32 v[108:109], v[138:139], v[108:109] op_sel_hi:[0,1]
	v_and_or_b32 v117, v111, s79, v110
	v_and_b32_sdwa v111, v106, v197 dst_sel:DWORD dst_unused:UNUSED_PAD src0_sel:WORD_1 src1_sel:DWORD
	v_pk_fma_f32 v[108:109], v[42:43], v[136:137], v[108:109] op_sel_hi:[1,0,1]
	v_and_b32_sdwa v110, v107, v197 dst_sel:DWORD dst_unused:UNUSED_PAD src0_sel:WORD_1 src1_sel:DWORD
	v_add3_u32 v106, v106, v111, s78
	v_pk_mul_f32 v[108:109], v[96:97], v[108:109] op_sel_hi:[0,1]
	v_pk_mul_f32 v[102:103], v[138:139], v[102:103] op_sel_hi:[0,1]
	v_add3_u32 v107, v107, v110, s78
	v_lshrrev_b32_e32 v106, 16, v106
	v_and_b32_sdwa v110, v108, v197 dst_sel:DWORD dst_unused:UNUSED_PAD src0_sel:WORD_1 src1_sel:DWORD
	v_pk_fma_f32 v[102:103], v[44:45], v[136:137], v[102:103] op_sel_hi:[1,0,1]
	v_and_or_b32 v106, v107, s79, v106
	v_and_b32_sdwa v107, v109, v197 dst_sel:DWORD dst_unused:UNUSED_PAD src0_sel:WORD_1 src1_sel:DWORD
	v_add3_u32 v108, v108, v110, s78
	v_pk_mul_f32 v[102:103], v[96:97], v[102:103] op_sel_hi:[0,1]
	v_add3_u32 v107, v109, v107, s78
	v_lshrrev_b32_e32 v108, 16, v108
	v_and_b32_sdwa v109, v102, v197 dst_sel:DWORD dst_unused:UNUSED_PAD src0_sel:WORD_1 src1_sel:DWORD
	v_and_or_b32 v107, v107, s79, v108
	v_and_b32_sdwa v108, v103, v197 dst_sel:DWORD dst_unused:UNUSED_PAD src0_sel:WORD_1 src1_sel:DWORD
	v_add3_u32 v102, v102, v109, s78
	v_add3_u32 v103, v103, v108, s78
	v_lshrrev_b32_e32 v102, 16, v102
	v_and_or_b32 v108, v103, s79, v102
	v_pk_mul_f32 v[102:103], v[138:139], v[104:105] op_sel_hi:[0,1]
	v_pk_fma_f32 v[102:103], v[46:47], v[136:137], v[102:103] op_sel_hi:[1,0,1]
	v_pk_mul_f32 v[98:99], v[138:139], v[98:99] op_sel_hi:[0,1]
	v_pk_mul_f32 v[102:103], v[96:97], v[102:103] op_sel_hi:[0,1]
	v_and_b32_sdwa v105, v102, v197 dst_sel:DWORD dst_unused:UNUSED_PAD src0_sel:WORD_1 src1_sel:DWORD
	v_and_b32_sdwa v104, v103, v197 dst_sel:DWORD dst_unused:UNUSED_PAD src0_sel:WORD_1 src1_sel:DWORD
	v_add3_u32 v102, v102, v105, s78
	v_pk_fma_f32 v[98:99], v[16:17], v[136:137], v[98:99] op_sel_hi:[1,0,1]
	v_add3_u32 v103, v103, v104, s78
	v_lshrrev_b32_e32 v102, 16, v102
	v_pk_mul_f32 v[98:99], v[96:97], v[98:99] op_sel_hi:[0,1]
	v_pk_mul_f32 v[100:101], v[138:139], v[100:101] op_sel_hi:[0,1]
	v_and_or_b32 v109, v103, s79, v102
	v_and_b32_sdwa v103, v98, v197 dst_sel:DWORD dst_unused:UNUSED_PAD src0_sel:WORD_1 src1_sel:DWORD
	v_pk_fma_f32 v[100:101], v[18:19], v[136:137], v[100:101] op_sel_hi:[1,0,1]
	v_and_b32_sdwa v102, v99, v197 dst_sel:DWORD dst_unused:UNUSED_PAD src0_sel:WORD_1 src1_sel:DWORD
	v_add3_u32 v98, v98, v103, s78
	v_pk_mul_f32 v[100:101], v[96:97], v[100:101] op_sel_hi:[0,1]
	v_pk_mul_f32 v[90:91], v[138:139], v[90:91] op_sel_hi:[0,1]
	v_add3_u32 v99, v99, v102, s78
	v_lshrrev_b32_e32 v98, 16, v98
	v_and_b32_sdwa v102, v100, v197 dst_sel:DWORD dst_unused:UNUSED_PAD src0_sel:WORD_1 src1_sel:DWORD
	v_pk_fma_f32 v[90:91], v[20:21], v[136:137], v[90:91] op_sel_hi:[1,0,1]
	v_and_or_b32 v98, v99, s79, v98
	v_and_b32_sdwa v99, v101, v197 dst_sel:DWORD dst_unused:UNUSED_PAD src0_sel:WORD_1 src1_sel:DWORD
	v_add3_u32 v100, v100, v102, s78
	v_pk_mul_f32 v[90:91], v[96:97], v[90:91] op_sel_hi:[0,1]
	v_add3_u32 v99, v101, v99, s78
	v_lshrrev_b32_e32 v100, 16, v100
	v_and_b32_sdwa v101, v90, v197 dst_sel:DWORD dst_unused:UNUSED_PAD src0_sel:WORD_1 src1_sel:DWORD
	v_and_or_b32 v99, v99, s79, v100
	v_and_b32_sdwa v100, v91, v197 dst_sel:DWORD dst_unused:UNUSED_PAD src0_sel:WORD_1 src1_sel:DWORD
	v_add3_u32 v90, v90, v101, s78
	v_add3_u32 v91, v91, v100, s78
	v_lshrrev_b32_e32 v90, 16, v90
	v_and_or_b32 v100, v91, s79, v90
	v_pk_mul_f32 v[90:91], v[138:139], v[92:93] op_sel_hi:[0,1]
	v_pk_fma_f32 v[90:91], v[22:23], v[136:137], v[90:91] op_sel_hi:[1,0,1]
	v_pk_mul_f32 v[86:87], v[138:139], v[86:87] op_sel_hi:[0,1]
	v_pk_mul_f32 v[90:91], v[96:97], v[90:91] op_sel_hi:[0,1]
	v_and_b32_sdwa v93, v90, v197 dst_sel:DWORD dst_unused:UNUSED_PAD src0_sel:WORD_1 src1_sel:DWORD
	v_and_b32_sdwa v92, v91, v197 dst_sel:DWORD dst_unused:UNUSED_PAD src0_sel:WORD_1 src1_sel:DWORD
	v_add3_u32 v90, v90, v93, s78
	v_pk_fma_f32 v[86:87], v[24:25], v[136:137], v[86:87] op_sel_hi:[1,0,1]
	v_add3_u32 v91, v91, v92, s78
	v_lshrrev_b32_e32 v90, 16, v90
	v_pk_mul_f32 v[86:87], v[96:97], v[86:87] op_sel_hi:[0,1]
	v_pk_mul_f32 v[88:89], v[138:139], v[88:89] op_sel_hi:[0,1]
	v_and_or_b32 v101, v91, s79, v90
	v_and_b32_sdwa v91, v86, v197 dst_sel:DWORD dst_unused:UNUSED_PAD src0_sel:WORD_1 src1_sel:DWORD
	v_pk_fma_f32 v[88:89], v[26:27], v[136:137], v[88:89] op_sel_hi:[1,0,1]
	v_and_b32_sdwa v90, v87, v197 dst_sel:DWORD dst_unused:UNUSED_PAD src0_sel:WORD_1 src1_sel:DWORD
	v_add3_u32 v86, v86, v91, s78
	v_pk_mul_f32 v[88:89], v[96:97], v[88:89] op_sel_hi:[0,1]
	v_pk_mul_f32 v[82:83], v[138:139], v[82:83] op_sel_hi:[0,1]
	v_add3_u32 v87, v87, v90, s78
	v_lshrrev_b32_e32 v86, 16, v86
	v_and_b32_sdwa v90, v88, v197 dst_sel:DWORD dst_unused:UNUSED_PAD src0_sel:WORD_1 src1_sel:DWORD
	v_pk_fma_f32 v[82:83], v[28:29], v[136:137], v[82:83] op_sel_hi:[1,0,1]
	v_and_or_b32 v86, v87, s79, v86
	v_and_b32_sdwa v87, v89, v197 dst_sel:DWORD dst_unused:UNUSED_PAD src0_sel:WORD_1 src1_sel:DWORD
	v_add3_u32 v88, v88, v90, s78
	v_pk_mul_f32 v[82:83], v[96:97], v[82:83] op_sel_hi:[0,1]
	v_add3_u32 v87, v89, v87, s78
	v_lshrrev_b32_e32 v88, 16, v88
	v_and_b32_sdwa v89, v82, v197 dst_sel:DWORD dst_unused:UNUSED_PAD src0_sel:WORD_1 src1_sel:DWORD
	v_and_or_b32 v87, v87, s79, v88
	v_and_b32_sdwa v88, v83, v197 dst_sel:DWORD dst_unused:UNUSED_PAD src0_sel:WORD_1 src1_sel:DWORD
	v_add3_u32 v82, v82, v89, s78
	v_add3_u32 v83, v83, v88, s78
	v_lshrrev_b32_e32 v82, 16, v82
	v_and_or_b32 v88, v83, s79, v82
	v_pk_mul_f32 v[82:83], v[138:139], v[84:85] op_sel_hi:[0,1]
	v_pk_fma_f32 v[82:83], v[30:31], v[136:137], v[82:83] op_sel_hi:[1,0,1]
	v_pk_mul_f32 v[76:77], v[138:139], v[76:77] op_sel_hi:[0,1]
	v_pk_mul_f32 v[82:83], v[96:97], v[82:83] op_sel_hi:[0,1]
	v_and_b32_sdwa v85, v82, v197 dst_sel:DWORD dst_unused:UNUSED_PAD src0_sel:WORD_1 src1_sel:DWORD
	v_and_b32_sdwa v84, v83, v197 dst_sel:DWORD dst_unused:UNUSED_PAD src0_sel:WORD_1 src1_sel:DWORD
	v_add3_u32 v82, v82, v85, s78
	v_pk_fma_f32 v[76:77], v[0:1], v[136:137], v[76:77] op_sel_hi:[1,0,1]
	v_add3_u32 v83, v83, v84, s78
	v_lshrrev_b32_e32 v82, 16, v82
	v_pk_mul_f32 v[76:77], v[96:97], v[76:77] op_sel_hi:[0,1]
	v_pk_mul_f32 v[78:79], v[138:139], v[78:79] op_sel_hi:[0,1]
	v_and_or_b32 v89, v83, s79, v82
	v_and_b32_sdwa v83, v76, v197 dst_sel:DWORD dst_unused:UNUSED_PAD src0_sel:WORD_1 src1_sel:DWORD
	v_pk_fma_f32 v[78:79], v[2:3], v[136:137], v[78:79] op_sel_hi:[1,0,1]
	v_and_b32_sdwa v82, v77, v197 dst_sel:DWORD dst_unused:UNUSED_PAD src0_sel:WORD_1 src1_sel:DWORD
	v_add3_u32 v76, v76, v83, s78
	v_pk_mul_f32 v[78:79], v[96:97], v[78:79] op_sel_hi:[0,1]
	v_pk_mul_f32 v[72:73], v[138:139], v[72:73] op_sel_hi:[0,1]
	v_add3_u32 v77, v77, v82, s78
	v_lshrrev_b32_e32 v76, 16, v76
	v_and_b32_sdwa v82, v78, v197 dst_sel:DWORD dst_unused:UNUSED_PAD src0_sel:WORD_1 src1_sel:DWORD
	v_pk_fma_f32 v[72:73], v[4:5], v[136:137], v[72:73] op_sel_hi:[1,0,1]
	v_and_or_b32 v76, v77, s79, v76
	v_and_b32_sdwa v77, v79, v197 dst_sel:DWORD dst_unused:UNUSED_PAD src0_sel:WORD_1 src1_sel:DWORD
	v_add3_u32 v78, v78, v82, s78
	v_pk_mul_f32 v[72:73], v[96:97], v[72:73] op_sel_hi:[0,1]
	v_add3_u32 v77, v79, v77, s78
	v_lshrrev_b32_e32 v78, 16, v78
	v_and_b32_sdwa v79, v72, v197 dst_sel:DWORD dst_unused:UNUSED_PAD src0_sel:WORD_1 src1_sel:DWORD
	v_and_or_b32 v77, v77, s79, v78
	v_and_b32_sdwa v78, v73, v197 dst_sel:DWORD dst_unused:UNUSED_PAD src0_sel:WORD_1 src1_sel:DWORD
	v_add3_u32 v72, v72, v79, s78
	v_add3_u32 v73, v73, v78, s78
	v_lshrrev_b32_e32 v72, 16, v72
	v_and_or_b32 v78, v73, s79, v72
	v_pk_mul_f32 v[72:73], v[138:139], v[74:75] op_sel_hi:[0,1]
	v_pk_fma_f32 v[72:73], v[6:7], v[136:137], v[72:73] op_sel_hi:[1,0,1]
	v_pk_mul_f32 v[68:69], v[138:139], v[68:69] op_sel_hi:[0,1]
	v_pk_mul_f32 v[72:73], v[96:97], v[72:73] op_sel_hi:[0,1]
	v_and_b32_sdwa v75, v72, v197 dst_sel:DWORD dst_unused:UNUSED_PAD src0_sel:WORD_1 src1_sel:DWORD
	v_and_b32_sdwa v74, v73, v197 dst_sel:DWORD dst_unused:UNUSED_PAD src0_sel:WORD_1 src1_sel:DWORD
	v_add3_u32 v72, v72, v75, s78
	v_pk_fma_f32 v[68:69], v[8:9], v[136:137], v[68:69] op_sel_hi:[1,0,1]
	v_add3_u32 v73, v73, v74, s78
	v_lshrrev_b32_e32 v72, 16, v72
	v_pk_mul_f32 v[68:69], v[96:97], v[68:69] op_sel_hi:[0,1]
	v_pk_mul_f32 v[70:71], v[138:139], v[70:71] op_sel_hi:[0,1]
	v_and_or_b32 v79, v73, s79, v72
	v_and_b32_sdwa v73, v68, v197 dst_sel:DWORD dst_unused:UNUSED_PAD src0_sel:WORD_1 src1_sel:DWORD
	v_pk_fma_f32 v[70:71], v[10:11], v[136:137], v[70:71] op_sel_hi:[1,0,1]
	v_and_b32_sdwa v72, v69, v197 dst_sel:DWORD dst_unused:UNUSED_PAD src0_sel:WORD_1 src1_sel:DWORD
	v_add3_u32 v68, v68, v73, s78
	v_pk_mul_f32 v[70:71], v[96:97], v[70:71] op_sel_hi:[0,1]
	v_pk_mul_f32 v[64:65], v[138:139], v[64:65] op_sel_hi:[0,1]
	v_add3_u32 v69, v69, v72, s78
	v_lshrrev_b32_e32 v68, 16, v68
	v_and_b32_sdwa v72, v70, v197 dst_sel:DWORD dst_unused:UNUSED_PAD src0_sel:WORD_1 src1_sel:DWORD
	v_pk_fma_f32 v[64:65], v[12:13], v[136:137], v[64:65] op_sel_hi:[1,0,1]
	v_and_or_b32 v68, v69, s79, v68
	v_and_b32_sdwa v69, v71, v197 dst_sel:DWORD dst_unused:UNUSED_PAD src0_sel:WORD_1 src1_sel:DWORD
	v_add3_u32 v70, v70, v72, s78
	v_pk_mul_f32 v[64:65], v[96:97], v[64:65] op_sel_hi:[0,1]
	v_add3_u32 v69, v71, v69, s78
	v_lshrrev_b32_e32 v70, 16, v70
	v_and_b32_sdwa v71, v64, v197 dst_sel:DWORD dst_unused:UNUSED_PAD src0_sel:WORD_1 src1_sel:DWORD
	v_and_or_b32 v69, v69, s79, v70
	v_and_b32_sdwa v70, v65, v197 dst_sel:DWORD dst_unused:UNUSED_PAD src0_sel:WORD_1 src1_sel:DWORD
	v_add3_u32 v64, v64, v71, s78
	v_add3_u32 v65, v65, v70, s78
	v_lshrrev_b32_e32 v64, 16, v64
	v_and_or_b32 v70, v65, s79, v64
	v_pk_mul_f32 v[64:65], v[138:139], v[66:67] op_sel_hi:[0,1]
	v_pk_fma_f32 v[64:65], v[14:15], v[136:137], v[64:65] op_sel_hi:[1,0,1]
	v_lshrrev_b32_e32 v126, 16, v126
	v_pk_mul_f32 v[64:65], v[96:97], v[64:65] op_sel_hi:[0,1]
	v_and_b32_sdwa v67, v64, v197 dst_sel:DWORD dst_unused:UNUSED_PAD src0_sel:WORD_1 src1_sel:DWORD
	v_and_b32_sdwa v66, v65, v197 dst_sel:DWORD dst_unused:UNUSED_PAD src0_sel:WORD_1 src1_sel:DWORD
	v_add3_u32 v64, v64, v67, s78
	v_add3_u32 v65, v65, v66, s78
	v_lshrrev_b32_e32 v64, 16, v64
	v_and_or_b32 v133, v127, s79, v126
	v_and_or_b32 v71, v65, s79, v64
	s_nop 0
	v_permlane32_swap_b32_e32 v131, v133
	v_lshl_add_u64 v[126:127], v[184:185], 1, v[140:141]
	v_permlane32_swap_b32_e32 v122, v124
	v_permlane32_swap_b32_e32 v123, v125
	v_permlane32_swap_b32_e32 v114, v116
	v_permlane32_swap_b32_e32 v115, v117
	v_permlane32_swap_b32_e32 v106, v108
	v_permlane32_swap_b32_e32 v107, v109
	v_permlane32_swap_b32_e32 v98, v100
	v_permlane32_swap_b32_e32 v99, v101
	v_permlane32_swap_b32_e32 v86, v88
	v_permlane32_swap_b32_e32 v87, v89
	v_permlane32_swap_b32_e32 v76, v78
	v_permlane32_swap_b32_e32 v77, v79
	v_permlane32_swap_b32_e32 v68, v70
	v_permlane32_swap_b32_e32 v69, v71
	global_store_dwordx4 v[126:127], v[130:133], off sc1
	global_store_dwordx4 v[126:127], v[122:125], off offset:32 sc1
	global_store_dwordx4 v[126:127], v[114:117], off offset:64 sc1
	global_store_dwordx4 v[126:127], v[106:109], off offset:96 sc1
	global_store_dwordx4 v[126:127], v[98:101], off offset:128 sc1
	global_store_dwordx4 v[126:127], v[86:89], off offset:160 sc1
	global_store_dwordx4 v[126:127], v[76:79], off offset:192 sc1
	global_store_dwordx4 v[126:127], v[68:71], off offset:224 sc1
.LBB0_801:
	s_and_b64 vcc, exec, s[8:9]
	s_cbranch_vccz .LBB0_782
	flat_store_dwordx4 v[134:135], v[48:51] sc1
	flat_store_dwordx4 v[134:135], v[52:55] offset:1024 sc1
	flat_store_dwordx4 v[134:135], v[56:59] offset:2048 sc1
	flat_store_dwordx4 v[134:135], v[60:63] offset:3072 sc1
	v_add_co_u32_e32 v48, vcc, 0x1000, v134
	s_movk_i32 s2, 0x2000
	s_nop 0
	v_addc_co_u32_e32 v49, vcc, 0, v135, vcc
	flat_store_dwordx4 v[48:49], v[32:35] sc1
	flat_store_dwordx4 v[48:49], v[36:39] offset:1024 sc1
	flat_store_dwordx4 v[48:49], v[40:43] offset:2048 sc1
	flat_store_dwordx4 v[48:49], v[44:47] offset:3072 sc1
	v_add_co_u32_e32 v32, vcc, s2, v134
	v_mov_b32_e32 v82, v97
	s_nop 0
	v_addc_co_u32_e32 v33, vcc, 0, v135, vcc
	flat_store_dwordx4 v[32:33], v[16:19] sc1
	flat_store_dwordx4 v[32:33], v[20:23] offset:1024 sc1
	flat_store_dwordx4 v[32:33], v[24:27] offset:2048 sc1
	flat_store_dwordx4 v[32:33], v[28:31] offset:3072 sc1
	v_add_co_u32_e32 v16, vcc, s87, v134
	v_mov_b32_e32 v83, v97
	s_nop 0
	v_addc_co_u32_e32 v17, vcc, 0, v135, vcc
	flat_store_dwordx4 v[16:17], v[0:3] sc1
	flat_store_dwordx4 v[16:17], v[4:7] offset:1024 sc1
	flat_store_dwordx4 v[16:17], v[8:11] offset:2048 sc1
	flat_store_dwordx4 v[16:17], v[12:15] offset:3072 sc1
	v_add_co_u32_e32 v0, vcc, 0x4000, v134
	s_nop 1
	v_addc_co_u32_e32 v1, vcc, 0, v135, vcc
	flat_store_dwordx4 v[0:1], v[80:83] sc1
	s_waitcnt vmcnt(0)
	s_waitcnt vmcnt(0) lgkmcnt(0)
	s_barrier
	s_and_saveexec_b64 s[8:9], s[0:1]
	s_cbranch_execz .LBB0_781
	s_mov_b64 s[10:11], exec
	v_mbcnt_lo_u32_b32 v0, s10, 0
	buffer_wbl2 sc1
	s_waitcnt vmcnt(0)
	v_mbcnt_hi_u32_b32 v0, s11, v0
	v_cmp_eq_u32_e32 vcc, 0, v0
	s_and_b64 s[2:3], exec, vcc
	s_mov_b64 exec, s[2:3]
	s_cbranch_execz .LBB0_781
	s_lshl_b32 s40, s4, 4
	s_lshl_b64 s[2:3], s[40:41], 2
	v_readlane_b32 s5, v252, 21
	s_add_u32 s2, s5, s2
	v_readlane_b32 s5, v252, 22
	s_addc_u32 s3, s5, s3
	s_bcnt1_i32_b64 s5, s[10:11]
	v_mov_b32_e32 v0, s5
	global_atomic_add v97, v0, s[2:3]
	s_branch .LBB0_781

.LBB0_808:
	v_div_scale_f32 v0, s[0:1], v218, v218, 1.0
	v_rcp_f32_e32 v1, v0
	v_lshl_add_u64 v[4:5], s[40:41], 1, v[158:159]
	v_lshl_add_u64 v[4:5], v[184:185], 1, v[4:5]
	v_fma_f32 v2, -v0, v1, 1.0
	v_fmac_f32_e32 v1, v2, v1
	v_div_scale_f32 v2, vcc, 1.0, v218, 1.0
	v_mul_f32_e32 v3, v2, v1
	v_fma_f32 v6, -v0, v3, v2
	v_fmac_f32_e32 v3, v6, v1
	v_fma_f32 v0, -v0, v3, v2
	v_div_fmas_f32 v0, v0, v1, v3
	v_div_fixup_f32 v6, v0, v218, 1.0
	v_pk_mul_f32 v[0:1], v[6:7], v[32:33] op_sel_hi:[0,1]
	v_and_b32_sdwa v2, v1, v197 dst_sel:DWORD dst_unused:UNUSED_PAD src0_sel:WORD_1 src1_sel:DWORD
	v_and_b32_sdwa v3, v0, v197 dst_sel:DWORD dst_unused:UNUSED_PAD src0_sel:WORD_1 src1_sel:DWORD
	v_add3_u32 v1, v1, v2, s78
	v_add3_u32 v0, v0, v3, s78
	v_pk_mul_f32 v[2:3], v[6:7], v[34:35] op_sel_hi:[0,1]
	v_lshrrev_b32_e32 v0, 16, v0
	v_and_b32_sdwa v7, v2, v197 dst_sel:DWORD dst_unused:UNUSED_PAD src0_sel:WORD_1 src1_sel:DWORD
	v_and_or_b32 v0, v1, s79, v0
	v_and_b32_sdwa v1, v3, v197 dst_sel:DWORD dst_unused:UNUSED_PAD src0_sel:WORD_1 src1_sel:DWORD
	v_add3_u32 v2, v2, v7, s78
	v_add3_u32 v1, v3, v1, s78
	v_lshrrev_b32_e32 v2, 16, v2
	v_and_or_b32 v1, v1, s79, v2
	v_pk_mul_f32 v[2:3], v[6:7], v[36:37] op_sel_hi:[0,1]
	v_and_b32_sdwa v7, v3, v197 dst_sel:DWORD dst_unused:UNUSED_PAD src0_sel:WORD_1 src1_sel:DWORD
	v_and_b32_sdwa v8, v2, v197 dst_sel:DWORD dst_unused:UNUSED_PAD src0_sel:WORD_1 src1_sel:DWORD
	v_add3_u32 v2, v2, v8, s78
	v_pk_mul_f32 v[8:9], v[6:7], v[38:39] op_sel_hi:[0,1]
	v_add3_u32 v3, v3, v7, s78
	v_lshrrev_b32_e32 v2, 16, v2
	v_and_b32_sdwa v7, v8, v197 dst_sel:DWORD dst_unused:UNUSED_PAD src0_sel:WORD_1 src1_sel:DWORD
	v_and_or_b32 v2, v3, s79, v2
	v_and_b32_sdwa v3, v9, v197 dst_sel:DWORD dst_unused:UNUSED_PAD src0_sel:WORD_1 src1_sel:DWORD
	v_add3_u32 v7, v8, v7, s78
	v_add3_u32 v3, v9, v3, s78
	v_lshrrev_b32_e32 v7, 16, v7
	v_and_or_b32 v3, v3, s79, v7
	v_permlane32_swap_b32_e32 v0, v2
	s_nop 0
	v_permlane32_swap_b32_e32 v1, v3
	global_store_dwordx4 v[4:5], v[0:3], off sc1
	s_nop 1
	v_pk_mul_f32 v[0:1], v[6:7], v[40:41] op_sel_hi:[0,1]
	v_and_b32_sdwa v2, v1, v197 dst_sel:DWORD dst_unused:UNUSED_PAD src0_sel:WORD_1 src1_sel:DWORD
	v_and_b32_sdwa v3, v0, v197 dst_sel:DWORD dst_unused:UNUSED_PAD src0_sel:WORD_1 src1_sel:DWORD
	v_add3_u32 v1, v1, v2, s78
	v_add3_u32 v0, v0, v3, s78
	v_pk_mul_f32 v[2:3], v[6:7], v[42:43] op_sel_hi:[0,1]
	v_lshrrev_b32_e32 v0, 16, v0
	v_and_b32_sdwa v7, v2, v197 dst_sel:DWORD dst_unused:UNUSED_PAD src0_sel:WORD_1 src1_sel:DWORD
	v_and_or_b32 v0, v1, s79, v0
	v_and_b32_sdwa v1, v3, v197 dst_sel:DWORD dst_unused:UNUSED_PAD src0_sel:WORD_1 src1_sel:DWORD
	v_add3_u32 v2, v2, v7, s78
	v_add3_u32 v1, v3, v1, s78
	v_lshrrev_b32_e32 v2, 16, v2
	v_and_or_b32 v1, v1, s79, v2
	v_pk_mul_f32 v[2:3], v[6:7], v[44:45] op_sel_hi:[0,1]
	v_and_b32_sdwa v7, v3, v197 dst_sel:DWORD dst_unused:UNUSED_PAD src0_sel:WORD_1 src1_sel:DWORD
	v_and_b32_sdwa v8, v2, v197 dst_sel:DWORD dst_unused:UNUSED_PAD src0_sel:WORD_1 src1_sel:DWORD
	v_add3_u32 v2, v2, v8, s78
	v_pk_mul_f32 v[8:9], v[6:7], v[46:47] op_sel_hi:[0,1]
	v_add3_u32 v3, v3, v7, s78
	v_lshrrev_b32_e32 v2, 16, v2
	v_and_b32_sdwa v7, v8, v197 dst_sel:DWORD dst_unused:UNUSED_PAD src0_sel:WORD_1 src1_sel:DWORD
	v_and_or_b32 v2, v3, s79, v2
	v_and_b32_sdwa v3, v9, v197 dst_sel:DWORD dst_unused:UNUSED_PAD src0_sel:WORD_1 src1_sel:DWORD
	v_add3_u32 v7, v8, v7, s78
	v_add3_u32 v3, v9, v3, s78
	v_lshrrev_b32_e32 v7, 16, v7
	v_and_or_b32 v3, v3, s79, v7
	v_permlane32_swap_b32_e32 v0, v2
	s_nop 0
	v_permlane32_swap_b32_e32 v1, v3
	global_store_dwordx4 v[4:5], v[0:3], off offset:32 sc1
	s_nop 1
	v_pk_mul_f32 v[0:1], v[6:7], v[48:49] op_sel_hi:[0,1]
	v_and_b32_sdwa v2, v1, v197 dst_sel:DWORD dst_unused:UNUSED_PAD src0_sel:WORD_1 src1_sel:DWORD
	v_and_b32_sdwa v3, v0, v197 dst_sel:DWORD dst_unused:UNUSED_PAD src0_sel:WORD_1 src1_sel:DWORD
	v_add3_u32 v1, v1, v2, s78
	v_add3_u32 v0, v0, v3, s78
	v_pk_mul_f32 v[2:3], v[6:7], v[50:51] op_sel_hi:[0,1]
	v_lshrrev_b32_e32 v0, 16, v0
	v_and_b32_sdwa v7, v2, v197 dst_sel:DWORD dst_unused:UNUSED_PAD src0_sel:WORD_1 src1_sel:DWORD
	v_and_or_b32 v0, v1, s79, v0
	v_and_b32_sdwa v1, v3, v197 dst_sel:DWORD dst_unused:UNUSED_PAD src0_sel:WORD_1 src1_sel:DWORD
	v_add3_u32 v2, v2, v7, s78
	v_add3_u32 v1, v3, v1, s78
	v_lshrrev_b32_e32 v2, 16, v2
	v_and_or_b32 v1, v1, s79, v2
	v_pk_mul_f32 v[2:3], v[6:7], v[52:53] op_sel_hi:[0,1]
	v_and_b32_sdwa v7, v3, v197 dst_sel:DWORD dst_unused:UNUSED_PAD src0_sel:WORD_1 src1_sel:DWORD
	v_and_b32_sdwa v8, v2, v197 dst_sel:DWORD dst_unused:UNUSED_PAD src0_sel:WORD_1 src1_sel:DWORD
	v_add3_u32 v2, v2, v8, s78
	v_pk_mul_f32 v[8:9], v[6:7], v[54:55] op_sel_hi:[0,1]
	v_add3_u32 v3, v3, v7, s78
	v_lshrrev_b32_e32 v2, 16, v2
	v_and_b32_sdwa v7, v8, v197 dst_sel:DWORD dst_unused:UNUSED_PAD src0_sel:WORD_1 src1_sel:DWORD
	v_and_or_b32 v2, v3, s79, v2
	v_and_b32_sdwa v3, v9, v197 dst_sel:DWORD dst_unused:UNUSED_PAD src0_sel:WORD_1 src1_sel:DWORD
	v_add3_u32 v7, v8, v7, s78
	v_add3_u32 v3, v9, v3, s78
	v_lshrrev_b32_e32 v7, 16, v7
	v_and_or_b32 v3, v3, s79, v7
	v_permlane32_swap_b32_e32 v0, v2
	s_nop 0
	v_permlane32_swap_b32_e32 v1, v3
	global_store_dwordx4 v[4:5], v[0:3], off offset:64 sc1
	s_nop 1
	v_pk_mul_f32 v[0:1], v[6:7], v[56:57] op_sel_hi:[0,1]
	v_and_b32_sdwa v2, v1, v197 dst_sel:DWORD dst_unused:UNUSED_PAD src0_sel:WORD_1 src1_sel:DWORD
	v_and_b32_sdwa v3, v0, v197 dst_sel:DWORD dst_unused:UNUSED_PAD src0_sel:WORD_1 src1_sel:DWORD
	v_add3_u32 v1, v1, v2, s78
	v_add3_u32 v0, v0, v3, s78
	v_pk_mul_f32 v[2:3], v[6:7], v[58:59] op_sel_hi:[0,1]
	v_lshrrev_b32_e32 v0, 16, v0
	v_and_b32_sdwa v7, v2, v197 dst_sel:DWORD dst_unused:UNUSED_PAD src0_sel:WORD_1 src1_sel:DWORD
	v_and_or_b32 v0, v1, s79, v0
	v_and_b32_sdwa v1, v3, v197 dst_sel:DWORD dst_unused:UNUSED_PAD src0_sel:WORD_1 src1_sel:DWORD
	v_add3_u32 v2, v2, v7, s78
	v_add3_u32 v1, v3, v1, s78
	v_lshrrev_b32_e32 v2, 16, v2
	v_and_or_b32 v1, v1, s79, v2
	v_pk_mul_f32 v[2:3], v[6:7], v[60:61] op_sel_hi:[0,1]
	v_and_b32_sdwa v7, v3, v197 dst_sel:DWORD dst_unused:UNUSED_PAD src0_sel:WORD_1 src1_sel:DWORD
	v_and_b32_sdwa v8, v2, v197 dst_sel:DWORD dst_unused:UNUSED_PAD src0_sel:WORD_1 src1_sel:DWORD
	v_add3_u32 v3, v3, v7, s78
	v_add3_u32 v2, v2, v8, s78
	v_pk_mul_f32 v[6:7], v[6:7], v[62:63] op_sel_hi:[0,1]
	v_lshrrev_b32_e32 v2, 16, v2
	v_and_b32_sdwa v8, v6, v197 dst_sel:DWORD dst_unused:UNUSED_PAD src0_sel:WORD_1 src1_sel:DWORD
	v_and_or_b32 v2, v3, s79, v2
	v_and_b32_sdwa v3, v7, v197 dst_sel:DWORD dst_unused:UNUSED_PAD src0_sel:WORD_1 src1_sel:DWORD
	v_add3_u32 v6, v6, v8, s78
	v_add3_u32 v3, v7, v3, s78
	v_lshrrev_b32_e32 v6, 16, v6
	v_and_or_b32 v3, v3, s79, v6
	v_permlane32_swap_b32_e32 v0, v2
	s_nop 0
	v_permlane32_swap_b32_e32 v1, v3
	global_store_dwordx4 v[4:5], v[0:3], off offset:96 sc1
	s_load_dword s0, s[84:85], 0x10
	s_waitcnt lgkmcnt(0)
	s_lshr_b32 s0, s0, 16
	s_cmp_lg_u32 s0, 0
	s_cselect_b64 s[0:1], -1, 0
	s_cmp_lg_u64 s[0:1], 0
	s_addc_u32 s14, s14, s63
	s_cmp_ge_i32 s14, s12
	s_cbranch_scc1 .LBB0_885

.LBB0_888:
	v_fmamk_f32 v64, v64, 0x3dd53b94, v174
	v_exp_f32_e32 v64, v64
	v_fmamk_f32 v65, v65, 0x3dd53b94, v174
	v_exp_f32_e32 v65, v65
	v_fmamk_f32 v66, v66, 0x3dd53b94, v174
	v_exp_f32_e32 v66, v66
	v_fmamk_f32 v67, v67, 0x3dd53b94, v174
	v_exp_f32_e32 v67, v67
	v_fmamk_f32 v68, v68, 0x3dd53b94, v174
	v_add_f32_e32 v92, 0, v64
	v_exp_f32_e32 v68, v68
	v_fmamk_f32 v69, v69, 0x3dd53b94, v174
	v_add_f32_e32 v92, v65, v92
	v_exp_f32_e32 v69, v69
	v_fmamk_f32 v70, v70, 0x3dd53b94, v174
	v_add_f32_e32 v92, v66, v92
	v_exp_f32_e32 v70, v70
	v_fmamk_f32 v71, v71, 0x3dd53b94, v174
	v_add_f32_e32 v92, v67, v92
	v_exp_f32_e32 v71, v71
	v_fmamk_f32 v72, v72, 0x3dd53b94, v174
	v_add_f32_e32 v92, v68, v92
	v_exp_f32_e32 v72, v72
	v_fmamk_f32 v73, v73, 0x3dd53b94, v174
	v_add_f32_e32 v92, v69, v92
	v_exp_f32_e32 v73, v73
	v_fmamk_f32 v74, v74, 0x3dd53b94, v174
	v_add_f32_e32 v92, v70, v92
	v_exp_f32_e32 v74, v74
	v_fmamk_f32 v75, v75, 0x3dd53b94, v174
	v_add_f32_e32 v92, v71, v92
	v_exp_f32_e32 v75, v75
	v_fmamk_f32 v76, v76, 0x3dd53b94, v174
	v_add_f32_e32 v92, v72, v92
	v_exp_f32_e32 v76, v76
	v_fmamk_f32 v77, v77, 0x3dd53b94, v174
	v_cvt_pk_bf16_f32 v64, v64, v65
	v_cvt_pk_bf16_f32 v65, v66, v67
	v_cvt_pk_bf16_f32 v66, v68, v69
	v_cvt_pk_bf16_f32 v67, v70, v71
	v_add_f32_e32 v92, v73, v92
	v_exp_f32_e32 v77, v77
	v_fmamk_f32 v78, v78, 0x3dd53b94, v174
	s_waitcnt vmcnt(7)
	v_mfma_f32_32x32x16_bf16 v[48:63], v[134:137], v[64:67], v[48:63]
	v_add_f32_e32 v92, v74, v92
	v_exp_f32_e32 v78, v78
	v_fmac_f32_e32 v174, 0x3dd53b94, v79
	v_add_f32_e32 v92, v75, v92
	v_exp_f32_e32 v79, v174
	v_add_f32_e32 v92, v76, v92
	v_add_f32_e32 v92, v77, v92
	s_waitcnt vmcnt(6)
	v_mfma_f32_32x32x16_bf16 v[32:47], v[126:129], v[64:67], v[32:47]
	v_add_f32_e32 v92, v78, v92
	v_add_f32_e32 v92, v79, v92
	s_lshl_b32 s2, s9, 8
	v_mov_b32_e32 v93, v92
	s_or_b32 s2, s2, s10
	s_nop 0
	v_permlane32_swap_b32_e32 v92, v93
	s_waitcnt vmcnt(5)
	v_mfma_f32_32x32x16_bf16 v[16:31], v[122:125], v[64:67], v[16:31]
	v_add_f32_e32 v92, v92, v93
	v_add_f32_e32 v92, v106, v92
	s_lshl_b32 s40, s8, 8
	s_add_i32 s0, s0, s92
	s_waitcnt vmcnt(4)
	v_mfma_f32_32x32x16_bf16 v[0:15], v[102:105], v[64:67], v[0:15]
	v_cvt_pk_bf16_f32 v64, v72, v73
	v_cvt_pk_bf16_f32 v65, v74, v75
	v_cvt_pk_bf16_f32 v66, v76, v77
	v_cvt_pk_bf16_f32 v67, v78, v79
	s_waitcnt vmcnt(3)
	s_nop 0
	v_mfma_f32_32x32x16_bf16 v[48:63], v[98:101], v[64:67], v[48:63]
	s_waitcnt vmcnt(2)
	v_mfma_f32_32x32x16_bf16 v[32:47], v[88:91], v[64:67], v[32:47]
	s_waitcnt vmcnt(1)
	v_mfma_f32_32x32x16_bf16 v[16:31], v[84:87], v[64:67], v[16:31]
	s_waitcnt vmcnt(0)
	v_mfma_f32_32x32x16_bf16 v[0:15], v[80:83], v[64:67], v[0:15]
	v_or_b32_e32 v64, s2, v182
	v_bfrev_b32_e32 v65, 64
	v_lshl_or_b32 v96, v64, 12, v65
	v_lshl_add_u64 v[64:65], s[36:37], 0, v[96:97]
	v_lshl_add_u64 v[70:71], v[64:65], 0, s[40:41]
	v_div_scale_f32 v64, s[2:3], v92, v92, 1.0
	v_rcp_f32_e32 v65, v64
	v_readlane_b32 s2, v254, 14
	s_add_i32 s1, s1, s2
	s_cmp_lt_u32 s0, 64
	v_fma_f32 v66, -v64, v65, 1.0
	v_fmac_f32_e32 v65, v66, v65
	v_div_scale_f32 v66, vcc, 1.0, v92, 1.0
	v_mul_f32_e32 v67, v66, v65
	v_fma_f32 v68, -v64, v67, v66
	v_fmac_f32_e32 v67, v68, v65
	v_fma_f32 v64, -v64, v67, v66
	v_div_fmas_f32 v64, v64, v65, v67
	v_div_fixup_f32 v64, v64, v92, 1.0
	v_pk_mul_f32 v[48:49], v[64:65], v[48:49] op_sel_hi:[0,1]
	v_and_b32_sdwa v66, v48, v197 dst_sel:DWORD dst_unused:UNUSED_PAD src0_sel:WORD_1 src1_sel:DWORD
	v_and_b32_sdwa v65, v49, v197 dst_sel:DWORD dst_unused:UNUSED_PAD src0_sel:WORD_1 src1_sel:DWORD
	v_add3_u32 v48, v48, v66, s78
	v_add3_u32 v49, v49, v65, s78
	v_lshrrev_b32_e32 v48, 16, v48
	v_and_or_b32 v66, v49, s79, v48
	v_pk_mul_f32 v[48:49], v[64:65], v[50:51] op_sel_hi:[0,1]
	v_and_b32_sdwa v51, v48, v197 dst_sel:DWORD dst_unused:UNUSED_PAD src0_sel:WORD_1 src1_sel:DWORD
	v_and_b32_sdwa v50, v49, v197 dst_sel:DWORD dst_unused:UNUSED_PAD src0_sel:WORD_1 src1_sel:DWORD
	v_add3_u32 v48, v48, v51, s78
	v_add3_u32 v49, v49, v50, s78
	v_lshrrev_b32_e32 v48, 16, v48
	v_and_or_b32 v67, v49, s79, v48
	v_pk_mul_f32 v[48:49], v[64:65], v[52:53] op_sel_hi:[0,1]
	v_and_b32_sdwa v51, v48, v197 dst_sel:DWORD dst_unused:UNUSED_PAD src0_sel:WORD_1 src1_sel:DWORD
	v_and_b32_sdwa v50, v49, v197 dst_sel:DWORD dst_unused:UNUSED_PAD src0_sel:WORD_1 src1_sel:DWORD
	v_add3_u32 v48, v48, v51, s78
	v_add3_u32 v49, v49, v50, s78
	v_lshrrev_b32_e32 v48, 16, v48
	v_and_or_b32 v68, v49, s79, v48
	v_pk_mul_f32 v[48:49], v[64:65], v[54:55] op_sel_hi:[0,1]
	v_and_b32_sdwa v50, v49, v197 dst_sel:DWORD dst_unused:UNUSED_PAD src0_sel:WORD_1 src1_sel:DWORD
	v_and_b32_sdwa v51, v48, v197 dst_sel:DWORD dst_unused:UNUSED_PAD src0_sel:WORD_1 src1_sel:DWORD
	v_add3_u32 v49, v49, v50, s78
	v_add3_u32 v48, v48, v51, s78
	v_pk_mul_f32 v[50:51], v[64:65], v[56:57] op_sel_hi:[0,1]
	v_and_b32_sdwa v52, v51, v197 dst_sel:DWORD dst_unused:UNUSED_PAD src0_sel:WORD_1 src1_sel:DWORD
	v_and_b32_sdwa v53, v50, v197 dst_sel:DWORD dst_unused:UNUSED_PAD src0_sel:WORD_1 src1_sel:DWORD
	v_add3_u32 v51, v51, v52, s78
	v_add3_u32 v50, v50, v53, s78
	v_pk_mul_f32 v[52:53], v[64:65], v[58:59] op_sel_hi:[0,1]
	v_lshrrev_b32_e32 v50, 16, v50
	v_and_b32_sdwa v54, v52, v197 dst_sel:DWORD dst_unused:UNUSED_PAD src0_sel:WORD_1 src1_sel:DWORD
	v_and_or_b32 v50, v51, s79, v50
	v_and_b32_sdwa v51, v53, v197 dst_sel:DWORD dst_unused:UNUSED_PAD src0_sel:WORD_1 src1_sel:DWORD
	v_add3_u32 v52, v52, v54, s78
	v_add3_u32 v51, v53, v51, s78
	v_lshrrev_b32_e32 v52, 16, v52
	v_and_or_b32 v51, v51, s79, v52
	v_pk_mul_f32 v[52:53], v[64:65], v[60:61] op_sel_hi:[0,1]
	v_and_b32_sdwa v54, v53, v197 dst_sel:DWORD dst_unused:UNUSED_PAD src0_sel:WORD_1 src1_sel:DWORD
	v_and_b32_sdwa v55, v52, v197 dst_sel:DWORD dst_unused:UNUSED_PAD src0_sel:WORD_1 src1_sel:DWORD
	v_add3_u32 v53, v53, v54, s78
	v_add3_u32 v52, v52, v55, s78
	v_pk_mul_f32 v[54:55], v[64:65], v[62:63] op_sel_hi:[0,1]
	v_lshrrev_b32_e32 v52, 16, v52
	v_and_b32_sdwa v56, v54, v197 dst_sel:DWORD dst_unused:UNUSED_PAD src0_sel:WORD_1 src1_sel:DWORD
	v_and_or_b32 v52, v53, s79, v52
	v_and_b32_sdwa v53, v55, v197 dst_sel:DWORD dst_unused:UNUSED_PAD src0_sel:WORD_1 src1_sel:DWORD
	v_add3_u32 v54, v54, v56, s78
	v_add3_u32 v53, v55, v53, s78
	v_lshrrev_b32_e32 v54, 16, v54
	v_lshrrev_b32_e32 v48, 16, v48
	v_and_or_b32 v53, v53, s79, v54
	v_and_or_b32 v69, v49, s79, v48
	v_lshl_add_u64 v[48:49], v[184:185], 1, v[70:71]
	v_permlane32_swap_b32_e32 v50, v52
	v_permlane32_swap_b32_e32 v51, v53
	v_pk_mul_f32 v[32:33], v[64:65], v[32:33] op_sel_hi:[0,1]
	global_store_dwordx4 v[48:49], v[50:53], off offset:32 sc1
	v_pk_mul_f32 v[34:35], v[64:65], v[34:35] op_sel_hi:[0,1]
	v_pk_mul_f32 v[16:17], v[64:65], v[16:17] op_sel_hi:[0,1]
	v_and_b32_sdwa v51, v32, v197 dst_sel:DWORD dst_unused:UNUSED_PAD src0_sel:WORD_1 src1_sel:DWORD
	v_and_b32_sdwa v50, v33, v197 dst_sel:DWORD dst_unused:UNUSED_PAD src0_sel:WORD_1 src1_sel:DWORD
	v_add3_u32 v32, v32, v51, s78
	v_add3_u32 v33, v33, v50, s78
	v_lshrrev_b32_e32 v32, 16, v32
	v_and_b32_sdwa v50, v34, v197 dst_sel:DWORD dst_unused:UNUSED_PAD src0_sel:WORD_1 src1_sel:DWORD
	v_and_or_b32 v32, v33, s79, v32
	v_and_b32_sdwa v33, v35, v197 dst_sel:DWORD dst_unused:UNUSED_PAD src0_sel:WORD_1 src1_sel:DWORD
	v_add3_u32 v34, v34, v50, s78
	v_add3_u32 v33, v35, v33, s78
	v_lshrrev_b32_e32 v34, 16, v34
	v_and_or_b32 v33, v33, s79, v34
	v_pk_mul_f32 v[34:35], v[64:65], v[36:37] op_sel_hi:[0,1]
	v_and_b32_sdwa v36, v35, v197 dst_sel:DWORD dst_unused:UNUSED_PAD src0_sel:WORD_1 src1_sel:DWORD
	v_and_b32_sdwa v37, v34, v197 dst_sel:DWORD dst_unused:UNUSED_PAD src0_sel:WORD_1 src1_sel:DWORD
	v_add3_u32 v35, v35, v36, s78
	v_add3_u32 v34, v34, v37, s78
	v_pk_mul_f32 v[36:37], v[64:65], v[38:39] op_sel_hi:[0,1]
	v_lshrrev_b32_e32 v34, 16, v34
	v_and_b32_sdwa v38, v36, v197 dst_sel:DWORD dst_unused:UNUSED_PAD src0_sel:WORD_1 src1_sel:DWORD
	v_and_or_b32 v34, v35, s79, v34
	v_and_b32_sdwa v35, v37, v197 dst_sel:DWORD dst_unused:UNUSED_PAD src0_sel:WORD_1 src1_sel:DWORD
	v_add3_u32 v36, v36, v38, s78
	v_add3_u32 v35, v37, v35, s78
	v_lshrrev_b32_e32 v36, 16, v36
	v_and_or_b32 v35, v35, s79, v36
	v_permlane32_swap_b32_e32 v32, v34
	s_nop 0
	v_permlane32_swap_b32_e32 v33, v35
	global_store_dwordx4 v[48:49], v[32:35], off offset:64 sc1
	v_pk_mul_f32 v[18:19], v[64:65], v[18:19] op_sel_hi:[0,1]
	v_pk_mul_f32 v[0:1], v[64:65], v[0:1] op_sel_hi:[0,1]
	v_pk_mul_f32 v[32:33], v[64:65], v[40:41] op_sel_hi:[0,1]
	v_and_b32_sdwa v34, v33, v197 dst_sel:DWORD dst_unused:UNUSED_PAD src0_sel:WORD_1 src1_sel:DWORD
	v_and_b32_sdwa v35, v32, v197 dst_sel:DWORD dst_unused:UNUSED_PAD src0_sel:WORD_1 src1_sel:DWORD
	v_add3_u32 v33, v33, v34, s78
	v_add3_u32 v32, v32, v35, s78
	v_pk_mul_f32 v[34:35], v[64:65], v[42:43] op_sel_hi:[0,1]
	v_lshrrev_b32_e32 v32, 16, v32
	v_and_b32_sdwa v36, v34, v197 dst_sel:DWORD dst_unused:UNUSED_PAD src0_sel:WORD_1 src1_sel:DWORD
	v_and_or_b32 v32, v33, s79, v32
	v_and_b32_sdwa v33, v35, v197 dst_sel:DWORD dst_unused:UNUSED_PAD src0_sel:WORD_1 src1_sel:DWORD
	v_add3_u32 v34, v34, v36, s78
	v_add3_u32 v33, v35, v33, s78
	v_lshrrev_b32_e32 v34, 16, v34
	v_and_or_b32 v33, v33, s79, v34
	v_pk_mul_f32 v[34:35], v[64:65], v[44:45] op_sel_hi:[0,1]
	v_and_b32_sdwa v36, v35, v197 dst_sel:DWORD dst_unused:UNUSED_PAD src0_sel:WORD_1 src1_sel:DWORD
	v_and_b32_sdwa v37, v34, v197 dst_sel:DWORD dst_unused:UNUSED_PAD src0_sel:WORD_1 src1_sel:DWORD
	v_add3_u32 v35, v35, v36, s78
	v_add3_u32 v34, v34, v37, s78
	v_pk_mul_f32 v[36:37], v[64:65], v[46:47] op_sel_hi:[0,1]
	v_lshrrev_b32_e32 v34, 16, v34
	v_and_b32_sdwa v38, v36, v197 dst_sel:DWORD dst_unused:UNUSED_PAD src0_sel:WORD_1 src1_sel:DWORD
	v_and_or_b32 v34, v35, s79, v34
	v_and_b32_sdwa v35, v37, v197 dst_sel:DWORD dst_unused:UNUSED_PAD src0_sel:WORD_1 src1_sel:DWORD
	v_add3_u32 v36, v36, v38, s78
	v_add3_u32 v35, v37, v35, s78
	v_lshrrev_b32_e32 v36, 16, v36
	v_and_or_b32 v35, v35, s79, v36
	v_permlane32_swap_b32_e32 v32, v34
	s_nop 0
	v_permlane32_swap_b32_e32 v33, v35
	global_store_dwordx4 v[48:49], v[32:35], off offset:96 sc1
	v_pk_mul_f32 v[2:3], v[64:65], v[2:3] op_sel_hi:[0,1]
	v_permlane32_swap_b32_e32 v66, v68
	v_and_b32_sdwa v33, v16, v197 dst_sel:DWORD dst_unused:UNUSED_PAD src0_sel:WORD_1 src1_sel:DWORD
	v_and_b32_sdwa v32, v17, v197 dst_sel:DWORD dst_unused:UNUSED_PAD src0_sel:WORD_1 src1_sel:DWORD
	v_add3_u32 v16, v16, v33, s78
	v_add3_u32 v17, v17, v32, s78
	v_lshrrev_b32_e32 v16, 16, v16
	v_and_b32_sdwa v32, v18, v197 dst_sel:DWORD dst_unused:UNUSED_PAD src0_sel:WORD_1 src1_sel:DWORD
	v_and_or_b32 v16, v17, s79, v16
	v_and_b32_sdwa v17, v19, v197 dst_sel:DWORD dst_unused:UNUSED_PAD src0_sel:WORD_1 src1_sel:DWORD
	v_add3_u32 v18, v18, v32, s78
	v_add3_u32 v17, v19, v17, s78
	v_lshrrev_b32_e32 v18, 16, v18
	v_and_or_b32 v17, v17, s79, v18
	v_pk_mul_f32 v[18:19], v[64:65], v[20:21] op_sel_hi:[0,1]
	v_and_b32_sdwa v20, v19, v197 dst_sel:DWORD dst_unused:UNUSED_PAD src0_sel:WORD_1 src1_sel:DWORD
	v_and_b32_sdwa v21, v18, v197 dst_sel:DWORD dst_unused:UNUSED_PAD src0_sel:WORD_1 src1_sel:DWORD
	v_add3_u32 v19, v19, v20, s78
	v_add3_u32 v18, v18, v21, s78
	v_pk_mul_f32 v[20:21], v[64:65], v[22:23] op_sel_hi:[0,1]
	v_lshrrev_b32_e32 v18, 16, v18
	v_and_b32_sdwa v22, v20, v197 dst_sel:DWORD dst_unused:UNUSED_PAD src0_sel:WORD_1 src1_sel:DWORD
	v_and_or_b32 v18, v19, s79, v18
	v_and_b32_sdwa v19, v21, v197 dst_sel:DWORD dst_unused:UNUSED_PAD src0_sel:WORD_1 src1_sel:DWORD
	v_add3_u32 v20, v20, v22, s78
	v_add3_u32 v19, v21, v19, s78
	v_lshrrev_b32_e32 v20, 16, v20
	v_and_or_b32 v19, v19, s79, v20
	v_permlane32_swap_b32_e32 v16, v18
	s_nop 0
	v_permlane32_swap_b32_e32 v17, v19
	global_store_dwordx4 v[48:49], v[16:19], off offset:128 sc1
	v_permlane32_swap_b32_e32 v67, v69
	s_nop 0
	v_pk_mul_f32 v[16:17], v[64:65], v[24:25] op_sel_hi:[0,1]
	v_and_b32_sdwa v18, v17, v197 dst_sel:DWORD dst_unused:UNUSED_PAD src0_sel:WORD_1 src1_sel:DWORD
	v_and_b32_sdwa v19, v16, v197 dst_sel:DWORD dst_unused:UNUSED_PAD src0_sel:WORD_1 src1_sel:DWORD
	v_add3_u32 v17, v17, v18, s78
	v_add3_u32 v16, v16, v19, s78
	v_pk_mul_f32 v[18:19], v[64:65], v[26:27] op_sel_hi:[0,1]
	v_lshrrev_b32_e32 v16, 16, v16
	v_and_b32_sdwa v20, v18, v197 dst_sel:DWORD dst_unused:UNUSED_PAD src0_sel:WORD_1 src1_sel:DWORD
	v_and_or_b32 v16, v17, s79, v16
	v_and_b32_sdwa v17, v19, v197 dst_sel:DWORD dst_unused:UNUSED_PAD src0_sel:WORD_1 src1_sel:DWORD
	v_add3_u32 v18, v18, v20, s78
	v_add3_u32 v17, v19, v17, s78
	v_lshrrev_b32_e32 v18, 16, v18
	v_and_or_b32 v17, v17, s79, v18
	v_pk_mul_f32 v[18:19], v[64:65], v[28:29] op_sel_hi:[0,1]
	v_and_b32_sdwa v20, v19, v197 dst_sel:DWORD dst_unused:UNUSED_PAD src0_sel:WORD_1 src1_sel:DWORD
	v_and_b32_sdwa v21, v18, v197 dst_sel:DWORD dst_unused:UNUSED_PAD src0_sel:WORD_1 src1_sel:DWORD
	v_add3_u32 v19, v19, v20, s78
	v_add3_u32 v18, v18, v21, s78
	v_pk_mul_f32 v[20:21], v[64:65], v[30:31] op_sel_hi:[0,1]
	v_lshrrev_b32_e32 v18, 16, v18
	v_and_b32_sdwa v22, v20, v197 dst_sel:DWORD dst_unused:UNUSED_PAD src0_sel:WORD_1 src1_sel:DWORD
	v_and_or_b32 v18, v19, s79, v18
	v_and_b32_sdwa v19, v21, v197 dst_sel:DWORD dst_unused:UNUSED_PAD src0_sel:WORD_1 src1_sel:DWORD
	v_add3_u32 v20, v20, v22, s78
	v_add3_u32 v19, v21, v19, s78
	v_lshrrev_b32_e32 v20, 16, v20
	v_and_or_b32 v19, v19, s79, v20
	v_permlane32_swap_b32_e32 v16, v18
	s_nop 0
	v_permlane32_swap_b32_e32 v17, v19
	global_store_dwordx4 v[48:49], v[16:19], off offset:160 sc1
	global_store_dwordx4 v[48:49], v[66:69], off sc1
	s_nop 0
	v_and_b32_sdwa v17, v0, v197 dst_sel:DWORD dst_unused:UNUSED_PAD src0_sel:WORD_1 src1_sel:DWORD
	v_and_b32_sdwa v16, v1, v197 dst_sel:DWORD dst_unused:UNUSED_PAD src0_sel:WORD_1 src1_sel:DWORD
	v_add3_u32 v0, v0, v17, s78
	v_add3_u32 v1, v1, v16, s78
	v_lshrrev_b32_e32 v0, 16, v0
	v_and_b32_sdwa v16, v2, v197 dst_sel:DWORD dst_unused:UNUSED_PAD src0_sel:WORD_1 src1_sel:DWORD
	v_and_or_b32 v0, v1, s79, v0
	v_and_b32_sdwa v1, v3, v197 dst_sel:DWORD dst_unused:UNUSED_PAD src0_sel:WORD_1 src1_sel:DWORD
	v_add3_u32 v2, v2, v16, s78
	v_add3_u32 v1, v3, v1, s78
	v_lshrrev_b32_e32 v2, 16, v2
	v_and_or_b32 v1, v1, s79, v2
	v_pk_mul_f32 v[2:3], v[64:65], v[4:5] op_sel_hi:[0,1]
	v_and_b32_sdwa v4, v3, v197 dst_sel:DWORD dst_unused:UNUSED_PAD src0_sel:WORD_1 src1_sel:DWORD
	v_and_b32_sdwa v5, v2, v197 dst_sel:DWORD dst_unused:UNUSED_PAD src0_sel:WORD_1 src1_sel:DWORD
	v_add3_u32 v3, v3, v4, s78
	v_add3_u32 v2, v2, v5, s78
	v_pk_mul_f32 v[4:5], v[64:65], v[6:7] op_sel_hi:[0,1]
	v_lshrrev_b32_e32 v2, 16, v2
	v_and_b32_sdwa v6, v4, v197 dst_sel:DWORD dst_unused:UNUSED_PAD src0_sel:WORD_1 src1_sel:DWORD
	v_and_or_b32 v2, v3, s79, v2
	v_and_b32_sdwa v3, v5, v197 dst_sel:DWORD dst_unused:UNUSED_PAD src0_sel:WORD_1 src1_sel:DWORD
	v_add3_u32 v4, v4, v6, s78
	v_add3_u32 v3, v5, v3, s78
	v_lshrrev_b32_e32 v4, 16, v4
	v_and_or_b32 v3, v3, s79, v4
	v_permlane32_swap_b32_e32 v0, v2
	s_nop 0
	v_permlane32_swap_b32_e32 v1, v3
	global_store_dwordx4 v[48:49], v[0:3], off offset:192 sc1
	s_nop 1
	v_pk_mul_f32 v[0:1], v[64:65], v[8:9] op_sel_hi:[0,1]
	v_and_b32_sdwa v2, v1, v197 dst_sel:DWORD dst_unused:UNUSED_PAD src0_sel:WORD_1 src1_sel:DWORD
	v_and_b32_sdwa v3, v0, v197 dst_sel:DWORD dst_unused:UNUSED_PAD src0_sel:WORD_1 src1_sel:DWORD
	v_add3_u32 v1, v1, v2, s78
	v_add3_u32 v0, v0, v3, s78
	v_pk_mul_f32 v[2:3], v[64:65], v[10:11] op_sel_hi:[0,1]
	v_lshrrev_b32_e32 v0, 16, v0
	v_and_b32_sdwa v4, v2, v197 dst_sel:DWORD dst_unused:UNUSED_PAD src0_sel:WORD_1 src1_sel:DWORD
	v_and_or_b32 v0, v1, s79, v0
	v_and_b32_sdwa v1, v3, v197 dst_sel:DWORD dst_unused:UNUSED_PAD src0_sel:WORD_1 src1_sel:DWORD
	v_add3_u32 v2, v2, v4, s78
	v_add3_u32 v1, v3, v1, s78
	v_lshrrev_b32_e32 v2, 16, v2
	v_and_or_b32 v1, v1, s79, v2
	v_pk_mul_f32 v[2:3], v[64:65], v[12:13] op_sel_hi:[0,1]
	v_and_b32_sdwa v4, v3, v197 dst_sel:DWORD dst_unused:UNUSED_PAD src0_sel:WORD_1 src1_sel:DWORD
	v_and_b32_sdwa v5, v2, v197 dst_sel:DWORD dst_unused:UNUSED_PAD src0_sel:WORD_1 src1_sel:DWORD
	v_add3_u32 v3, v3, v4, s78
	v_add3_u32 v2, v2, v5, s78
	v_pk_mul_f32 v[4:5], v[64:65], v[14:15] op_sel_hi:[0,1]
	v_lshrrev_b32_e32 v2, 16, v2
	v_and_b32_sdwa v6, v4, v197 dst_sel:DWORD dst_unused:UNUSED_PAD src0_sel:WORD_1 src1_sel:DWORD
	v_and_or_b32 v2, v3, s79, v2
	v_and_b32_sdwa v3, v5, v197 dst_sel:DWORD dst_unused:UNUSED_PAD src0_sel:WORD_1 src1_sel:DWORD
	v_add3_u32 v4, v4, v6, s78
	v_add3_u32 v3, v5, v3, s78
	v_lshrrev_b32_e32 v4, 16, v4
	v_and_or_b32 v3, v3, s79, v4
	v_permlane32_swap_b32_e32 v0, v2
	s_nop 0
	v_permlane32_swap_b32_e32 v1, v3
	global_store_dwordx4 v[48:49], v[0:3], off offset:224 sc1
	s_cbranch_scc0 .LBB0_904

.LBB0_976:
	s_ashr_i32 s13, s12, 31
	s_lshl_b64 s[2:3], s[12:13], 22
	v_readlane_b32 s12, v250, 6
	v_lshl_or_b32 v136, s22, 8, v134
	v_readlane_b32 s13, v250, 7
	s_add_u32 s2, s12, s2
	v_lshl_add_u32 v138, s14, 8, v133
	s_addc_u32 s3, s13, s3
	v_ashrrev_i32_e32 v137, 31, v136
	v_ashrrev_i32_e32 v139, 31, v138
	v_lshl_add_u64 v[136:137], v[136:137], 2, s[2:3]
	v_lshlrev_b64 v[140:141], 13, v[138:139]
	v_lshl_add_u64 v[140:141], v[136:137], 0, v[140:141]
	global_store_dwordx4 v[140:141], v[126:129], off sc1
	global_store_dwordx4 v[140:141], v[122:125], off offset:64 sc1
	global_store_dwordx4 v[140:141], v[110:113], off offset:512 sc1
	global_store_dwordx4 v[140:141], v[102:105], off offset:576 sc1
	s_mov_b64 s[2:3], 0x100000
	v_readlane_b32 s74, v254, 50
	v_or_b32_e32 v102, 16, v138
	v_ashrrev_i32_e32 v103, 31, v102
	v_lshlrev_b64 v[102:103], 13, v[102:103]
	v_lshl_add_u64 v[102:103], v[136:137], 0, v[102:103]
	global_store_dwordx4 v[102:103], v[118:121], off sc1
	global_store_dwordx4 v[102:103], v[114:117], off offset:64 sc1
	global_store_dwordx4 v[102:103], v[92:95], off offset:512 sc1
	global_store_dwordx4 v[102:103], v[84:87], off offset:576 sc1
	v_readlane_b32 s36, v254, 53
	v_readlane_b32 s58, v254, 59
	v_or_b32_e32 v84, 32, v138
	v_ashrrev_i32_e32 v85, 31, v84
	v_lshlrev_b64 v[84:85], 13, v[84:85]
	v_lshl_add_u64 v[84:85], v[136:137], 0, v[84:85]
	global_store_dwordx4 v[84:85], v[106:109], off sc1
	global_store_dwordx4 v[84:85], v[98:101], off offset:64 sc1
	global_store_dwordx4 v[84:85], v[76:79], off offset:512 sc1
	global_store_dwordx4 v[84:85], v[72:75], off offset:576 sc1
	v_readlane_b32 s75, v254, 51
	v_readlane_b32 s82, v254, 52
	v_or_b32_e32 v72, 48, v138
	v_ashrrev_i32_e32 v73, 31, v72
	v_lshlrev_b64 v[72:73], 13, v[72:73]
	v_lshl_add_u64 v[72:73], v[136:137], 0, v[72:73]
	global_store_dwordx4 v[72:73], v[88:91], off sc1
	global_store_dwordx4 v[72:73], v[80:83], off offset:64 sc1
	global_store_dwordx4 v[72:73], v[68:71], off offset:512 sc1
	global_store_dwordx4 v[72:73], v[64:67], off offset:576 sc1
	v_readlane_b32 s37, v254, 54
	v_readlane_b32 s83, v254, 55
	v_lshl_add_u64 v[64:65], v[140:141], 0, s[2:3]
	s_mov_b32 s2, 0x100000
	v_add_co_u32_e32 v66, vcc, s2, v140
	s_mov_b64 s[2:3], 0x120000
	s_nop 0
	v_addc_co_u32_e32 v67, vcc, 0, v141, vcc
	global_store_dwordx4 v[66:67], v[60:63], off sc1
	global_store_dwordx4 v[64:65], v[56:59], off offset:64 sc1
	global_store_dwordx4 v[64:65], v[44:47], off offset:512 sc1
	global_store_dwordx4 v[64:65], v[40:43], off offset:576 sc1
	s_movk_i32 s86, 0x1000
	s_movk_i32 s87, 0x3000
	v_lshl_add_u64 v[40:41], v[140:141], 0, s[2:3]
	s_mov_b32 s2, 0x120000
	v_add_co_u32_e32 v42, vcc, s2, v140
	s_mov_b64 s[2:3], 0x140000
	s_nop 0
	v_addc_co_u32_e32 v43, vcc, 0, v141, vcc
	global_store_dwordx4 v[42:43], v[52:55], off sc1
	global_store_dwordx4 v[40:41], v[48:51], off offset:64 sc1
	global_store_dwordx4 v[40:41], v[28:31], off offset:512 sc1
	global_store_dwordx4 v[40:41], v[24:27], off offset:576 sc1
	v_readlane_b32 s63, v254, 58
	s_mov_b64 s[72:73], 0x2000
	v_lshl_add_u64 v[24:25], v[140:141], 0, s[2:3]
	s_mov_b32 s2, 0x140000
	v_add_co_u32_e32 v26, vcc, s2, v140
	s_mov_b64 s[2:3], 0x160000
	s_nop 0
	v_addc_co_u32_e32 v27, vcc, 0, v141, vcc
	global_store_dwordx4 v[26:27], v[36:39], off sc1
	global_store_dwordx4 v[24:25], v[32:35], off offset:64 sc1
	global_store_dwordx4 v[24:25], v[12:15], off offset:512 sc1
	global_store_dwordx4 v[24:25], v[8:11], off offset:576 sc1
	v_readlane_b32 s59, v254, 60
	v_readlane_b32 s60, v255, 4
	v_add_co_u32_e32 v10, vcc, 0x160000, v140
	v_lshl_add_u64 v[8:9], v[140:141], 0, s[2:3]
	s_nop 0
	v_addc_co_u32_e32 v11, vcc, 0, v141, vcc
	s_and_b64 vcc, exec, s[0:1]
	s_mov_b64 s[0:1], -1
	global_store_dwordx4 v[10:11], v[20:23], off sc1
	global_store_dwordx4 v[8:9], v[16:19], off offset:64 sc1
	global_store_dwordx4 v[8:9], v[4:7], off offset:512 sc1
	global_store_dwordx4 v[8:9], v[0:3], off offset:576 sc1
	v_readlane_b32 s61, v255, 5
	s_cbranch_vccnz .LBB0_965
	s_andn2_b64 vcc, exec, s[10:11]
	s_cbranch_vccnz .LBB0_964
	s_barrier
	s_branch .LBB0_964

.LBB0_1021:
	s_or_b64 exec, exec, s[8:9]
	s_mov_b64 s[2:3], 0x20000
	v_ashrrev_i32_e32 v149, 31, v148
	v_lshlrev_b64 v[134:135], 13, v[148:149]
	v_lshl_add_u64 v[134:135], s[96:97], 0, v[134:135]
	v_lshl_add_u64 v[134:135], v[162:163], 2, v[134:135]
	v_mov_b64_e32 v[136:137], v[134:135]
	flat_store_dwordx4 v[136:137], v[110:113] sc1
	flat_store_dwordx4 v[136:137], v[106:109] offset:16 sc1
	flat_store_dwordx4 v[136:137], v[4:7] offset:512 sc1
	flat_store_dwordx4 v[136:137], v[0:3] offset:528 sc1
	v_lshl_add_u64 v[136:137], v[134:135], 0, s[2:3]
	s_mov_b64 s[2:3], 0x40000
	flat_store_dwordx4 v[136:137], v[118:121] sc1
	flat_store_dwordx4 v[136:137], v[114:117] offset:16 sc1
	flat_store_dwordx4 v[136:137], v[12:15] offset:512 sc1
	flat_store_dwordx4 v[136:137], v[8:11] offset:528 sc1
	v_lshl_add_u64 v[136:137], v[134:135], 0, s[2:3]
	s_mov_b64 s[2:3], 0x60000
	flat_store_dwordx4 v[136:137], v[126:129] sc1
	flat_store_dwordx4 v[136:137], v[122:125] offset:16 sc1
	flat_store_dwordx4 v[136:137], v[24:27] offset:512 sc1
	flat_store_dwordx4 v[136:137], v[20:23] offset:528 sc1
	v_lshl_add_u64 v[136:137], v[134:135], 0, s[2:3]
	s_mov_b64 s[2:3], 0x100000
	flat_store_dwordx4 v[136:137], v[92:95] sc1
	flat_store_dwordx4 v[136:137], v[88:91] offset:16 sc1
	flat_store_dwordx4 v[136:137], v[40:43] offset:512 sc1
	flat_store_dwordx4 v[136:137], v[32:35] offset:528 sc1
	v_lshl_add_u64 v[136:137], v[134:135], 0, s[2:3]
	s_mov_b64 s[2:3], 0x120000
	flat_store_dwordx4 v[136:137], v[102:105] sc1
	flat_store_dwordx4 v[136:137], v[98:101] offset:16 sc1
	flat_store_dwordx4 v[136:137], v[60:63] offset:512 sc1
	flat_store_dwordx4 v[136:137], v[56:59] offset:528 sc1
	v_lshl_add_u64 v[136:137], v[134:135], 0, s[2:3]
	s_mov_b64 s[2:3], 0x140000
	flat_store_dwordx4 v[136:137], v[84:87] sc1
	flat_store_dwordx4 v[136:137], v[80:83] offset:16 sc1
	flat_store_dwordx4 v[136:137], v[76:79] offset:512 sc1
	flat_store_dwordx4 v[136:137], v[72:75] offset:528 sc1
	v_lshl_add_u64 v[136:137], v[134:135], 0, s[2:3]
	s_mov_b64 s[2:3], 0x160000
	v_lshl_add_u64 v[134:135], v[134:135], 0, s[2:3]
	flat_store_dwordx4 v[136:137], v[68:71] sc1
	flat_store_dwordx4 v[136:137], v[64:67] offset:16 sc1
	flat_store_dwordx4 v[136:137], v[52:55] offset:512 sc1
	flat_store_dwordx4 v[136:137], v[48:51] offset:528 sc1
	s_cmp_gt_u32 s40, 63
	flat_store_dwordx4 v[134:135], v[44:47] sc1
	flat_store_dwordx4 v[134:135], v[36:39] offset:16 sc1
	flat_store_dwordx4 v[134:135], v[28:31] offset:512 sc1
	flat_store_dwordx4 v[134:135], v[16:19] offset:528 sc1
	s_cbranch_scc1 .LBB0_1027
	s_lshl_b32 s8, s53, 4
	s_lshl_b32 s2, s60, 7
	s_ashr_i32 s9, s8, 31
	s_or_b32 s2, s2, 64
	s_lshl_b64 s[8:9], s[8:9], 2
	v_readlane_b32 s3, v252, 39
	s_add_u32 s8, s3, s8
	v_readlane_b32 s3, v252, 40
	s_addc_u32 s9, s3, s9
	s_mov_b32 s3, 0x100001
	s_branch .LBB0_1024

.LBB0_1029:
	s_or_b64 exec, exec, s[8:9]
	s_lshl_b32 s40, s60, 11
	s_lshl_b64 s[0:1], s[40:41], 2
	s_add_u32 s0, s7, s0
	s_addc_u32 s1, s52, s1
	v_readlane_b32 s2, v255, 2
	v_readlane_b32 s3, v255, 3
	s_add_u32 s2, s2, s12
	s_addc_u32 s3, s3, 0
	v_lshl_add_u64 v[148:149], s[2:3], 0, v[146:147]
	v_lshl_add_u64 v[146:147], s[0:1], 0, v[146:147]
	s_mov_b32 s0, 0x8000
	v_add_co_u32_e32 v138, vcc, s0, v148
	s_mov_b64 s[2:3], 0x8000
	s_nop 0
	v_addc_co_u32_e32 v139, vcc, 0, v149, vcc
	v_lshl_add_u64 v[158:159], v[148:149], 0, s[2:3]
	global_load_dwordx4 v[130:133], v[146:147], off offset:16
	global_load_dwordx4 v[134:137], v[146:147], off
	s_nop 0
	global_load_dwordx4 v[138:141], v[138:139], off
	s_nop 0
	global_load_dwordx4 v[142:145], v[158:159], off offset:16
	v_lshl_add_u64 v[174:175], v[148:149], 0, s[28:29]
	v_lshl_add_u32 v96, v172, 2, 0
	v_readlane_b32 s0, v253, 17
	v_readlane_b32 s1, v253, 18
	s_waitcnt vmcnt(0)
	v_pk_add_f32 v[140:141], v[140:141], 1.0 op_sel_hi:[1,0]
	s_nop 0
	v_pk_mul_f32 v[168:169], v[136:137], v[140:141]
	v_pk_add_f32 v[136:137], v[142:143], 1.0 op_sel_hi:[1,0]
	v_pk_add_f32 v[138:139], v[138:139], 1.0 op_sel_hi:[1,0]
	v_pk_mul_f32 v[166:167], v[130:131], v[136:137]
	v_add_co_u32_e32 v130, vcc, s6, v148
	v_pk_mul_f32 v[170:171], v[134:135], v[138:139]
	s_nop 0
	v_addc_co_u32_e32 v131, vcc, 0, v149, vcc
	global_load_dwordx4 v[138:141], v[130:131], off
	global_load_dwordx4 v[154:157], v[174:175], off offset:16
	s_waitcnt lgkmcnt(0)
	s_barrier
	v_pk_add_f32 v[134:135], v[144:145], 1.0 op_sel_hi:[1,0]
	s_nop 0
	v_pk_mul_f32 v[164:165], v[132:133], v[134:135]
	global_load_dwordx4 v[142:145], v[146:147], off offset:512
	global_load_dwordx4 v[150:153], v[146:147], off offset:528
	s_nop 0
	global_load_dwordx4 v[146:149], v[158:159], off offset:512
	s_nop 0
	global_load_dwordx4 v[158:161], v[158:159], off offset:528
	s_nop 0
	global_load_dwordx4 v[130:133], v[174:175], off offset:528
	global_load_dwordx4 v[134:137], v[174:175], off offset:512
	ds_read_b32 v174, v96 offset:8192
	s_waitcnt lgkmcnt(0)
	v_pk_mul_f32 v[108:109], v[108:109], v[174:175] op_sel_hi:[1,0]
	v_pk_mul_f32 v[110:111], v[110:111], v[174:175] op_sel_hi:[1,0]
	v_pk_mul_f32 v[112:113], v[112:113], v[174:175] op_sel_hi:[1,0]
	v_pk_mul_f32 v[106:107], v[106:107], v[174:175] op_sel_hi:[1,0]
	s_waitcnt vmcnt(7)
	v_pk_fma_f32 v[112:113], v[168:169], v[112:113], v[140:141]
	s_waitcnt vmcnt(6)
	v_pk_fma_f32 v[108:109], v[164:165], v[108:109], v[156:157]
	v_pk_fma_f32 v[110:111], v[170:171], v[110:111], v[138:139]
	v_pk_fma_f32 v[106:107], v[166:167], v[106:107], v[154:155]
	v_cvt_pk_bf16_f32 v174, v110, v111
	v_cvt_pk_bf16_f32 v175, v112, v113
	v_add_u32_e32 v110, s5, v172
	v_cvt_pk_bf16_f32 v176, v106, v107
	v_cvt_pk_bf16_f32 v177, v108, v109
	ds_read_b32 v108, v96 offset:8256
	v_ashrrev_i32_e32 v111, 31, v110
	v_lshlrev_b64 v[106:107], 12, v[110:111]
	v_lshl_add_u64 v[106:107], s[0:1], 0, v[106:107]
	v_lshlrev_b64 v[112:113], 1, v[162:163]
	s_waitcnt lgkmcnt(0)
	v_pk_mul_f32 v[118:119], v[118:119], v[108:109] op_sel_hi:[1,0]
	v_pk_mul_f32 v[120:121], v[120:121], v[108:109] op_sel_hi:[1,0]
	v_pk_mul_f32 v[114:115], v[114:115], v[108:109] op_sel_hi:[1,0]
	v_pk_mul_f32 v[108:109], v[116:117], v[108:109] op_sel_hi:[1,0]
	v_lshl_add_u64 v[106:107], v[106:107], 0, v[112:113]
	v_pk_fma_f32 v[108:109], v[164:165], v[108:109], v[156:157]
	v_pk_fma_f32 v[116:117], v[166:167], v[114:115], v[154:155]
	global_store_dwordx4 v[106:107], v[174:177], off sc1
	v_pk_fma_f32 v[120:121], v[168:169], v[120:121], v[140:141]
	v_pk_fma_f32 v[118:119], v[170:171], v[118:119], v[138:139]
	s_nop 0
	v_cvt_pk_bf16_f32 v114, v118, v119
	v_cvt_pk_bf16_f32 v115, v120, v121
	v_cvt_pk_bf16_f32 v116, v116, v117
	v_cvt_pk_bf16_f32 v117, v108, v109
	v_add_u32_e32 v108, 16, v110
	v_ashrrev_i32_e32 v109, 31, v108
	v_lshlrev_b64 v[108:109], 12, v[108:109]
	v_lshl_add_u64 v[108:109], s[0:1], 0, v[108:109]
	v_lshl_add_u64 v[108:109], v[108:109], 0, v[112:113]
	global_store_dwordx4 v[108:109], v[114:117], off sc1
	ds_read_b32 v114, v96 offset:8320
	s_waitcnt lgkmcnt(0)
	v_pk_mul_f32 v[118:119], v[128:129], v[114:115] op_sel_hi:[1,0]
	v_pk_mul_f32 v[116:117], v[126:127], v[114:115] op_sel_hi:[1,0]
	v_pk_mul_f32 v[120:121], v[122:123], v[114:115] op_sel_hi:[1,0]
	v_pk_mul_f32 v[114:115], v[124:125], v[114:115] op_sel_hi:[1,0]
	v_pk_fma_f32 v[118:119], v[168:169], v[118:119], v[140:141]
	v_pk_fma_f32 v[116:117], v[170:171], v[116:117], v[138:139]
	v_pk_fma_f32 v[114:115], v[164:165], v[114:115], v[156:157]
	v_pk_fma_f32 v[120:121], v[166:167], v[120:121], v[154:155]
	v_cvt_pk_bf16_f32 v116, v116, v117
	v_cvt_pk_bf16_f32 v117, v118, v119
	s_nop 0
	v_cvt_pk_bf16_f32 v118, v120, v121
	v_cvt_pk_bf16_f32 v119, v114, v115
	v_add_u32_e32 v114, 32, v110
	v_ashrrev_i32_e32 v115, 31, v114
	v_lshlrev_b64 v[114:115], 12, v[114:115]
	v_lshl_add_u64 v[114:115], s[0:1], 0, v[114:115]
	v_lshl_add_u64 v[114:115], v[114:115], 0, v[112:113]
	global_store_dwordx4 v[114:115], v[116:119], off sc1
	ds_read_b32 v116, v96 offset:8384
	s_waitcnt lgkmcnt(0)
	v_pk_mul_f32 v[92:93], v[92:93], v[116:117] op_sel_hi:[1,0]
	v_pk_mul_f32 v[88:89], v[88:89], v[116:117] op_sel_hi:[1,0]
	v_pk_mul_f32 v[94:95], v[94:95], v[116:117] op_sel_hi:[1,0]
	v_pk_fma_f32 v[92:93], v[170:171], v[92:93], v[138:139]
	v_pk_mul_f32 v[90:91], v[90:91], v[116:117] op_sel_hi:[1,0]
	v_pk_fma_f32 v[88:89], v[166:167], v[88:89], v[154:155]
	v_pk_fma_f32 v[94:95], v[168:169], v[94:95], v[140:141]
	v_pk_fma_f32 v[116:117], v[164:165], v[90:91], v[156:157]
	v_cvt_pk_bf16_f32 v90, v92, v93
	v_cvt_pk_bf16_f32 v91, v94, v95
	v_cvt_pk_bf16_f32 v92, v88, v89
	v_add_u32_e32 v88, 48, v110
	v_ashrrev_i32_e32 v89, 31, v88
	v_lshlrev_b64 v[88:89], 12, v[88:89]
	v_lshl_add_u64 v[88:89], s[0:1], 0, v[88:89]
	v_lshl_add_u64 v[88:89], v[88:89], 0, v[112:113]
	v_cvt_pk_bf16_f32 v93, v116, v117
	global_store_dwordx4 v[88:89], v[90:93], off sc1
	ds_read_b32 v90, v96 offset:8704
	s_waitcnt lgkmcnt(0)
	v_pk_mul_f32 v[94:95], v[104:105], v[90:91] op_sel_hi:[1,0]
	v_pk_mul_f32 v[92:93], v[102:103], v[90:91] op_sel_hi:[1,0]
	v_pk_mul_f32 v[98:99], v[98:99], v[90:91] op_sel_hi:[1,0]
	v_pk_mul_f32 v[90:91], v[100:101], v[90:91] op_sel_hi:[1,0]
	v_pk_fma_f32 v[94:95], v[168:169], v[94:95], v[140:141]
	v_pk_fma_f32 v[92:93], v[170:171], v[92:93], v[138:139]
	v_pk_fma_f32 v[90:91], v[164:165], v[90:91], v[156:157]
	v_pk_fma_f32 v[98:99], v[166:167], v[98:99], v[154:155]
	v_cvt_pk_bf16_f32 v92, v92, v93
	v_cvt_pk_bf16_f32 v93, v94, v95
	s_nop 0
	v_cvt_pk_bf16_f32 v94, v98, v99
	v_cvt_pk_bf16_f32 v95, v90, v91
	v_add_u32_e32 v90, 0x80, v110
	v_ashrrev_i32_e32 v91, 31, v90
	v_lshlrev_b64 v[90:91], 12, v[90:91]
	v_lshl_add_u64 v[90:91], s[0:1], 0, v[90:91]
	v_lshl_add_u64 v[90:91], v[90:91], 0, v[112:113]
	global_store_dwordx4 v[90:91], v[92:95], off sc1
	ds_read_b32 v92, v96 offset:8768
	s_waitcnt lgkmcnt(0)
	v_pk_mul_f32 v[84:85], v[84:85], v[92:93] op_sel_hi:[1,0]
	v_pk_mul_f32 v[80:81], v[80:81], v[92:93] op_sel_hi:[1,0]
	v_pk_mul_f32 v[86:87], v[86:87], v[92:93] op_sel_hi:[1,0]
	v_pk_fma_f32 v[84:85], v[170:171], v[84:85], v[138:139]
	v_pk_mul_f32 v[82:83], v[82:83], v[92:93] op_sel_hi:[1,0]
	v_pk_fma_f32 v[80:81], v[166:167], v[80:81], v[154:155]
	v_pk_fma_f32 v[86:87], v[168:169], v[86:87], v[140:141]
	v_pk_fma_f32 v[92:93], v[164:165], v[82:83], v[156:157]
	v_cvt_pk_bf16_f32 v82, v84, v85
	v_cvt_pk_bf16_f32 v83, v86, v87
	v_cvt_pk_bf16_f32 v84, v80, v81
	v_add_u32_e32 v80, 0x90, v110
	v_ashrrev_i32_e32 v81, 31, v80
	v_lshlrev_b64 v[80:81], 12, v[80:81]
	v_lshl_add_u64 v[80:81], s[0:1], 0, v[80:81]
	v_lshl_add_u64 v[80:81], v[80:81], 0, v[112:113]
	v_cvt_pk_bf16_f32 v85, v92, v93
	global_store_dwordx4 v[80:81], v[82:85], off sc1
	ds_read_b32 v82, v96 offset:8832
	s_waitcnt lgkmcnt(0)
	v_pk_mul_f32 v[68:69], v[68:69], v[82:83] op_sel_hi:[1,0]
	v_pk_mul_f32 v[64:65], v[64:65], v[82:83] op_sel_hi:[1,0]
	v_pk_mul_f32 v[70:71], v[70:71], v[82:83] op_sel_hi:[1,0]
	v_pk_fma_f32 v[68:69], v[170:171], v[68:69], v[138:139]
	v_pk_mul_f32 v[66:67], v[66:67], v[82:83] op_sel_hi:[1,0]
	v_pk_fma_f32 v[64:65], v[166:167], v[64:65], v[154:155]
	v_pk_fma_f32 v[70:71], v[168:169], v[70:71], v[140:141]
	v_pk_fma_f32 v[82:83], v[164:165], v[66:67], v[156:157]
	v_cvt_pk_bf16_f32 v66, v68, v69
	v_cvt_pk_bf16_f32 v67, v70, v71
	v_cvt_pk_bf16_f32 v68, v64, v65
	v_add_u32_e32 v64, 0xa0, v110
	v_ashrrev_i32_e32 v65, 31, v64
	v_lshlrev_b64 v[64:65], 12, v[64:65]
	v_lshl_add_u64 v[64:65], s[0:1], 0, v[64:65]
	v_lshl_add_u64 v[64:65], v[64:65], 0, v[112:113]
	v_cvt_pk_bf16_f32 v69, v82, v83
	global_store_dwordx4 v[64:65], v[66:69], off sc1
	ds_read_b32 v66, v96 offset:8896
	s_waitcnt lgkmcnt(0)
	v_pk_mul_f32 v[44:45], v[44:45], v[66:67] op_sel_hi:[1,0]
	v_pk_mul_f32 v[46:47], v[46:47], v[66:67] op_sel_hi:[1,0]
	v_pk_mul_f32 v[36:37], v[36:37], v[66:67] op_sel_hi:[1,0]
	v_pk_fma_f32 v[46:47], v[168:169], v[46:47], v[140:141]
	v_pk_fma_f32 v[44:45], v[170:171], v[44:45], v[138:139]
	v_pk_fma_f32 v[36:37], v[166:167], v[36:37], v[154:155]
	v_cvt_pk_bf16_f32 v44, v44, v45
	v_cvt_pk_bf16_f32 v45, v46, v47
	v_pk_mul_f32 v[38:39], v[38:39], v[66:67] op_sel_hi:[1,0]
	v_cvt_pk_bf16_f32 v46, v36, v37
	v_add_u32_e32 v36, 0xb0, v110
	v_ashrrev_i32_e32 v37, 31, v36
	v_lshlrev_b64 v[36:37], 12, v[36:37]
	v_lshl_add_u64 v[36:37], s[0:1], 0, v[36:37]
	v_lshl_add_u64 v[36:37], v[36:37], 0, v[112:113]
	v_pk_fma_f32 v[38:39], v[164:165], v[38:39], v[156:157]
	s_waitcnt vmcnt(10)
	v_pk_add_f32 v[66:67], v[146:147], 1.0 op_sel_hi:[1,0]
	v_cvt_pk_bf16_f32 v47, v38, v39
	global_store_dwordx4 v[36:37], v[44:47], off sc1
	ds_read_b32 v68, v96 offset:8192
	s_waitcnt vmcnt(10)
	v_pk_add_f32 v[38:39], v[160:161], 1.0 op_sel_hi:[1,0]
	v_pk_add_f32 v[44:45], v[158:159], 1.0 op_sel_hi:[1,0]
	v_pk_mul_f32 v[38:39], v[152:153], v[38:39]
	v_pk_mul_f32 v[44:45], v[150:151], v[44:45]
	v_pk_add_f32 v[46:47], v[148:149], 1.0 op_sel_hi:[1,0]
	v_pk_mul_f32 v[66:67], v[142:143], v[66:67]
	s_waitcnt lgkmcnt(0)
	v_pk_mul_f32 v[4:5], v[4:5], v[68:69] op_sel_hi:[1,0]
	v_pk_mul_f32 v[0:1], v[0:1], v[68:69] op_sel_hi:[1,0]
	v_pk_mul_f32 v[2:3], v[2:3], v[68:69] op_sel_hi:[1,0]
	v_pk_mul_f32 v[46:47], v[144:145], v[46:47]
	v_pk_mul_f32 v[6:7], v[6:7], v[68:69] op_sel_hi:[1,0]
	s_waitcnt vmcnt(8)
	v_pk_fma_f32 v[4:5], v[66:67], v[4:5], v[134:135]
	v_pk_fma_f32 v[68:69], v[38:39], v[2:3], v[132:133]
	v_pk_fma_f32 v[2:3], v[44:45], v[0:1], v[130:131]
	v_cvt_pk_bf16_f32 v0, v4, v5
	v_pk_fma_f32 v[6:7], v[46:47], v[6:7], v[136:137]
	s_nop 0
	v_cvt_pk_bf16_f32 v1, v6, v7
	v_cvt_pk_bf16_f32 v2, v2, v3
	v_cvt_pk_bf16_f32 v3, v68, v69
	global_store_dwordx4 v[106:107], v[0:3], off offset:256 sc1
	ds_read_b32 v0, v96 offset:8256
	s_waitcnt lgkmcnt(0)
	v_pk_mul_f32 v[4:5], v[14:15], v[0:1] op_sel_hi:[1,0]
	v_pk_mul_f32 v[2:3], v[12:13], v[0:1] op_sel_hi:[1,0]
	v_pk_mul_f32 v[6:7], v[8:9], v[0:1] op_sel_hi:[1,0]
	v_pk_mul_f32 v[0:1], v[10:11], v[0:1] op_sel_hi:[1,0]
	v_pk_fma_f32 v[2:3], v[66:67], v[2:3], v[134:135]
	v_pk_fma_f32 v[8:9], v[38:39], v[0:1], v[132:133]
	v_cvt_pk_bf16_f32 v0, v2, v3
	v_pk_fma_f32 v[4:5], v[46:47], v[4:5], v[136:137]
	v_pk_fma_f32 v[6:7], v[44:45], v[6:7], v[130:131]
	v_cvt_pk_bf16_f32 v1, v4, v5
	s_nop 0
	v_cvt_pk_bf16_f32 v2, v6, v7
	v_cvt_pk_bf16_f32 v3, v8, v9
	global_store_dwordx4 v[108:109], v[0:3], off offset:256 sc1
	ds_read_b32 v0, v96 offset:8320
	s_waitcnt lgkmcnt(0)
	v_pk_mul_f32 v[4:5], v[26:27], v[0:1] op_sel_hi:[1,0]
	v_pk_mul_f32 v[2:3], v[24:25], v[0:1] op_sel_hi:[1,0]
	v_pk_mul_f32 v[6:7], v[20:21], v[0:1] op_sel_hi:[1,0]
	v_pk_mul_f32 v[0:1], v[22:23], v[0:1] op_sel_hi:[1,0]
	v_pk_fma_f32 v[2:3], v[66:67], v[2:3], v[134:135]
	v_pk_fma_f32 v[8:9], v[38:39], v[0:1], v[132:133]
	v_cvt_pk_bf16_f32 v0, v2, v3
	v_pk_fma_f32 v[4:5], v[46:47], v[4:5], v[136:137]
	v_pk_fma_f32 v[6:7], v[44:45], v[6:7], v[130:131]
	v_cvt_pk_bf16_f32 v1, v4, v5
	s_nop 0
	v_cvt_pk_bf16_f32 v2, v6, v7
	v_cvt_pk_bf16_f32 v3, v8, v9
	global_store_dwordx4 v[114:115], v[0:3], off offset:256 sc1
	ds_read_b32 v0, v96 offset:8384
	s_waitcnt lgkmcnt(0)
	v_pk_mul_f32 v[4:5], v[42:43], v[0:1] op_sel_hi:[1,0]
	v_pk_mul_f32 v[2:3], v[40:41], v[0:1] op_sel_hi:[1,0]
	v_pk_mul_f32 v[6:7], v[32:33], v[0:1] op_sel_hi:[1,0]
	v_pk_mul_f32 v[0:1], v[34:35], v[0:1] op_sel_hi:[1,0]
	v_pk_fma_f32 v[2:3], v[66:67], v[2:3], v[134:135]
	v_pk_fma_f32 v[8:9], v[38:39], v[0:1], v[132:133]
	v_cvt_pk_bf16_f32 v0, v2, v3
	v_pk_fma_f32 v[4:5], v[46:47], v[4:5], v[136:137]
	v_pk_fma_f32 v[6:7], v[44:45], v[6:7], v[130:131]
	v_cvt_pk_bf16_f32 v1, v4, v5
	s_nop 0
	v_cvt_pk_bf16_f32 v2, v6, v7
	v_cvt_pk_bf16_f32 v3, v8, v9
	global_store_dwordx4 v[88:89], v[0:3], off offset:256 sc1
	ds_read_b32 v0, v96 offset:8704
	s_waitcnt lgkmcnt(0)
	v_pk_mul_f32 v[4:5], v[62:63], v[0:1] op_sel_hi:[1,0]
	v_pk_mul_f32 v[2:3], v[60:61], v[0:1] op_sel_hi:[1,0]
	v_pk_mul_f32 v[6:7], v[56:57], v[0:1] op_sel_hi:[1,0]
	v_pk_mul_f32 v[0:1], v[58:59], v[0:1] op_sel_hi:[1,0]
	v_pk_fma_f32 v[2:3], v[66:67], v[2:3], v[134:135]
	v_pk_fma_f32 v[8:9], v[38:39], v[0:1], v[132:133]
	v_cvt_pk_bf16_f32 v0, v2, v3
	v_pk_fma_f32 v[4:5], v[46:47], v[4:5], v[136:137]
	v_pk_fma_f32 v[6:7], v[44:45], v[6:7], v[130:131]
	v_cvt_pk_bf16_f32 v1, v4, v5
	s_nop 0
	v_cvt_pk_bf16_f32 v2, v6, v7
	v_cvt_pk_bf16_f32 v3, v8, v9
	global_store_dwordx4 v[90:91], v[0:3], off offset:256 sc1
	ds_read_b32 v0, v96 offset:8768
	s_waitcnt lgkmcnt(0)
	v_pk_mul_f32 v[4:5], v[78:79], v[0:1] op_sel_hi:[1,0]
	v_pk_mul_f32 v[2:3], v[76:77], v[0:1] op_sel_hi:[1,0]
	v_pk_mul_f32 v[6:7], v[72:73], v[0:1] op_sel_hi:[1,0]
	v_pk_mul_f32 v[0:1], v[74:75], v[0:1] op_sel_hi:[1,0]
	v_pk_fma_f32 v[2:3], v[66:67], v[2:3], v[134:135]
	v_pk_fma_f32 v[8:9], v[38:39], v[0:1], v[132:133]
	v_cvt_pk_bf16_f32 v0, v2, v3
	v_pk_fma_f32 v[4:5], v[46:47], v[4:5], v[136:137]
	v_pk_fma_f32 v[6:7], v[44:45], v[6:7], v[130:131]
	v_cvt_pk_bf16_f32 v1, v4, v5
	s_nop 0
	v_cvt_pk_bf16_f32 v2, v6, v7
	v_cvt_pk_bf16_f32 v3, v8, v9
	global_store_dwordx4 v[80:81], v[0:3], off offset:256 sc1
	ds_read_b32 v0, v96 offset:8832
	s_waitcnt lgkmcnt(0)
	v_pk_mul_f32 v[4:5], v[54:55], v[0:1] op_sel_hi:[1,0]
	v_pk_mul_f32 v[2:3], v[52:53], v[0:1] op_sel_hi:[1,0]
	v_pk_mul_f32 v[6:7], v[48:49], v[0:1] op_sel_hi:[1,0]
	v_pk_mul_f32 v[0:1], v[50:51], v[0:1] op_sel_hi:[1,0]
	v_pk_fma_f32 v[2:3], v[66:67], v[2:3], v[134:135]
	v_pk_fma_f32 v[8:9], v[38:39], v[0:1], v[132:133]
	v_cvt_pk_bf16_f32 v0, v2, v3
	v_pk_fma_f32 v[4:5], v[46:47], v[4:5], v[136:137]
	v_pk_fma_f32 v[6:7], v[44:45], v[6:7], v[130:131]
	v_cvt_pk_bf16_f32 v1, v4, v5
	s_nop 0
	v_cvt_pk_bf16_f32 v2, v6, v7
	v_cvt_pk_bf16_f32 v3, v8, v9
	global_store_dwordx4 v[64:65], v[0:3], off offset:256 sc1
	ds_read_b32 v0, v96 offset:8896
	s_waitcnt lgkmcnt(0)
	v_pk_mul_f32 v[4:5], v[30:31], v[0:1] op_sel_hi:[1,0]
	v_pk_mul_f32 v[2:3], v[28:29], v[0:1] op_sel_hi:[1,0]
	v_pk_mul_f32 v[6:7], v[16:17], v[0:1] op_sel_hi:[1,0]
	v_pk_fma_f32 v[2:3], v[66:67], v[2:3], v[134:135]
	v_pk_mul_f32 v[0:1], v[18:19], v[0:1] op_sel_hi:[1,0]
	v_pk_fma_f32 v[4:5], v[46:47], v[4:5], v[136:137]
	v_pk_fma_f32 v[8:9], v[38:39], v[0:1], v[132:133]
	v_pk_fma_f32 v[6:7], v[44:45], v[6:7], v[130:131]
	v_cvt_pk_bf16_f32 v0, v2, v3
	v_cvt_pk_bf16_f32 v1, v4, v5
	s_nop 0
	v_cvt_pk_bf16_f32 v2, v6, v7
	v_cvt_pk_bf16_f32 v3, v8, v9
	global_store_dwordx4 v[36:37], v[0:3], off offset:256 sc1
	s_waitcnt lgkmcnt(0)
	s_barrier

.LBB0_1086:
	s_or_b64 exec, exec, s[12:13]
	v_mov_b32_e32 v49, s7
	s_waitcnt lgkmcnt(0)
	s_barrier
	ds_read_b96 v[50:52], v49
	v_mov_b32_e32 v49, s17
	s_waitcnt vmcnt(4)
	v_pk_add_f32 v[22:23], v[22:23], 1.0 op_sel_hi:[1,0]
	v_pk_add_f32 v[20:21], v[20:21], 1.0 op_sel_hi:[1,0]
	v_pk_add_f32 v[4:5], v[4:5], 1.0 op_sel_hi:[1,0]
	s_waitcnt lgkmcnt(0)
	v_mov_b32_e32 v54, v51
	ds_read_b32 v51, v49
	v_mov_b32_e32 v55, v52
	v_pk_add_f32 v[6:7], v[6:7], 1.0 op_sel_hi:[1,0]
	s_add_i32 s4, s10, 0x2000
	s_ashr_i32 s5, s4, 31
	s_waitcnt lgkmcnt(0)
	v_pk_add_f32 v[50:51], v[54:55], v[50:51]
	s_lshl_b64 s[4:5], s[4:5], 12
	v_add_f32_e32 v49, v50, v51
	v_fmamk_f32 v49, v49, 0x3a000000, v196
	v_rsq_f32_e32 v50, v49
	s_add_i32 s2, s2, s18
	s_cmpk_lt_i32 s2, 0x200
	v_pk_mul_f32 v[26:27], v[26:27], v[50:51] op_sel_hi:[1,0]
	v_pk_mul_f32 v[24:25], v[24:25], v[50:51] op_sel_hi:[1,0]
	v_pk_mul_f32 v[18:19], v[18:19], v[26:27]
	v_pk_mul_f32 v[16:17], v[16:17], v[24:25]
	s_waitcnt vmcnt(2)
	v_pk_fma_f32 v[14:15], v[22:23], v[18:19], v[14:15]
	v_pk_fma_f32 v[12:13], v[20:21], v[16:17], v[12:13]
	v_pk_mul_f32 v[16:17], v[30:31], v[50:51] op_sel_hi:[1,0]
	v_pk_mul_f32 v[18:19], v[28:29], v[50:51] op_sel_hi:[1,0]
	v_pk_mul_f32 v[10:11], v[10:11], v[16:17]
	v_pk_mul_f32 v[8:9], v[8:9], v[18:19]
	v_pk_fma_f32 v[6:7], v[6:7], v[10:11], v[2:3]
	v_pk_fma_f32 v[2:3], v[4:5], v[8:9], v[0:1]
	v_bfe_u32 v0, v12, 16, 1
	v_add3_u32 v0, v12, v0, s78
	v_bfe_u32 v1, v13, 16, 1
	v_lshrrev_b32_e32 v0, 16, v0
	v_add3_u32 v1, v13, v1, s78
	v_and_or_b32 v0, v1, s79, v0
	v_bfe_u32 v1, v14, 16, 1
	v_add3_u32 v1, v14, v1, s78
	v_bfe_u32 v4, v15, 16, 1
	v_lshrrev_b32_e32 v1, 16, v1
	v_add3_u32 v4, v15, v4, s78
	v_and_or_b32 v1, v4, s79, v1
	v_bfe_u32 v4, v2, 16, 1
	v_add3_u32 v2, v2, v4, s78
	v_bfe_u32 v4, v3, 16, 1
	v_lshrrev_b32_e32 v2, 16, v2
	v_add3_u32 v3, v3, v4, s78
	v_and_or_b32 v2, v3, s79, v2
	v_bfe_u32 v3, v6, 16, 1
	v_add3_u32 v3, v6, v3, s78
	v_bfe_u32 v4, v7, 16, 1
	v_lshrrev_b32_e32 v3, 16, v3
	v_add3_u32 v4, v7, v4, s78
	v_and_or_b32 v3, v4, s79, v3
	v_lshl_add_u64 v[4:5], v[34:35], 0, s[4:5]
	global_store_dwordx4 v[4:5], v[0:3], off sc1
	s_barrier
	s_cbranch_scc0 .LBB0_1089
.LBB0_1087:
	s_add_i32 s10, s93, s2
	s_ashr_i32 s11, s10, 31
	s_lshl_b64 s[12:13], s[10:11], 13
	v_lshl_add_u64 v[0:1], v[44:45], 0, s[12:13]
	v_add_co_u32_e32 v4, vcc, 0x400000, v0
	s_mov_b64 s[4:5], 0x400000
	s_nop 0
	v_addc_co_u32_e32 v5, vcc, 0, v1, vcc
	global_load_dwordx4 v[24:27], v[0:1], off offset:16
	global_load_dwordx4 v[28:31], v[0:1], off
	v_lshl_add_u64 v[2:3], v[0:1], 0, s[4:5]
	global_load_dwordx4 v[50:53], v[4:5], off
	global_load_dwordx4 v[54:57], v[2:3], off offset:16
	v_add_co_u32_e32 v4, vcc, 0x800000, v0
	s_mov_b64 s[4:5], 0x800000
	s_nop 0
	v_addc_co_u32_e32 v5, vcc, 0, v1, vcc
	v_lshl_add_u64 v[2:3], v[0:1], 0, s[4:5]
	global_load_dwordx4 v[58:61], v[4:5], off
	global_load_dwordx4 v[62:65], v[2:3], off offset:16
	v_add_co_u32_e32 v4, vcc, 0xc00000, v0
	s_mov_b64 s[4:5], 0xc00000
	s_nop 0
	v_addc_co_u32_e32 v5, vcc, 0, v1, vcc
	v_lshl_add_u64 v[2:3], v[0:1], 0, s[4:5]
	global_load_dwordx4 v[66:69], v[4:5], off
	global_load_dwordx4 v[70:73], v[2:3], off offset:16
	v_add_co_u32_e32 v4, vcc, 0x1000000, v0
	s_mov_b64 s[4:5], 0x1000000
	s_nop 0
	v_addc_co_u32_e32 v5, vcc, 0, v1, vcc
	v_lshl_add_u64 v[2:3], v[0:1], 0, s[4:5]
	global_load_dwordx4 v[74:77], v[4:5], off
	global_load_dwordx4 v[78:81], v[2:3], off offset:16
	s_mov_b64 s[4:5], 0x1400000
	v_add_co_u32_e32 v4, vcc, 0x1400000, v0
	v_lshl_add_u64 v[2:3], v[0:1], 0, s[4:5]
	s_nop 0
	v_addc_co_u32_e32 v5, vcc, 0, v1, vcc
	global_load_dwordx4 v[82:85], v[4:5], off
	global_load_dwordx4 v[86:89], v[2:3], off offset:16
	v_add_co_u32_e32 v2, vcc, 0x1800000, v0
	s_mov_b64 s[4:5], 0x1800000
	s_nop 0
	v_addc_co_u32_e32 v3, vcc, 0, v1, vcc
	global_load_dwordx4 v[90:93], v[2:3], off
	v_add_co_u32_e32 v2, vcc, 0x1c00000, v0
	s_waitcnt vmcnt(0)
	v_pk_add_f32 v[30:31], v[30:31], v[52:53]
	v_addc_co_u32_e32 v3, vcc, 0, v1, vcc
	global_load_dwordx4 v[98:101], v[2:3], off
	v_lshl_add_u64 v[2:3], v[0:1], 0, s[4:5]
	s_mov_b64 s[4:5], 0x1c00000
	v_lshl_add_u64 v[0:1], v[0:1], 0, s[4:5]
	global_load_dwordx4 v[102:105], v[2:3], off offset:16
	global_load_dwordx4 v[106:109], v[0:1], off offset:16
	v_lshl_add_u64 v[0:1], v[46:47], 0, s[12:13]
	global_load_dwordx4 v[110:113], v[36:37], off
	global_load_dwordx4 v[114:117], v[0:1], off
	global_load_dwordx4 v[118:121], v[0:1], off offset:16
	global_load_dwordx4 v[122:125], v[36:37], off offset:16
	global_load_dwordx4 v[8:11], v[38:39], off offset:16
	global_load_dwordx4 v[16:19], v[38:39], off
	global_load_dwordx4 v[4:7], v[40:41], off offset:16
	global_load_dwordx4 v[20:23], v[40:41], off
	global_load_dwordx4 v[0:3], v[42:43], off offset:16
	global_load_dwordx4 v[12:15], v[42:43], off
	v_pk_add_f32 v[28:29], v[28:29], v[50:51]
	v_pk_add_f32 v[26:27], v[26:27], v[56:57]
	v_pk_add_f32 v[24:25], v[24:25], v[54:55]
	v_pk_add_f32 v[50:51], v[60:61], v[68:69]
	v_pk_add_f32 v[52:53], v[58:59], v[66:67]
	v_pk_add_f32 v[56:57], v[62:63], v[70:71]
	v_pk_add_f32 v[30:31], v[30:31], v[50:51]
	v_pk_add_f32 v[28:29], v[28:29], v[52:53]
	v_pk_add_f32 v[24:25], v[24:25], v[56:57]
	v_pk_add_f32 v[54:55], v[64:65], v[72:73]
	v_pk_add_f32 v[50:51], v[76:77], v[84:85]
	v_pk_add_f32 v[52:53], v[74:75], v[82:83]
	v_pk_add_f32 v[26:27], v[26:27], v[54:55]
	v_pk_add_f32 v[54:55], v[80:81], v[88:89]
	s_waitcnt vmcnt(12)
	v_pk_add_f32 v[56:57], v[92:93], v[100:101]
	v_pk_add_f32 v[58:59], v[90:91], v[98:99]
	v_pk_add_f32 v[50:51], v[50:51], v[56:57]
	v_pk_add_f32 v[52:53], v[52:53], v[58:59]
	v_pk_add_f32 v[30:31], v[30:31], v[50:51]
	v_pk_add_f32 v[28:29], v[28:29], v[52:53]
	v_pk_add_f32 v[50:51], v[78:79], v[86:87]
	s_waitcnt vmcnt(10)
	v_pk_add_f32 v[52:53], v[104:105], v[108:109]
	v_pk_add_f32 v[56:57], v[102:103], v[106:107]
	v_pk_add_f32 v[52:53], v[54:55], v[52:53]
	v_pk_add_f32 v[50:51], v[50:51], v[56:57]
	v_pk_add_f32 v[30:31], v[30:31], 0 op_sel_hi:[1,0]
	v_pk_add_f32 v[28:29], v[28:29], 0 op_sel_hi:[1,0]
	v_pk_add_f32 v[26:27], v[26:27], v[52:53]
	v_pk_add_f32 v[24:25], v[24:25], v[50:51]
	v_pk_add_f32 v[50:51], v[26:27], 0 op_sel_hi:[1,0]
	v_pk_add_f32 v[52:53], v[24:25], 0 op_sel_hi:[1,0]
	s_waitcnt vmcnt(8)
	v_pk_fma_f32 v[26:27], v[112:113], v[30:31], v[116:117]
	v_pk_fma_f32 v[24:25], v[110:111], v[28:29], v[114:115]
	v_mul_f32_e32 v29, v27, v27
	v_mul_f32_e32 v28, v25, v25
	v_fmac_f32_e32 v28, v24, v24
	v_fmac_f32_e32 v29, v26, v26
	v_add_f32_e32 v49, v28, v29
	s_waitcnt vmcnt(6)
	v_pk_fma_f32 v[30:31], v[124:125], v[50:51], v[120:121]
	v_pk_fma_f32 v[28:29], v[122:123], v[52:53], v[118:119]
	v_mul_f32_e32 v51, v31, v31
	v_mul_f32_e32 v50, v29, v29
	v_fmac_f32_e32 v50, v28, v28
	v_fmac_f32_e32 v51, v30, v30
	v_add_f32_e32 v50, v50, v51
	v_add_f32_e32 v49, v49, v50
	v_lshl_add_u64 v[50:51], v[32:33], 0, s[12:13]
	global_store_dwordx4 v[50:51], v[24:27], off sc1
	global_store_dwordx4 v[50:51], v[28:31], off offset:16 sc1
	v_add_f32_dpp v49, v49, v49 quad_perm:[1,0,3,2] row_mask:0xf bank_mask:0xf bound_ctrl:1
	s_nop 1
	v_add_f32_dpp v49, v49, v49 quad_perm:[2,3,0,1] row_mask:0xf bank_mask:0xf bound_ctrl:1
	s_nop 1
	v_add_f32_dpp v49, v49, v49 row_half_mirror row_mask:0xf bank_mask:0xf bound_ctrl:1
	s_nop 1
	v_add_f32_dpp v49, v49, v49 row_mirror row_mask:0xf bank_mask:0xf bound_ctrl:1
	v_cvt_i32_f32_e32 v49, v49
	s_nop 0
	v_readlane_b32 s3, v49, 0
	v_readlane_b32 s4, v49, 16
	v_readlane_b32 s5, v49, 32
	v_readlane_b32 s6, v49, 48
	s_and_saveexec_b64 s[12:13], s[0:1]
	s_cbranch_execz .LBB0_1086
	s_add_i32 s3, s4, s3
	s_add_i32 s3, s3, s5
	s_add_i32 s3, s3, s6
	v_cvt_f32_i32_e32 v49, s3
	v_mov_b32_e32 v50, s19
	ds_write_b32 v50, v49
	s_branch .LBB0_1086

.LBB0_1165:
	s_or_b64 exec, exec, s[34:35]
	s_waitcnt vmcnt(0)
	ds_write2st64_b32 v217, v130, v131 offset1:8
	s_waitcnt vmcnt(0) lgkmcnt(0)
	s_barrier
	v_or_b32_e32 v188, s2, v193
	v_ashrrev_i32_e32 v189, 31, v188
	s_and_saveexec_b64 s[2:3], s[96:97]
	s_xor_b64 s[34:35], exec, s[2:3]
	s_andn2_saveexec_b64 s[34:35], s[34:35]
	s_cbranch_execz .LBB0_1167
	s_ashr_i32 s23, s22, 31
	v_readlane_b32 s60, v252, 48
	s_lshl_b64 s[2:3], s[22:23], 2
	v_cndmask_b32_e64 v130, 2, 0, s[46:47]
	v_readlane_b32 s61, v252, 49
	v_or_b32_e32 v132, s2, v130
	s_mov_b32 s2, 0xb000
	v_mov_b64_e32 v[130:131], s[60:61]
	v_mad_u64_u32 v[130:131], s[60:61], v132, s2, v[130:131]
	v_mov_b32_e32 v132, 0xb000
	v_mad_i32_i24 v131, s3, v132, v131
	v_lshl_add_u64 v[134:135], v[188:189], 2, v[130:131]
	v_cndmask_b32_e64 v133, v87, v129, s[46:47]
	v_cndmask_b32_e64 v132, v86, v128, s[46:47]
	v_cndmask_b32_e64 v131, v85, v127, s[46:47]
	v_cndmask_b32_e64 v130, v84, v126, s[46:47]
	v_add_co_u32_e32 v136, vcc, s2, v134
	global_store_dwordx4 v[134:135], v[130:133], off sc1
	s_nop 0
	v_addc_co_u32_e32 v137, vcc, 0, v135, vcc
	v_cndmask_b32_e64 v133, v83, v125, s[46:47]
	v_cndmask_b32_e64 v132, v82, v124, s[46:47]
	v_cndmask_b32_e64 v131, v81, v123, s[46:47]
	v_cndmask_b32_e64 v130, v80, v122, s[46:47]
	global_store_dwordx4 v[136:137], v[130:133], off sc1
	s_movk_i32 s2, 0x5000
	s_nop 0
	v_cndmask_b32_e64 v133, v19, v59, s[46:47]
	v_cndmask_b32_e64 v132, v18, v58, s[46:47]
	v_cndmask_b32_e64 v131, v17, v57, s[46:47]
	v_cndmask_b32_e64 v130, v16, v56, s[46:47]
	global_store_dwordx4 v[134:135], v[130:133], off offset:16 sc1
	s_nop 1
	v_cndmask_b32_e64 v133, v23, v55, s[46:47]
	v_cndmask_b32_e64 v132, v22, v54, s[46:47]
	v_cndmask_b32_e64 v131, v21, v53, s[46:47]
	v_cndmask_b32_e64 v130, v20, v52, s[46:47]
	global_store_dwordx4 v[136:137], v[130:133], off offset:16 sc1
	v_add_co_u32_e32 v136, vcc, s2, v134
	s_mov_b32 s2, 0x10000
	s_nop 0
	v_addc_co_u32_e32 v137, vcc, 0, v135, vcc
	v_cndmask_b32_e64 v133, v71, v113, s[46:47]
	v_cndmask_b32_e64 v132, v70, v112, s[46:47]
	v_cndmask_b32_e64 v131, v69, v111, s[46:47]
	v_cndmask_b32_e64 v130, v68, v110, s[46:47]
	v_add_co_u32_e32 v134, vcc, s2, v134
	global_store_dwordx4 v[136:137], v[130:133], off offset:2048 sc1
	s_nop 0
	v_addc_co_u32_e32 v135, vcc, 0, v135, vcc
	v_cndmask_b32_e64 v133, v67, v109, s[46:47]
	v_cndmask_b32_e64 v132, v66, v108, s[46:47]
	v_cndmask_b32_e64 v131, v65, v107, s[46:47]
	v_cndmask_b32_e64 v130, v64, v106, s[46:47]
	global_store_dwordx4 v[134:135], v[130:133], off offset:2048 sc1
	s_nop 1
	v_cndmask_b32_e64 v133, v3, v43, s[46:47]
	v_cndmask_b32_e64 v132, v2, v42, s[46:47]
	v_cndmask_b32_e64 v131, v1, v41, s[46:47]
	v_cndmask_b32_e64 v130, v0, v40, s[46:47]
	global_store_dwordx4 v[136:137], v[130:133], off offset:2064 sc1
	s_nop 1
	v_cndmask_b32_e64 v133, v7, v39, s[46:47]
	v_cndmask_b32_e64 v132, v6, v38, s[46:47]
	v_cndmask_b32_e64 v131, v5, v37, s[46:47]
	v_cndmask_b32_e64 v130, v4, v36, s[46:47]
	global_store_dwordx4 v[134:135], v[130:133], off offset:2064 sc1

.LBB0_1179:
	s_waitcnt lgkmcnt(5)
	v_cndmask_b32_e64 v78, v78, v140, s[48:49]
	v_cndmask_b32_e64 v79, v79, v141, s[48:49]
	v_pk_mul_f32 v[78:79], v[102:103], v[78:79]
	v_cndmask_b32_e64 v94, v94, v138, s[48:49]
	v_pk_fma_f32 v[78:79], v[58:59], v[128:129], v[78:79]
	v_cndmask_b32_e64 v95, v95, v139, s[48:49]
	v_pk_fma_f32 v[78:79], v[54:55], v[120:121], v[78:79]
	v_pk_mul_f32 v[94:95], v[100:101], v[94:95]
	v_pk_add_f32 v[116:117], v[124:125], v[78:79]
	v_pk_fma_f32 v[94:95], v[56:57], v[126:127], v[94:95]
	v_mul_f32_e32 v78, 0xbfb8aa3b, v116
	v_exp_f32_e32 v78, v78
	v_mul_f32_e32 v79, 0xbfb8aa3b, v117
	v_exp_f32_e32 v79, v79
	v_pk_fma_f32 v[94:95], v[52:53], v[118:119], v[94:95]
	v_add_f32_e32 v78, 1.0, v78
	v_pk_add_f32 v[108:109], v[122:123], v[94:95]
	v_rcp_f32_e32 v142, v78
	v_mul_f32_e32 v94, 0xbfb8aa3b, v108
	v_exp_f32_e32 v94, v94
	v_mul_f32_e32 v95, 0xbfb8aa3b, v109
	v_add_f32_e32 v78, 1.0, v79
	v_mov_b32_e32 v79, v97
	v_exp_f32_e32 v95, v95
	v_add_f32_e32 v94, 1.0, v94
	v_mov_b32_dpp v79, v32 row_ror:1 row_mask:0xf bank_mask:0xf
	s_waitcnt lgkmcnt(0)
	v_cndmask_b32_e64 v134, v79, v134, s[48:49]
	v_mov_b32_e32 v79, v97
	v_mov_b32_e32 v105, v97
	v_rcp_f32_e32 v112, v94
	v_mov_b32_dpp v79, v33 row_ror:1 row_mask:0xf bank_mask:0xf
	v_cndmask_b32_e64 v135, v79, v135, s[48:49]
	v_mov_b32_e32 v79, v97
	v_add_f32_e32 v94, 1.0, v95
	v_mov_b32_dpp v105, v35 row_ror:1 row_mask:0xf bank_mask:0xf
	v_mov_b32_dpp v79, v34 row_ror:1 row_mask:0xf bank_mask:0xf
	v_rcp_f32_e32 v113, v94
	v_rcp_f32_e32 v143, v78
	ds_read_b128 v[138:141], v220 offset:48
	v_cndmask_b32_e64 v136, v79, v136, s[48:49]
	v_cndmask_b32_e64 v137, v105, v137, s[48:49]
	v_pk_mul_f32 v[136:137], v[88:89], v[136:137]
	v_pk_mul_f32 v[134:135], v[86:87], v[134:135]
	v_pk_fma_f32 v[136:137], v[42:43], v[92:93], v[136:137]
	v_pk_fma_f32 v[134:135], v[40:41], v[90:91], v[134:135]
	v_mov_b32_e32 v78, v97
	v_mov_b32_e32 v94, v97
	v_mov_b32_e32 v95, v97
	v_mov_b32_e32 v79, v97
	v_pk_fma_f32 v[136:137], v[38:39], v[84:85], v[136:137]
	v_pk_fma_f32 v[134:135], v[36:37], v[82:83], v[134:135]
	s_lshl_b32 s2, s22, 8
	v_mov_b32_dpp v78, v40 row_ror:15 row_mask:0xf bank_mask:0xf
	v_mov_b32_dpp v94, v41 row_ror:15 row_mask:0xf bank_mask:0xf
	v_mov_b32_dpp v95, v42 row_ror:15 row_mask:0xf bank_mask:0xf
	v_mov_b32_dpp v79, v43 row_ror:15 row_mask:0xf bank_mask:0xf
	v_pk_add_f32 v[134:135], v[66:67], v[134:135]
	v_pk_add_f32 v[136:137], v[68:69], v[136:137]
	v_pk_mul_f32 v[108:109], v[108:109], v[112:113]
	v_pk_mul_f32 v[112:113], v[116:117], v[142:143]
	v_pk_mul_f32 v[108:109], v[108:109], v[134:135]
	v_pk_mul_f32 v[112:113], v[112:113], v[136:137]
	v_cvt_pk_bf16_f32 v116, v108, v109
	s_nop 0
	v_cvt_pk_bf16_f32 v117, v112, v113
	s_and_saveexec_b64 s[22:23], s[50:51]
	s_movk_i32 s3, 0x2c00
	s_cbranch_execz .LBB0_1181
	v_add_u32_e32 v105, s2, v194
	v_mov_b64_e32 v[108:109], s[88:89]
	v_mad_i64_i32 v[108:109], s[34:35], v105, s3, v[108:109]
	v_lshl_add_u64 v[108:109], v[188:189], 1, v[108:109]
	global_store_dwordx4 v[108:109], v[114:117], off sc1
.LBB0_1181:
	s_or_b64 exec, exec, s[22:23]
	v_pk_mul_f32 v[108:109], v[54:55], v[128:129]
	v_pk_mul_f32 v[112:113], v[60:61], v[126:127]
	v_pk_fma_f32 v[58:59], v[58:59], v[102:103], v[108:109]
	s_waitcnt lgkmcnt(0)
	v_cndmask_b32_e64 v114, v78, v138, s[44:45]
	v_pk_fma_f32 v[58:59], v[62:63], v[120:121], v[58:59]
	v_cndmask_b32_e64 v115, v94, v139, s[44:45]
	v_pk_add_f32 v[58:59], v[124:125], v[58:59]
	v_cndmask_b32_e64 v78, v95, v140, s[44:45]
	v_mul_f32_e32 v105, 0xbfb8aa3b, v58
	v_exp_f32_e32 v105, v105
	v_mul_f32_e32 v108, 0xbfb8aa3b, v59
	v_exp_f32_e32 v109, v108
	v_pk_mul_f32 v[94:95], v[52:53], v[126:127]
	v_pk_fma_f32 v[52:53], v[52:53], v[100:101], v[112:113]
	v_add_f32_e32 v105, 1.0, v105
	v_pk_fma_f32 v[52:53], v[44:45], v[118:119], v[52:53]
	v_pk_fma_f32 v[56:57], v[56:57], v[100:101], v[94:95]
	v_pk_add_f32 v[52:53], v[122:123], v[52:53]
	v_rcp_f32_e32 v108, v105
	v_add_f32_e32 v105, 1.0, v109
	v_mul_f32_e32 v109, 0xbfb8aa3b, v52
	v_pk_fma_f32 v[56:57], v[60:61], v[118:119], v[56:57]
	v_exp_f32_e32 v112, v109
	v_mul_f32_e32 v109, 0xbfb8aa3b, v53
	v_pk_add_f32 v[56:57], v[122:123], v[56:57]
	v_exp_f32_e32 v113, v109
	v_mul_f32_e32 v94, 0xbfb8aa3b, v56
	v_mul_f32_e32 v95, 0xbfb8aa3b, v57
	v_exp_f32_e32 v94, v94
	v_exp_f32_e32 v95, v95
	v_rcp_f32_e32 v109, v105
	v_add_f32_e32 v105, 1.0, v112
	v_rcp_f32_e32 v116, v105
	v_add_f32_e32 v105, 1.0, v113
	v_pk_mul_f32 v[112:113], v[62:63], v[128:129]
	v_add_f32_e32 v94, 1.0, v94
	v_pk_fma_f32 v[54:55], v[54:55], v[102:103], v[112:113]
	v_add_f32_e32 v95, 1.0, v95
	v_pk_fma_f32 v[54:55], v[46:47], v[120:121], v[54:55]
	v_pk_mul_f32 v[44:45], v[44:45], v[126:127]
	v_rcp_f32_e32 v94, v94
	v_rcp_f32_e32 v95, v95
	v_pk_add_f32 v[54:55], v[124:125], v[54:55]
	v_cndmask_b32_e64 v75, v75, v131, s[44:45]
	v_cndmask_b32_e64 v74, v74, v130, s[44:45]
	v_pk_fma_f32 v[44:45], v[60:61], v[100:101], v[44:45]
	v_pk_mul_f32 v[46:47], v[46:47], v[128:129]
	v_mul_f32_e32 v112, 0xbfb8aa3b, v54
	v_pk_fma_f32 v[44:45], v[118:119], v[74:75], v[44:45]
	v_cndmask_b32_e64 v71, v71, v133, s[44:45]
	v_cndmask_b32_e64 v70, v70, v132, s[44:45]
	v_pk_fma_f32 v[46:47], v[62:63], v[102:103], v[46:47]
	v_pk_mul_f32 v[74:75], v[36:37], v[90:91]
	v_exp_f32_e32 v112, v112
	v_mul_f32_e32 v113, 0xbfb8aa3b, v55
	v_pk_fma_f32 v[46:47], v[120:121], v[70:71], v[46:47]
	v_pk_mul_f32 v[70:71], v[38:39], v[92:93]
	v_pk_fma_f32 v[40:41], v[40:41], v[86:87], v[74:75]
	v_exp_f32_e32 v113, v113
	v_pk_fma_f32 v[42:43], v[42:43], v[88:89], v[70:71]
	v_pk_fma_f32 v[40:41], v[48:49], v[82:83], v[40:41]
	v_pk_fma_f32 v[42:43], v[50:51], v[84:85], v[42:43]
	v_pk_add_f32 v[40:41], v[66:67], v[40:41]
	v_pk_mul_f32 v[56:57], v[56:57], v[94:95]
	v_pk_add_f32 v[42:43], v[68:69], v[42:43]
	v_pk_mul_f32 v[58:59], v[58:59], v[108:109]
	v_pk_mul_f32 v[40:41], v[56:57], v[40:41]
	v_rcp_f32_e32 v117, v105
	v_add_f32_e32 v105, 1.0, v112
	v_pk_mul_f32 v[42:43], v[58:59], v[42:43]
	v_cvt_pk_bf16_f32 v112, v40, v41
	v_or_b32_e32 v40, 1, v194
	v_rcp_f32_e32 v134, v105
	v_add_f32_e32 v105, 1.0, v113
	v_cvt_pk_bf16_f32 v113, v42, v43
	v_add_u32_e32 v42, s2, v40
	v_mov_b64_e32 v[40:41], s[88:89]
	v_mad_i64_i32 v[42:43], s[22:23], v42, s3, v[40:41]
	v_lshlrev_b64 v[70:71], 1, v[188:189]
	v_pk_mul_f32 v[56:57], v[48:49], v[90:91]
	v_pk_add_f32 v[44:45], v[122:123], v[44:45]
	v_pk_add_f32 v[46:47], v[124:125], v[46:47]
	v_lshl_add_u64 v[42:43], v[42:43], 0, v[70:71]
	v_pk_fma_f32 v[36:37], v[36:37], v[86:87], v[56:57]
	v_mul_f32_e32 v60, 0xbfb8aa3b, v44
	v_mul_f32_e32 v61, 0xbfb8aa3b, v45
	v_mul_f32_e32 v62, 0xbfb8aa3b, v46
	v_mul_f32_e32 v63, 0xbfb8aa3b, v47
	global_store_dwordx4 v[42:43], v[110:113], off sc1
	v_pk_mul_f32 v[42:43], v[50:51], v[92:93]
	v_pk_fma_f32 v[36:37], v[32:33], v[82:83], v[36:37]
	v_exp_f32_e32 v60, v60
	v_exp_f32_e32 v61, v61
	v_exp_f32_e32 v62, v62
	v_exp_f32_e32 v63, v63
	v_pk_fma_f32 v[38:39], v[38:39], v[88:89], v[42:43]
	v_pk_add_f32 v[36:37], v[66:67], v[36:37]
	v_pk_mul_f32 v[42:43], v[52:53], v[116:117]
	v_rcp_f32_e32 v135, v105
	v_pk_mul_f32 v[36:37], v[42:43], v[36:37]
	v_add_f32_e32 v60, 1.0, v60
	v_cvt_pk_bf16_f32 v108, v36, v37
	v_or_b32_e32 v36, 2, v194
	v_add_u32_e32 v36, s2, v36
	v_add_f32_e32 v61, 1.0, v61
	v_add_f32_e32 v62, 1.0, v62
	v_add_f32_e32 v63, 1.0, v63
	v_pk_fma_f32 v[38:39], v[34:35], v[84:85], v[38:39]
	v_mad_i64_i32 v[36:37], s[22:23], v36, s3, v[40:41]
	v_rcp_f32_e32 v60, v60
	v_rcp_f32_e32 v61, v61
	v_rcp_f32_e32 v62, v62
	v_rcp_f32_e32 v63, v63
	v_pk_add_f32 v[38:39], v[68:69], v[38:39]
	v_pk_mul_f32 v[52:53], v[54:55], v[134:135]
	v_lshl_add_u64 v[36:37], v[36:37], 0, v[70:71]
	v_pk_mul_f32 v[38:39], v[52:53], v[38:39]
	v_pk_mul_f32 v[34:35], v[34:35], v[92:93]
	v_cvt_pk_bf16_f32 v109, v38, v39
	global_store_dwordx4 v[36:37], v[106:109], off sc1
	v_pk_mul_f32 v[32:33], v[32:33], v[90:91]
	v_cndmask_b32_e64 v79, v79, v141, s[44:45]
	v_pk_fma_f32 v[34:35], v[50:51], v[88:89], v[34:35]
	v_pk_fma_f32 v[32:33], v[48:49], v[86:87], v[32:33]
	v_pk_fma_f32 v[34:35], v[84:85], v[78:79], v[34:35]
	v_pk_fma_f32 v[32:33], v[82:83], v[114:115], v[32:33]
	v_pk_add_f32 v[34:35], v[68:69], v[34:35]
	v_pk_add_f32 v[32:33], v[66:67], v[32:33]
	v_pk_mul_f32 v[36:37], v[44:45], v[60:61]
	v_pk_mul_f32 v[38:39], v[46:47], v[62:63]
	v_pk_mul_f32 v[32:33], v[36:37], v[32:33]
	v_pk_mul_f32 v[34:35], v[38:39], v[34:35]
	v_cvt_pk_bf16_f32 v100, v32, v33
	s_nop 0
	v_cvt_pk_bf16_f32 v101, v34, v35
	s_and_saveexec_b64 s[22:23], s[52:53]
	s_cbranch_execz .LBB0_1183
	v_or_b32_e32 v32, 3, v194
	v_add_u32_e32 v34, s2, v32
	v_mov_b64_e32 v[32:33], s[88:89]
	v_mad_i64_i32 v[32:33], s[34:35], v34, s3, v[32:33]
	v_lshl_add_u64 v[32:33], v[188:189], 1, v[32:33]
	global_store_dwordx4 v[32:33], v[98:101], off sc1

.LBB0_1187:
	s_waitcnt lgkmcnt(5)
	v_cndmask_b32_e64 v93, v99, v93, s[48:49]
	v_cndmask_b32_e64 v92, v98, v92, s[48:49]
	v_pk_mul_f32 v[92:93], v[60:61], v[92:93]
	v_cndmask_b32_e64 v83, v83, v95, s[48:49]
	v_pk_fma_f32 v[92:93], v[24:25], v[56:57], v[92:93]
	v_cndmask_b32_e64 v82, v82, v94, s[48:49]
	v_pk_fma_f32 v[92:93], v[28:29], v[48:49], v[92:93]
	v_pk_mul_f32 v[82:83], v[62:63], v[82:83]
	v_pk_add_f32 v[98:99], v[52:53], v[92:93]
	v_pk_fma_f32 v[82:83], v[26:27], v[58:59], v[82:83]
	v_mul_f32_e32 v92, 0xbfb8aa3b, v98
	v_exp_f32_e32 v92, v92
	v_mul_f32_e32 v93, 0xbfb8aa3b, v99
	v_exp_f32_e32 v93, v93
	v_pk_fma_f32 v[82:83], v[30:31], v[50:51], v[82:83]
	v_add_f32_e32 v92, 1.0, v92
	v_pk_add_f32 v[82:83], v[54:55], v[82:83]
	v_rcp_f32_e32 v100, v92
	v_add_f32_e32 v92, 1.0, v93
	v_mul_f32_e32 v93, 0xbfb8aa3b, v82
	v_exp_f32_e32 v93, v93
	v_mul_f32_e32 v94, 0xbfb8aa3b, v83
	v_rcp_f32_e32 v101, v92
	v_exp_f32_e32 v95, v94
	v_add_f32_e32 v92, 1.0, v93
	v_mov_b32_e32 v93, v97
	v_mov_b32_e32 v104, v97
	v_rcp_f32_e32 v94, v92
	v_mov_b32_dpp v93, v4 row_ror:1 row_mask:0xf bank_mask:0xf
	s_waitcnt lgkmcnt(0)
	v_cndmask_b32_e64 v102, v93, v88, s[48:49]
	v_mov_b32_e32 v88, v97
	v_add_f32_e32 v92, 1.0, v95
	v_mov_b32_dpp v104, v7 row_ror:1 row_mask:0xf bank_mask:0xf
	v_mov_b32_dpp v88, v5 row_ror:1 row_mask:0xf bank_mask:0xf
	v_cndmask_b32_e64 v103, v88, v89, s[48:49]
	v_mov_b32_e32 v88, v97
	v_rcp_f32_e32 v95, v92
	v_cndmask_b32_e64 v91, v104, v91, s[48:49]
	v_mov_b32_dpp v88, v6 row_ror:1 row_mask:0xf bank_mask:0xf
	v_cndmask_b32_e64 v90, v88, v90, s[48:49]
	v_pk_mul_f32 v[90:91], v[46:47], v[90:91]
	v_pk_mul_f32 v[102:103], v[44:45], v[102:103]
	v_pk_fma_f32 v[90:91], v[14:15], v[42:43], v[90:91]
	v_pk_fma_f32 v[102:103], v[12:13], v[40:41], v[102:103]
	v_pk_fma_f32 v[90:91], v[10:11], v[38:39], v[90:91]
	v_pk_fma_f32 v[102:103], v[8:9], v[36:37], v[102:103]
	v_mov_b32_e32 v92, v97
	v_mov_b32_e32 v93, v97
	v_mov_b32_e32 v89, v97
	v_mov_b32_e32 v88, v97
	v_pk_add_f32 v[102:103], v[32:33], v[102:103]
	v_pk_add_f32 v[90:91], v[34:35], v[90:91]
	v_pk_mul_f32 v[98:99], v[98:99], v[100:101]
	v_pk_mul_f32 v[82:83], v[82:83], v[94:95]
	v_mov_b32_dpp v92, v12 row_ror:15 row_mask:0xf bank_mask:0xf
	v_mov_b32_dpp v93, v13 row_ror:15 row_mask:0xf bank_mask:0xf
	v_mov_b32_dpp v89, v14 row_ror:15 row_mask:0xf bank_mask:0xf
	v_mov_b32_dpp v88, v15 row_ror:15 row_mask:0xf bank_mask:0xf
	v_pk_mul_f32 v[90:91], v[82:83], v[90:91]
	v_pk_mul_f32 v[82:83], v[98:99], v[102:103]
	s_nop 0
	v_cvt_pk_bf16_f32 v82, v82, v83
	v_cvt_pk_bf16_f32 v83, v90, v91
	s_and_saveexec_b64 s[22:23], s[54:55]
	s_cbranch_execz .LBB0_1189
	v_add_u32_e32 v90, 0x80, v194
	v_add_u32_e32 v94, s2, v90
	v_mov_b64_e32 v[90:91], s[88:89]
	v_mad_i64_i32 v[90:91], s[34:35], v94, s3, v[90:91]
	v_lshl_add_u64 v[90:91], v[188:189], 1, v[90:91]
	global_store_dwordx4 v[90:91], v[80:83], off sc1
.LBB0_1189:
	s_or_b64 exec, exec, s[22:23]
	s_nop 0
	v_cndmask_b32_e64 v80, v92, v84, s[44:45]
	v_cndmask_b32_e64 v81, v93, v85, s[44:45]
	v_pk_mul_f32 v[84:85], v[28:29], v[56:57]
	v_cndmask_b32_e64 v82, v89, v86, s[44:45]
	v_pk_fma_f32 v[24:25], v[24:25], v[60:61], v[84:85]
	v_pk_mul_f32 v[90:91], v[18:19], v[58:59]
	v_pk_fma_f32 v[24:25], v[16:17], v[48:49], v[24:25]
	v_cndmask_b32_e64 v66, v78, v66, s[44:45]
	v_pk_add_f32 v[24:25], v[52:53], v[24:25]
	v_cndmask_b32_e64 v67, v79, v67, s[44:45]
	v_mul_f32_e32 v83, 0xbfb8aa3b, v24
	v_exp_f32_e32 v84, v83
	v_mul_f32_e32 v83, 0xbfb8aa3b, v25
	v_exp_f32_e32 v85, v83
	v_cndmask_b32_e64 v83, v88, v87, s[44:45]
	v_pk_mul_f32 v[86:87], v[30:31], v[58:59]
	v_pk_mul_f32 v[88:89], v[16:17], v[56:57]
	v_pk_fma_f32 v[26:27], v[26:27], v[62:63], v[86:87]
	v_pk_fma_f32 v[28:29], v[28:29], v[60:61], v[88:89]
	v_pk_fma_f32 v[26:27], v[18:19], v[50:51], v[26:27]
	v_pk_fma_f32 v[28:29], v[20:21], v[48:49], v[28:29]
	v_pk_add_f32 v[26:27], v[54:55], v[26:27]
	v_pk_fma_f32 v[30:31], v[30:31], v[62:63], v[90:91]
	v_mul_f32_e32 v86, 0xbfb8aa3b, v26
	v_mul_f32_e32 v87, 0xbfb8aa3b, v27
	v_exp_f32_e32 v86, v86
	v_exp_f32_e32 v87, v87
	v_pk_mul_f32 v[20:21], v[20:21], v[56:57]
	v_add_f32_e32 v84, 1.0, v84
	v_add_f32_e32 v85, 1.0, v85
	v_pk_fma_f32 v[30:31], v[22:23], v[50:51], v[30:31]
	v_pk_fma_f32 v[16:17], v[16:17], v[60:61], v[20:21]
	v_pk_mul_f32 v[22:23], v[22:23], v[58:59]
	v_rcp_f32_e32 v84, v84
	v_rcp_f32_e32 v85, v85
	v_add_f32_e32 v86, 1.0, v86
	v_add_f32_e32 v87, 1.0, v87
	v_pk_add_f32 v[28:29], v[52:53], v[28:29]
	v_pk_fma_f32 v[16:17], v[48:49], v[66:67], v[16:17]
	v_cndmask_b32_e64 v48, v74, v68, s[44:45]
	v_cndmask_b32_e64 v49, v75, v69, s[44:45]
	v_pk_fma_f32 v[18:19], v[18:19], v[62:63], v[22:23]
	v_rcp_f32_e32 v86, v86
	v_mul_f32_e32 v88, 0xbfb8aa3b, v28
	v_mul_f32_e32 v89, 0xbfb8aa3b, v29
	v_rcp_f32_e32 v87, v87
	v_pk_fma_f32 v[18:19], v[50:51], v[48:49], v[18:19]
	v_pk_mul_f32 v[50:51], v[8:9], v[40:41]
	v_exp_f32_e32 v88, v88
	v_exp_f32_e32 v89, v89
	v_pk_mul_f32 v[48:49], v[10:11], v[42:43]
	v_pk_fma_f32 v[12:13], v[12:13], v[44:45], v[50:51]
	v_pk_fma_f32 v[14:15], v[14:15], v[46:47], v[48:49]
	v_pk_fma_f32 v[12:13], v[0:1], v[36:37], v[12:13]
	v_pk_add_f32 v[30:31], v[54:55], v[30:31]
	v_pk_fma_f32 v[14:15], v[2:3], v[38:39], v[14:15]
	v_pk_add_f32 v[12:13], v[32:33], v[12:13]
	v_pk_mul_f32 v[24:25], v[24:25], v[84:85]
	v_mul_f32_e32 v90, 0xbfb8aa3b, v30
	v_mul_f32_e32 v91, 0xbfb8aa3b, v31
	v_pk_add_f32 v[14:15], v[34:35], v[14:15]
	v_pk_mul_f32 v[26:27], v[26:27], v[86:87]
	v_pk_mul_f32 v[12:13], v[24:25], v[12:13]
	v_add_f32_e32 v88, 1.0, v88
	v_add_f32_e32 v89, 1.0, v89
	v_exp_f32_e32 v90, v90
	v_exp_f32_e32 v91, v91
	v_pk_mul_f32 v[14:15], v[26:27], v[14:15]
	v_cvt_pk_bf16_f32 v78, v12, v13
	v_add_u32_e32 v12, 0x81, v194
	v_rcp_f32_e32 v88, v88
	v_rcp_f32_e32 v89, v89
	v_cvt_pk_bf16_f32 v79, v14, v15
	v_add_u32_e32 v14, s2, v12
	v_mov_b64_e32 v[12:13], s[88:89]
	v_pk_add_f32 v[16:17], v[52:53], v[16:17]
	v_pk_add_f32 v[18:19], v[54:55], v[18:19]
	v_mad_i64_i32 v[14:15], s[22:23], v14, s3, v[12:13]
	v_pk_mul_f32 v[24:25], v[0:1], v[40:41]
	v_mul_f32_e32 v20, 0xbfb8aa3b, v16
	v_mul_f32_e32 v21, 0xbfb8aa3b, v17
	v_mul_f32_e32 v22, 0xbfb8aa3b, v18
	v_mul_f32_e32 v23, 0xbfb8aa3b, v19
	v_lshl_add_u64 v[14:15], v[14:15], 0, v[70:71]
	v_pk_fma_f32 v[8:9], v[8:9], v[44:45], v[24:25]
	v_add_f32_e32 v90, 1.0, v90
	v_add_f32_e32 v91, 1.0, v91
	v_exp_f32_e32 v20, v20
	v_exp_f32_e32 v21, v21
	v_exp_f32_e32 v22, v22
	v_exp_f32_e32 v23, v23
	global_store_dwordx4 v[14:15], v[76:79], off sc1
	v_pk_mul_f32 v[14:15], v[2:3], v[42:43]
	v_pk_fma_f32 v[8:9], v[4:5], v[36:37], v[8:9]
	v_rcp_f32_e32 v90, v90
	v_rcp_f32_e32 v91, v91
	v_pk_fma_f32 v[10:11], v[10:11], v[46:47], v[14:15]
	v_pk_add_f32 v[8:9], v[32:33], v[8:9]
	v_pk_mul_f32 v[14:15], v[28:29], v[88:89]
	v_add_f32_e32 v20, 1.0, v20
	v_pk_mul_f32 v[8:9], v[14:15], v[8:9]
	v_add_f32_e32 v21, 1.0, v21
	v_cvt_pk_bf16_f32 v74, v8, v9
	v_add_u32_e32 v8, s2, v195
	v_add_f32_e32 v22, 1.0, v22
	v_add_f32_e32 v23, 1.0, v23
	v_pk_fma_f32 v[10:11], v[6:7], v[38:39], v[10:11]
	v_mad_i64_i32 v[8:9], s[22:23], v8, s3, v[12:13]
	v_rcp_f32_e32 v20, v20
	v_rcp_f32_e32 v21, v21
	v_rcp_f32_e32 v22, v22
	v_rcp_f32_e32 v23, v23
	v_pk_add_f32 v[10:11], v[34:35], v[10:11]
	v_pk_mul_f32 v[24:25], v[30:31], v[90:91]
	v_lshl_add_u64 v[8:9], v[8:9], 0, v[70:71]
	v_pk_mul_f32 v[10:11], v[24:25], v[10:11]
	v_pk_mul_f32 v[6:7], v[6:7], v[42:43]
	v_cvt_pk_bf16_f32 v75, v10, v11
	global_store_dwordx4 v[8:9], v[72:75], off sc1
	v_pk_mul_f32 v[4:5], v[4:5], v[40:41]
	v_pk_fma_f32 v[2:3], v[2:3], v[46:47], v[6:7]
	v_pk_fma_f32 v[0:1], v[0:1], v[44:45], v[4:5]
	v_pk_fma_f32 v[2:3], v[38:39], v[82:83], v[2:3]
	v_pk_fma_f32 v[0:1], v[36:37], v[80:81], v[0:1]
	v_pk_add_f32 v[2:3], v[34:35], v[2:3]
	v_pk_add_f32 v[0:1], v[32:33], v[0:1]
	v_pk_mul_f32 v[4:5], v[16:17], v[20:21]
	v_pk_mul_f32 v[6:7], v[18:19], v[22:23]
	v_pk_mul_f32 v[0:1], v[4:5], v[0:1]
	v_pk_mul_f32 v[2:3], v[6:7], v[2:3]
	v_cvt_pk_bf16_f32 v66, v0, v1
	s_nop 0
	v_cvt_pk_bf16_f32 v67, v2, v3
	s_and_saveexec_b64 s[22:23], s[56:57]
	s_cbranch_execz .LBB0_1191
	v_add_u32_e32 v2, s2, v214
	v_mov_b64_e32 v[0:1], s[88:89]
	v_mad_i64_i32 v[0:1], s[2:3], v2, s3, v[0:1]
	v_lshl_add_u64 v[0:1], v[188:189], 1, v[0:1]
	global_store_dwordx4 v[0:1], v[64:67], off sc1

.LBB0_1336:
	s_ashr_i32 s13, s12, 31
	s_lshl_b64 s[2:3], s[12:13], 22
	v_readlane_b32 s12, v250, 6
	v_lshl_or_b32 v140, s36, 8, v138
	v_readlane_b32 s13, v250, 7
	s_add_u32 s2, s12, s2
	v_lshl_add_u32 v142, s20, 8, v137
	s_addc_u32 s3, s13, s3
	v_ashrrev_i32_e32 v141, 31, v140
	v_ashrrev_i32_e32 v143, 31, v142
	v_lshl_add_u64 v[140:141], v[140:141], 2, s[2:3]
	v_lshlrev_b64 v[144:145], 13, v[142:143]
	v_lshl_add_u64 v[144:145], v[140:141], 0, v[144:145]
	global_store_dwordx4 v[144:145], v[126:129], off sc1
	global_store_dwordx4 v[144:145], v[122:125], off offset:64 sc1
	global_store_dwordx4 v[144:145], v[110:113], off offset:512 sc1
	global_store_dwordx4 v[144:145], v[102:105], off offset:576 sc1
	s_mov_b64 s[2:3], 0x100000
	s_nop 0
	v_or_b32_e32 v102, 16, v142
	v_ashrrev_i32_e32 v103, 31, v102
	v_lshlrev_b64 v[102:103], 13, v[102:103]
	v_lshl_add_u64 v[102:103], v[140:141], 0, v[102:103]
	global_store_dwordx4 v[102:103], v[118:121], off sc1
	global_store_dwordx4 v[102:103], v[114:117], off offset:64 sc1
	global_store_dwordx4 v[102:103], v[92:95], off offset:512 sc1
	global_store_dwordx4 v[102:103], v[84:87], off offset:576 sc1
	s_nop 1
	v_or_b32_e32 v84, 32, v142
	v_ashrrev_i32_e32 v85, 31, v84
	v_lshlrev_b64 v[84:85], 13, v[84:85]
	v_lshl_add_u64 v[84:85], v[140:141], 0, v[84:85]
	global_store_dwordx4 v[84:85], v[106:109], off sc1
	global_store_dwordx4 v[84:85], v[98:101], off offset:64 sc1
	global_store_dwordx4 v[84:85], v[76:79], off offset:512 sc1
	global_store_dwordx4 v[84:85], v[72:75], off offset:576 sc1
	s_nop 1
	v_or_b32_e32 v72, 48, v142
	v_ashrrev_i32_e32 v73, 31, v72
	v_lshlrev_b64 v[72:73], 13, v[72:73]
	v_lshl_add_u64 v[72:73], v[140:141], 0, v[72:73]
	global_store_dwordx4 v[72:73], v[88:91], off sc1
	global_store_dwordx4 v[72:73], v[80:83], off offset:64 sc1
	global_store_dwordx4 v[72:73], v[68:71], off offset:512 sc1
	global_store_dwordx4 v[72:73], v[64:67], off offset:576 sc1
	s_nop 1
	v_lshl_add_u64 v[64:65], v[144:145], 0, s[2:3]
	s_mov_b32 s2, 0x100000
	v_add_co_u32_e32 v66, vcc, s2, v144
	s_mov_b64 s[2:3], 0x120000
	s_nop 0
	v_addc_co_u32_e32 v67, vcc, 0, v145, vcc
	global_store_dwordx4 v[66:67], v[60:63], off sc1
	global_store_dwordx4 v[64:65], v[56:59], off offset:64 sc1
	global_store_dwordx4 v[64:65], v[44:47], off offset:512 sc1
	global_store_dwordx4 v[64:65], v[40:43], off offset:576 sc1
	s_nop 1
	v_lshl_add_u64 v[40:41], v[144:145], 0, s[2:3]
	s_mov_b32 s2, 0x120000
	v_add_co_u32_e32 v42, vcc, s2, v144
	s_mov_b64 s[2:3], 0x140000
	s_nop 0
	v_addc_co_u32_e32 v43, vcc, 0, v145, vcc
	global_store_dwordx4 v[42:43], v[52:55], off sc1
	global_store_dwordx4 v[40:41], v[48:51], off offset:64 sc1
	global_store_dwordx4 v[40:41], v[28:31], off offset:512 sc1
	global_store_dwordx4 v[40:41], v[24:27], off offset:576 sc1
	s_nop 1
	v_lshl_add_u64 v[24:25], v[144:145], 0, s[2:3]
	s_mov_b32 s2, 0x140000
	v_add_co_u32_e32 v26, vcc, s2, v144
	s_mov_b64 s[2:3], 0x160000
	s_nop 0
	v_addc_co_u32_e32 v27, vcc, 0, v145, vcc
	global_store_dwordx4 v[26:27], v[36:39], off sc1
	global_store_dwordx4 v[24:25], v[32:35], off offset:64 sc1
	global_store_dwordx4 v[24:25], v[12:15], off offset:512 sc1
	global_store_dwordx4 v[24:25], v[8:11], off offset:576 sc1
	s_nop 1
	v_add_co_u32_e32 v10, vcc, 0x160000, v144
	v_lshl_add_u64 v[8:9], v[144:145], 0, s[2:3]
	s_nop 0
	v_addc_co_u32_e32 v11, vcc, 0, v145, vcc
	s_and_b64 vcc, exec, s[0:1]
	s_mov_b64 s[0:1], -1
	global_store_dwordx4 v[10:11], v[20:23], off sc1
	global_store_dwordx4 v[8:9], v[16:19], off offset:64 sc1
	global_store_dwordx4 v[8:9], v[4:7], off offset:512 sc1
	global_store_dwordx4 v[8:9], v[0:3], off offset:576 sc1
	s_cbranch_vccnz .LBB0_1325
	s_andn2_b64 vcc, exec, s[10:11]
	s_cbranch_vccnz .LBB0_1324
	s_barrier
	s_branch .LBB0_1324

.LBB0_1385:
	s_or_b64 exec, exec, s[8:9]
	s_mov_b64 s[2:3], 0x20000
	v_ashrrev_i32_e32 v149, 31, v148
	v_lshlrev_b64 v[134:135], 13, v[148:149]
	v_lshl_add_u64 v[134:135], s[96:97], 0, v[134:135]
	v_lshl_add_u64 v[134:135], v[162:163], 2, v[134:135]
	v_mov_b64_e32 v[136:137], v[134:135]
	flat_store_dwordx4 v[136:137], v[110:113] sc1
	flat_store_dwordx4 v[136:137], v[106:109] offset:16 sc1
	flat_store_dwordx4 v[136:137], v[4:7] offset:512 sc1
	flat_store_dwordx4 v[136:137], v[0:3] offset:528 sc1
	v_lshl_add_u64 v[136:137], v[134:135], 0, s[2:3]
	s_mov_b64 s[2:3], 0x40000
	flat_store_dwordx4 v[136:137], v[118:121] sc1
	flat_store_dwordx4 v[136:137], v[114:117] offset:16 sc1
	flat_store_dwordx4 v[136:137], v[12:15] offset:512 sc1
	flat_store_dwordx4 v[136:137], v[8:11] offset:528 sc1
	v_lshl_add_u64 v[136:137], v[134:135], 0, s[2:3]
	s_mov_b64 s[2:3], 0x60000
	flat_store_dwordx4 v[136:137], v[126:129] sc1
	flat_store_dwordx4 v[136:137], v[122:125] offset:16 sc1
	flat_store_dwordx4 v[136:137], v[24:27] offset:512 sc1
	flat_store_dwordx4 v[136:137], v[20:23] offset:528 sc1
	v_lshl_add_u64 v[136:137], v[134:135], 0, s[2:3]
	s_mov_b64 s[2:3], 0x100000
	flat_store_dwordx4 v[136:137], v[92:95] sc1
	flat_store_dwordx4 v[136:137], v[88:91] offset:16 sc1
	flat_store_dwordx4 v[136:137], v[40:43] offset:512 sc1
	flat_store_dwordx4 v[136:137], v[36:39] offset:528 sc1
	v_lshl_add_u64 v[136:137], v[134:135], 0, s[2:3]
	s_mov_b64 s[2:3], 0x120000
	flat_store_dwordx4 v[136:137], v[102:105] sc1
	flat_store_dwordx4 v[136:137], v[98:101] offset:16 sc1
	flat_store_dwordx4 v[136:137], v[60:63] offset:512 sc1
	flat_store_dwordx4 v[136:137], v[56:59] offset:528 sc1
	v_lshl_add_u64 v[136:137], v[134:135], 0, s[2:3]
	s_mov_b64 s[2:3], 0x140000
	flat_store_dwordx4 v[136:137], v[84:87] sc1
	flat_store_dwordx4 v[136:137], v[80:83] offset:16 sc1
	flat_store_dwordx4 v[136:137], v[76:79] offset:512 sc1
	flat_store_dwordx4 v[136:137], v[72:75] offset:528 sc1
	v_lshl_add_u64 v[136:137], v[134:135], 0, s[2:3]
	s_mov_b64 s[2:3], 0x160000
	v_lshl_add_u64 v[134:135], v[134:135], 0, s[2:3]
	flat_store_dwordx4 v[136:137], v[68:71] sc1
	flat_store_dwordx4 v[136:137], v[64:67] offset:16 sc1
	flat_store_dwordx4 v[136:137], v[52:55] offset:512 sc1
	flat_store_dwordx4 v[136:137], v[48:51] offset:528 sc1
	s_cmp_gt_u32 s40, 63
	flat_store_dwordx4 v[134:135], v[44:47] sc1
	flat_store_dwordx4 v[134:135], v[32:35] offset:16 sc1
	flat_store_dwordx4 v[134:135], v[28:31] offset:512 sc1
	flat_store_dwordx4 v[134:135], v[16:19] offset:528 sc1
	s_cbranch_scc1 .LBB0_1391
	s_lshl_b32 s8, s51, 4
	s_lshl_b32 s2, s60, 7
	s_ashr_i32 s9, s8, 31
	s_addk_i32 s2, 0x80
	s_lshl_b64 s[8:9], s[8:9], 2
	v_readlane_b32 s3, v252, 39
	s_add_u32 s8, s3, s8
	v_readlane_b32 s3, v252, 40
	s_addc_u32 s9, s3, s9
	s_mov_b32 s3, 0x100001
	s_branch .LBB0_1388

.LBB0_1393:
	s_or_b64 exec, exec, s[8:9]
	s_lshl_b32 s40, s60, 11
	s_lshl_b64 s[0:1], s[40:41], 2
	s_add_u32 s0, s46, s0
	s_addc_u32 s1, s47, s1
	s_add_u32 s0, s0, 0x2000
	s_addc_u32 s1, s1, 0
	v_readlane_b32 s2, v255, 2
	v_readlane_b32 s3, v255, 3
	s_add_u32 s2, s2, s12
	s_addc_u32 s3, s3, 0
	v_lshl_add_u64 v[148:149], s[2:3], 0, v[146:147]
	s_mov_b64 s[2:3], 0x26000
	v_lshl_add_u64 v[158:159], v[148:149], 0, s[2:3]
	s_mov_b64 s[2:3], 0x24000
	v_lshl_add_u64 v[174:175], v[148:149], 0, s[2:3]
	s_mov_b32 s2, 0x26000
	v_add_co_u32_e32 v138, vcc, s2, v148
	v_lshl_add_u64 v[134:135], s[0:1], 0, v[146:147]
	s_nop 0
	v_addc_co_u32_e32 v139, vcc, 0, v149, vcc
	global_load_dwordx4 v[130:133], v[134:135], off offset:16
	s_nop 0
	global_load_dwordx4 v[134:137], v[134:135], off
	s_nop 0
	global_load_dwordx4 v[138:141], v[138:139], off
	s_nop 0
	global_load_dwordx4 v[142:145], v[158:159], off offset:16
	s_mov_b32 s2, 0x24000
	v_lshl_add_u32 v96, v172, 2, 0
	s_waitcnt vmcnt(0)
	v_pk_add_f32 v[140:141], v[140:141], 1.0 op_sel_hi:[1,0]
	s_nop 0
	v_pk_mul_f32 v[168:169], v[136:137], v[140:141]
	v_pk_add_f32 v[136:137], v[142:143], 1.0 op_sel_hi:[1,0]
	v_pk_add_f32 v[138:139], v[138:139], 1.0 op_sel_hi:[1,0]
	v_pk_mul_f32 v[166:167], v[130:131], v[136:137]
	v_add_co_u32_e32 v130, vcc, s2, v148
	v_pk_mul_f32 v[170:171], v[134:135], v[138:139]
	s_nop 0
	v_addc_co_u32_e32 v131, vcc, 0, v149, vcc
	global_load_dwordx4 v[150:153], v[130:131], off
	global_load_dwordx4 v[154:157], v[174:175], off offset:16
	v_or_b32_e32 v130, 0x80, v162
	s_waitcnt lgkmcnt(0)
	s_barrier
	v_ashrrev_i32_e32 v131, 31, v130
	v_pk_add_f32 v[134:135], v[144:145], 1.0 op_sel_hi:[1,0]
	v_lshl_add_u64 v[130:131], v[130:131], 2, s[0:1]
	v_pk_mul_f32 v[164:165], v[132:133], v[134:135]
	global_load_dwordx4 v[138:141], v[130:131], off
	global_load_dwordx4 v[146:149], v[130:131], off offset:16
	global_load_dwordx4 v[142:145], v[158:159], off offset:512
	s_nop 0
	global_load_dwordx4 v[158:161], v[158:159], off offset:528
	s_nop 0
	global_load_dwordx4 v[130:133], v[174:175], off offset:528
	global_load_dwordx4 v[134:137], v[174:175], off offset:512
	ds_read_b32 v174, v96 offset:8192
	v_readlane_b32 s0, v253, 17
	v_readlane_b32 s1, v253, 18
	s_waitcnt lgkmcnt(0)
	v_pk_mul_f32 v[108:109], v[108:109], v[174:175] op_sel_hi:[1,0]
	v_pk_mul_f32 v[110:111], v[110:111], v[174:175] op_sel_hi:[1,0]
	v_pk_mul_f32 v[112:113], v[112:113], v[174:175] op_sel_hi:[1,0]
	v_pk_mul_f32 v[106:107], v[106:107], v[174:175] op_sel_hi:[1,0]
	s_waitcnt vmcnt(7)
	v_pk_fma_f32 v[112:113], v[168:169], v[112:113], v[152:153]
	s_waitcnt vmcnt(6)
	v_pk_fma_f32 v[108:109], v[164:165], v[108:109], v[156:157]
	v_pk_fma_f32 v[110:111], v[170:171], v[110:111], v[150:151]
	v_pk_fma_f32 v[106:107], v[166:167], v[106:107], v[154:155]
	v_cvt_pk_bf16_f32 v174, v110, v111
	v_cvt_pk_bf16_f32 v175, v112, v113
	v_add_u32_e32 v110, s5, v172
	v_cvt_pk_bf16_f32 v176, v106, v107
	v_cvt_pk_bf16_f32 v177, v108, v109
	ds_read_b32 v108, v96 offset:8256
	v_ashrrev_i32_e32 v111, 31, v110
	v_lshlrev_b64 v[106:107], 12, v[110:111]
	v_lshl_add_u64 v[106:107], s[0:1], 0, v[106:107]
	v_lshlrev_b64 v[112:113], 1, v[162:163]
	s_waitcnt lgkmcnt(0)
	v_pk_mul_f32 v[118:119], v[118:119], v[108:109] op_sel_hi:[1,0]
	v_pk_mul_f32 v[120:121], v[120:121], v[108:109] op_sel_hi:[1,0]
	v_pk_mul_f32 v[114:115], v[114:115], v[108:109] op_sel_hi:[1,0]
	v_pk_mul_f32 v[108:109], v[116:117], v[108:109] op_sel_hi:[1,0]
	v_lshl_add_u64 v[106:107], v[106:107], 0, v[112:113]
	v_pk_fma_f32 v[108:109], v[164:165], v[108:109], v[156:157]
	v_pk_fma_f32 v[116:117], v[166:167], v[114:115], v[154:155]
	global_store_dwordx4 v[106:107], v[174:177], off sc1
	v_pk_fma_f32 v[120:121], v[168:169], v[120:121], v[152:153]
	v_pk_fma_f32 v[118:119], v[170:171], v[118:119], v[150:151]
	s_nop 0
	v_cvt_pk_bf16_f32 v114, v118, v119
	v_cvt_pk_bf16_f32 v115, v120, v121
	v_cvt_pk_bf16_f32 v116, v116, v117
	v_cvt_pk_bf16_f32 v117, v108, v109
	v_add_u32_e32 v108, 16, v110
	v_ashrrev_i32_e32 v109, 31, v108
	v_lshlrev_b64 v[108:109], 12, v[108:109]
	v_lshl_add_u64 v[108:109], s[0:1], 0, v[108:109]
	v_lshl_add_u64 v[108:109], v[108:109], 0, v[112:113]
	global_store_dwordx4 v[108:109], v[114:117], off sc1
	ds_read_b32 v114, v96 offset:8320
	s_waitcnt lgkmcnt(0)
	v_pk_mul_f32 v[118:119], v[128:129], v[114:115] op_sel_hi:[1,0]
	v_pk_mul_f32 v[116:117], v[126:127], v[114:115] op_sel_hi:[1,0]
	v_pk_mul_f32 v[120:121], v[122:123], v[114:115] op_sel_hi:[1,0]
	v_pk_mul_f32 v[114:115], v[124:125], v[114:115] op_sel_hi:[1,0]
	v_pk_fma_f32 v[118:119], v[168:169], v[118:119], v[152:153]
	v_pk_fma_f32 v[116:117], v[170:171], v[116:117], v[150:151]
	v_pk_fma_f32 v[114:115], v[164:165], v[114:115], v[156:157]
	v_pk_fma_f32 v[120:121], v[166:167], v[120:121], v[154:155]
	v_cvt_pk_bf16_f32 v116, v116, v117
	v_cvt_pk_bf16_f32 v117, v118, v119
	s_nop 0
	v_cvt_pk_bf16_f32 v118, v120, v121
	v_cvt_pk_bf16_f32 v119, v114, v115
	v_add_u32_e32 v114, 32, v110
	v_ashrrev_i32_e32 v115, 31, v114
	v_lshlrev_b64 v[114:115], 12, v[114:115]
	v_lshl_add_u64 v[114:115], s[0:1], 0, v[114:115]
	v_lshl_add_u64 v[114:115], v[114:115], 0, v[112:113]
	global_store_dwordx4 v[114:115], v[116:119], off sc1
	ds_read_b32 v116, v96 offset:8384
	s_waitcnt lgkmcnt(0)
	v_pk_mul_f32 v[92:93], v[92:93], v[116:117] op_sel_hi:[1,0]
	v_pk_mul_f32 v[88:89], v[88:89], v[116:117] op_sel_hi:[1,0]
	v_pk_mul_f32 v[94:95], v[94:95], v[116:117] op_sel_hi:[1,0]
	v_pk_fma_f32 v[92:93], v[170:171], v[92:93], v[150:151]
	v_pk_mul_f32 v[90:91], v[90:91], v[116:117] op_sel_hi:[1,0]
	v_pk_fma_f32 v[88:89], v[166:167], v[88:89], v[154:155]
	v_pk_fma_f32 v[94:95], v[168:169], v[94:95], v[152:153]
	v_pk_fma_f32 v[116:117], v[164:165], v[90:91], v[156:157]
	v_cvt_pk_bf16_f32 v90, v92, v93
	v_cvt_pk_bf16_f32 v91, v94, v95
	v_cvt_pk_bf16_f32 v92, v88, v89
	v_add_u32_e32 v88, 48, v110
	v_ashrrev_i32_e32 v89, 31, v88
	v_lshlrev_b64 v[88:89], 12, v[88:89]
	v_lshl_add_u64 v[88:89], s[0:1], 0, v[88:89]
	v_lshl_add_u64 v[88:89], v[88:89], 0, v[112:113]
	v_cvt_pk_bf16_f32 v93, v116, v117
	global_store_dwordx4 v[88:89], v[90:93], off sc1
	ds_read_b32 v90, v96 offset:8704
	s_waitcnt lgkmcnt(0)
	v_pk_mul_f32 v[94:95], v[104:105], v[90:91] op_sel_hi:[1,0]
	v_pk_mul_f32 v[92:93], v[102:103], v[90:91] op_sel_hi:[1,0]
	v_pk_mul_f32 v[98:99], v[98:99], v[90:91] op_sel_hi:[1,0]
	v_pk_mul_f32 v[90:91], v[100:101], v[90:91] op_sel_hi:[1,0]
	v_pk_fma_f32 v[94:95], v[168:169], v[94:95], v[152:153]
	v_pk_fma_f32 v[92:93], v[170:171], v[92:93], v[150:151]
	v_pk_fma_f32 v[90:91], v[164:165], v[90:91], v[156:157]
	v_pk_fma_f32 v[98:99], v[166:167], v[98:99], v[154:155]
	v_cvt_pk_bf16_f32 v92, v92, v93
	v_cvt_pk_bf16_f32 v93, v94, v95
	s_nop 0
	v_cvt_pk_bf16_f32 v94, v98, v99
	v_cvt_pk_bf16_f32 v95, v90, v91
	v_add_u32_e32 v90, 0x80, v110
	v_ashrrev_i32_e32 v91, 31, v90
	v_lshlrev_b64 v[90:91], 12, v[90:91]
	v_lshl_add_u64 v[90:91], s[0:1], 0, v[90:91]
	v_lshl_add_u64 v[90:91], v[90:91], 0, v[112:113]
	global_store_dwordx4 v[90:91], v[92:95], off sc1
	ds_read_b32 v92, v96 offset:8768
	s_waitcnt lgkmcnt(0)
	v_pk_mul_f32 v[84:85], v[84:85], v[92:93] op_sel_hi:[1,0]
	v_pk_mul_f32 v[80:81], v[80:81], v[92:93] op_sel_hi:[1,0]
	v_pk_mul_f32 v[86:87], v[86:87], v[92:93] op_sel_hi:[1,0]
	v_pk_fma_f32 v[84:85], v[170:171], v[84:85], v[150:151]
	v_pk_mul_f32 v[82:83], v[82:83], v[92:93] op_sel_hi:[1,0]
	v_pk_fma_f32 v[80:81], v[166:167], v[80:81], v[154:155]
	v_pk_fma_f32 v[86:87], v[168:169], v[86:87], v[152:153]
	v_pk_fma_f32 v[92:93], v[164:165], v[82:83], v[156:157]
	v_cvt_pk_bf16_f32 v82, v84, v85
	v_cvt_pk_bf16_f32 v83, v86, v87
	v_cvt_pk_bf16_f32 v84, v80, v81
	v_add_u32_e32 v80, 0x90, v110
	v_ashrrev_i32_e32 v81, 31, v80
	v_lshlrev_b64 v[80:81], 12, v[80:81]
	v_lshl_add_u64 v[80:81], s[0:1], 0, v[80:81]
	v_lshl_add_u64 v[80:81], v[80:81], 0, v[112:113]
	v_cvt_pk_bf16_f32 v85, v92, v93
	global_store_dwordx4 v[80:81], v[82:85], off sc1
	ds_read_b32 v82, v96 offset:8832
	s_waitcnt lgkmcnt(0)
	v_pk_mul_f32 v[68:69], v[68:69], v[82:83] op_sel_hi:[1,0]
	v_pk_mul_f32 v[64:65], v[64:65], v[82:83] op_sel_hi:[1,0]
	v_pk_mul_f32 v[70:71], v[70:71], v[82:83] op_sel_hi:[1,0]
	v_pk_fma_f32 v[68:69], v[170:171], v[68:69], v[150:151]
	v_pk_mul_f32 v[66:67], v[66:67], v[82:83] op_sel_hi:[1,0]
	v_pk_fma_f32 v[64:65], v[166:167], v[64:65], v[154:155]
	v_pk_fma_f32 v[70:71], v[168:169], v[70:71], v[152:153]
	v_pk_fma_f32 v[82:83], v[164:165], v[66:67], v[156:157]
	v_cvt_pk_bf16_f32 v66, v68, v69
	v_cvt_pk_bf16_f32 v67, v70, v71
	v_cvt_pk_bf16_f32 v68, v64, v65
	v_add_u32_e32 v64, 0xa0, v110
	v_ashrrev_i32_e32 v65, 31, v64
	v_lshlrev_b64 v[64:65], 12, v[64:65]
	v_lshl_add_u64 v[64:65], s[0:1], 0, v[64:65]
	v_lshl_add_u64 v[64:65], v[64:65], 0, v[112:113]
	v_cvt_pk_bf16_f32 v69, v82, v83
	global_store_dwordx4 v[64:65], v[66:69], off sc1
	ds_read_b32 v66, v96 offset:8896
	s_waitcnt lgkmcnt(0)
	v_pk_mul_f32 v[44:45], v[44:45], v[66:67] op_sel_hi:[1,0]
	v_pk_mul_f32 v[46:47], v[46:47], v[66:67] op_sel_hi:[1,0]
	v_pk_mul_f32 v[32:33], v[32:33], v[66:67] op_sel_hi:[1,0]
	v_pk_fma_f32 v[46:47], v[168:169], v[46:47], v[152:153]
	v_pk_fma_f32 v[44:45], v[170:171], v[44:45], v[150:151]
	v_pk_fma_f32 v[32:33], v[166:167], v[32:33], v[154:155]
	v_cvt_pk_bf16_f32 v44, v44, v45
	v_cvt_pk_bf16_f32 v45, v46, v47
	v_pk_mul_f32 v[34:35], v[34:35], v[66:67] op_sel_hi:[1,0]
	v_cvt_pk_bf16_f32 v46, v32, v33
	v_add_u32_e32 v32, 0xb0, v110
	v_ashrrev_i32_e32 v33, 31, v32
	v_lshlrev_b64 v[32:33], 12, v[32:33]
	v_lshl_add_u64 v[32:33], s[0:1], 0, v[32:33]
	v_lshl_add_u64 v[32:33], v[32:33], 0, v[112:113]
	v_pk_fma_f32 v[34:35], v[164:165], v[34:35], v[156:157]
	s_waitcnt vmcnt(10)
	v_pk_add_f32 v[66:67], v[142:143], 1.0 op_sel_hi:[1,0]
	v_cvt_pk_bf16_f32 v47, v34, v35
	global_store_dwordx4 v[32:33], v[44:47], off sc1
	ds_read_b32 v68, v96 offset:8192
	s_waitcnt vmcnt(10)
	v_pk_add_f32 v[34:35], v[160:161], 1.0 op_sel_hi:[1,0]
	v_pk_add_f32 v[44:45], v[158:159], 1.0 op_sel_hi:[1,0]
	v_pk_mul_f32 v[34:35], v[148:149], v[34:35]
	v_pk_mul_f32 v[44:45], v[146:147], v[44:45]
	v_pk_add_f32 v[46:47], v[144:145], 1.0 op_sel_hi:[1,0]
	v_pk_mul_f32 v[66:67], v[138:139], v[66:67]
	s_waitcnt lgkmcnt(0)
	v_pk_mul_f32 v[4:5], v[4:5], v[68:69] op_sel_hi:[1,0]
	v_pk_mul_f32 v[0:1], v[0:1], v[68:69] op_sel_hi:[1,0]
	v_pk_mul_f32 v[2:3], v[2:3], v[68:69] op_sel_hi:[1,0]
	v_pk_mul_f32 v[46:47], v[140:141], v[46:47]
	v_pk_mul_f32 v[6:7], v[6:7], v[68:69] op_sel_hi:[1,0]
	s_waitcnt vmcnt(8)
	v_pk_fma_f32 v[4:5], v[66:67], v[4:5], v[134:135]
	v_pk_fma_f32 v[68:69], v[34:35], v[2:3], v[132:133]
	v_pk_fma_f32 v[2:3], v[44:45], v[0:1], v[130:131]
	v_cvt_pk_bf16_f32 v0, v4, v5
	v_pk_fma_f32 v[6:7], v[46:47], v[6:7], v[136:137]
	s_nop 0
	v_cvt_pk_bf16_f32 v1, v6, v7
	v_cvt_pk_bf16_f32 v2, v2, v3
	v_cvt_pk_bf16_f32 v3, v68, v69
	global_store_dwordx4 v[106:107], v[0:3], off offset:256 sc1
	ds_read_b32 v0, v96 offset:8256
	s_waitcnt lgkmcnt(0)
	v_pk_mul_f32 v[4:5], v[14:15], v[0:1] op_sel_hi:[1,0]
	v_pk_mul_f32 v[2:3], v[12:13], v[0:1] op_sel_hi:[1,0]
	v_pk_mul_f32 v[6:7], v[8:9], v[0:1] op_sel_hi:[1,0]
	v_pk_mul_f32 v[0:1], v[10:11], v[0:1] op_sel_hi:[1,0]
	v_pk_fma_f32 v[2:3], v[66:67], v[2:3], v[134:135]
	v_pk_fma_f32 v[8:9], v[34:35], v[0:1], v[132:133]
	v_cvt_pk_bf16_f32 v0, v2, v3
	v_pk_fma_f32 v[4:5], v[46:47], v[4:5], v[136:137]
	v_pk_fma_f32 v[6:7], v[44:45], v[6:7], v[130:131]
	v_cvt_pk_bf16_f32 v1, v4, v5
	s_nop 0
	v_cvt_pk_bf16_f32 v2, v6, v7
	v_cvt_pk_bf16_f32 v3, v8, v9
	global_store_dwordx4 v[108:109], v[0:3], off offset:256 sc1
	ds_read_b32 v0, v96 offset:8320
	s_waitcnt lgkmcnt(0)
	v_pk_mul_f32 v[4:5], v[26:27], v[0:1] op_sel_hi:[1,0]
	v_pk_mul_f32 v[2:3], v[24:25], v[0:1] op_sel_hi:[1,0]
	v_pk_mul_f32 v[6:7], v[20:21], v[0:1] op_sel_hi:[1,0]
	v_pk_mul_f32 v[0:1], v[22:23], v[0:1] op_sel_hi:[1,0]
	v_pk_fma_f32 v[2:3], v[66:67], v[2:3], v[134:135]
	v_pk_fma_f32 v[8:9], v[34:35], v[0:1], v[132:133]
	v_cvt_pk_bf16_f32 v0, v2, v3
	v_pk_fma_f32 v[4:5], v[46:47], v[4:5], v[136:137]
	v_pk_fma_f32 v[6:7], v[44:45], v[6:7], v[130:131]
	v_cvt_pk_bf16_f32 v1, v4, v5
	s_nop 0
	v_cvt_pk_bf16_f32 v2, v6, v7
	v_cvt_pk_bf16_f32 v3, v8, v9
	global_store_dwordx4 v[114:115], v[0:3], off offset:256 sc1
	ds_read_b32 v0, v96 offset:8384
	s_waitcnt lgkmcnt(0)
	v_pk_mul_f32 v[4:5], v[42:43], v[0:1] op_sel_hi:[1,0]
	v_pk_mul_f32 v[2:3], v[40:41], v[0:1] op_sel_hi:[1,0]
	v_pk_mul_f32 v[6:7], v[36:37], v[0:1] op_sel_hi:[1,0]
	v_pk_mul_f32 v[0:1], v[38:39], v[0:1] op_sel_hi:[1,0]
	v_pk_fma_f32 v[2:3], v[66:67], v[2:3], v[134:135]
	v_pk_fma_f32 v[8:9], v[34:35], v[0:1], v[132:133]
	v_cvt_pk_bf16_f32 v0, v2, v3
	v_pk_fma_f32 v[4:5], v[46:47], v[4:5], v[136:137]
	v_pk_fma_f32 v[6:7], v[44:45], v[6:7], v[130:131]
	v_cvt_pk_bf16_f32 v1, v4, v5
	s_nop 0
	v_cvt_pk_bf16_f32 v2, v6, v7
	v_cvt_pk_bf16_f32 v3, v8, v9
	global_store_dwordx4 v[88:89], v[0:3], off offset:256 sc1
	ds_read_b32 v0, v96 offset:8704
	s_waitcnt lgkmcnt(0)
	v_pk_mul_f32 v[4:5], v[62:63], v[0:1] op_sel_hi:[1,0]
	v_pk_mul_f32 v[2:3], v[60:61], v[0:1] op_sel_hi:[1,0]
	v_pk_mul_f32 v[6:7], v[56:57], v[0:1] op_sel_hi:[1,0]
	v_pk_mul_f32 v[0:1], v[58:59], v[0:1] op_sel_hi:[1,0]
	v_pk_fma_f32 v[2:3], v[66:67], v[2:3], v[134:135]
	v_pk_fma_f32 v[8:9], v[34:35], v[0:1], v[132:133]
	v_cvt_pk_bf16_f32 v0, v2, v3
	v_pk_fma_f32 v[4:5], v[46:47], v[4:5], v[136:137]
	v_pk_fma_f32 v[6:7], v[44:45], v[6:7], v[130:131]
	v_cvt_pk_bf16_f32 v1, v4, v5
	s_nop 0
	v_cvt_pk_bf16_f32 v2, v6, v7
	v_cvt_pk_bf16_f32 v3, v8, v9
	global_store_dwordx4 v[90:91], v[0:3], off offset:256 sc1
	ds_read_b32 v0, v96 offset:8768
	s_waitcnt lgkmcnt(0)
	v_pk_mul_f32 v[4:5], v[78:79], v[0:1] op_sel_hi:[1,0]
	v_pk_mul_f32 v[2:3], v[76:77], v[0:1] op_sel_hi:[1,0]
	v_pk_mul_f32 v[6:7], v[72:73], v[0:1] op_sel_hi:[1,0]
	v_pk_mul_f32 v[0:1], v[74:75], v[0:1] op_sel_hi:[1,0]
	v_pk_fma_f32 v[2:3], v[66:67], v[2:3], v[134:135]
	v_pk_fma_f32 v[8:9], v[34:35], v[0:1], v[132:133]
	v_cvt_pk_bf16_f32 v0, v2, v3
	v_pk_fma_f32 v[4:5], v[46:47], v[4:5], v[136:137]
	v_pk_fma_f32 v[6:7], v[44:45], v[6:7], v[130:131]
	v_cvt_pk_bf16_f32 v1, v4, v5
	s_nop 0
	v_cvt_pk_bf16_f32 v2, v6, v7
	v_cvt_pk_bf16_f32 v3, v8, v9
	global_store_dwordx4 v[80:81], v[0:3], off offset:256 sc1
	ds_read_b32 v0, v96 offset:8832
	s_waitcnt lgkmcnt(0)
	v_pk_mul_f32 v[4:5], v[54:55], v[0:1] op_sel_hi:[1,0]
	v_pk_mul_f32 v[2:3], v[52:53], v[0:1] op_sel_hi:[1,0]
	v_pk_mul_f32 v[6:7], v[48:49], v[0:1] op_sel_hi:[1,0]
	v_pk_mul_f32 v[0:1], v[50:51], v[0:1] op_sel_hi:[1,0]
	v_pk_fma_f32 v[2:3], v[66:67], v[2:3], v[134:135]
	v_pk_fma_f32 v[8:9], v[34:35], v[0:1], v[132:133]
	v_cvt_pk_bf16_f32 v0, v2, v3
	v_pk_fma_f32 v[4:5], v[46:47], v[4:5], v[136:137]
	v_pk_fma_f32 v[6:7], v[44:45], v[6:7], v[130:131]
	v_cvt_pk_bf16_f32 v1, v4, v5
	s_nop 0
	v_cvt_pk_bf16_f32 v2, v6, v7
	v_cvt_pk_bf16_f32 v3, v8, v9
	global_store_dwordx4 v[64:65], v[0:3], off offset:256 sc1
	ds_read_b32 v0, v96 offset:8896
	s_waitcnt lgkmcnt(0)
	v_pk_mul_f32 v[4:5], v[30:31], v[0:1] op_sel_hi:[1,0]
	v_pk_mul_f32 v[2:3], v[28:29], v[0:1] op_sel_hi:[1,0]
	v_pk_mul_f32 v[6:7], v[16:17], v[0:1] op_sel_hi:[1,0]
	v_pk_fma_f32 v[2:3], v[66:67], v[2:3], v[134:135]
	v_pk_mul_f32 v[0:1], v[18:19], v[0:1] op_sel_hi:[1,0]
	v_pk_fma_f32 v[4:5], v[46:47], v[4:5], v[136:137]
	v_pk_fma_f32 v[8:9], v[34:35], v[0:1], v[132:133]
	v_pk_fma_f32 v[6:7], v[44:45], v[6:7], v[130:131]
	v_cvt_pk_bf16_f32 v0, v2, v3
	v_cvt_pk_bf16_f32 v1, v4, v5
	s_nop 0
	v_cvt_pk_bf16_f32 v2, v6, v7
	v_cvt_pk_bf16_f32 v3, v8, v9
	global_store_dwordx4 v[32:33], v[0:3], off offset:256 sc1
	s_waitcnt lgkmcnt(0)
	s_barrier

.LBB0_1416:
	s_cmp_lt_i32 s43, 32
	v_lshl_add_u32 v164, s43, 8, v154
	v_lshl_or_b32 v162, s44, 8, v156
	s_cselect_b32 s2, s87, 0x6000
	s_cselect_b32 s22, s68, s96
	s_cselect_b32 s23, s69, s97
	s_cmp_gt_i32 s43, 15
	v_ashrrev_i32_e32 v165, 31, v164
	s_cselect_b32 s2, s2, 0
	v_ashrrev_i32_e32 v163, 31, v162
	v_lshlrev_b64 v[132:133], 11, v[164:165]
	s_lshl_b32 s2, s2, 2
	v_lshl_add_u64 v[132:133], v[132:133], 0, v[162:163]
	s_add_u32 s2, s49, s2
	v_lshlrev_b64 v[152:153], 2, v[132:133]
	s_addc_u32 s3, s50, 0
	v_lshl_add_u64 v[166:167], s[96:97], 0, v[152:153]
	v_lshl_add_u64 v[130:131], v[162:163], 2, s[2:3]
	global_load_dwordx4 v[142:145], v[130:131], off
	global_load_dwordx4 v[138:141], v[130:131], off offset:64
	global_load_dwordx4 v[134:137], v[130:131], off offset:512
	global_load_dwordx4 v[130:133], v[130:131], off offset:576
	v_lshl_add_u64 v[168:169], s[22:23], 0, v[152:153]
	s_and_b64 vcc, exec, s[0:1]
	s_mov_b64 s[0:1], -1
	v_mov_b64_e32 v[240:241], v[166:167]
	global_load_dwordx4 v[220:223], v[240:241], off
	global_load_dwordx4 v[224:227], v[240:241], off offset:64
	global_load_dwordx4 v[228:231], v[240:241], off offset:512
	global_load_dwordx4 v[232:235], v[240:241], off offset:576
	s_mov_b64 s[2:3], 0x20000
	v_lshl_add_u64 v[240:241], v[166:167], 0, s[2:3]
	global_load_dwordx4 v[236:239], v[240:241], off
	global_load_dwordx4 v[170:173], v[240:241], off offset:64
	global_load_dwordx4 v[174:177], v[240:241], off offset:512
	global_load_dwordx4 v[178:181], v[240:241], off offset:576
	s_mov_b64 s[2:3], 0x40000
	v_lshl_add_u64 v[240:241], v[166:167], 0, s[2:3]
	global_load_dwordx4 v[182:185], v[240:241], off
	global_load_dwordx4 v[186:189], v[240:241], off offset:64
	global_load_dwordx4 v[190:193], v[240:241], off offset:512
	global_load_dwordx4 v[202:205], v[240:241], off offset:576
	s_mov_b64 s[2:3], 0x60000
	v_lshl_add_u64 v[240:241], v[166:167], 0, s[2:3]
	global_load_dwordx4 v[206:209], v[240:241], off
	global_load_dwordx4 v[214:217], v[240:241], off offset:64
	global_load_dwordx4 v[158:161], v[240:241], off offset:512
	s_waitcnt vmcnt(14)
	v_pk_fma_f32 v[222:223], v[128:129], v[144:145], v[222:223]
	v_pk_fma_f32 v[220:221], v[126:127], v[142:143], v[220:221]
	v_mov_b64_e32 v[242:243], v[168:169]
	global_store_dwordx4 v[242:243], v[220:223], off sc1
	s_nop 1
	global_load_dwordx4 v[220:223], v[240:241], off offset:576
	s_waitcnt vmcnt(15)
	v_pk_fma_f32 v[226:227], v[124:125], v[140:141], v[226:227]
	v_pk_fma_f32 v[224:225], v[122:123], v[138:139], v[224:225]
	global_store_dwordx4 v[242:243], v[224:227], off offset:64 sc1
	s_mov_b64 s[2:3], 0x100000
	v_lshl_add_u64 v[240:241], v[166:167], 0, s[2:3]
	global_load_dwordx4 v[224:227], v[240:241], off
	s_waitcnt vmcnt(16)
	v_pk_fma_f32 v[230:231], v[120:121], v[136:137], v[230:231]
	v_pk_fma_f32 v[228:229], v[118:119], v[134:135], v[228:229]
	global_store_dwordx4 v[242:243], v[228:231], off offset:512 sc1
	s_nop 1
	global_load_dwordx4 v[228:231], v[240:241], off offset:64
	s_waitcnt vmcnt(17)
	v_pk_fma_f32 v[234:235], v[108:109], v[132:133], v[234:235]
	v_pk_fma_f32 v[232:233], v[106:107], v[130:131], v[232:233]
	global_store_dwordx4 v[242:243], v[232:235], off offset:576 sc1
	s_nop 1
	global_load_dwordx4 v[232:235], v[240:241], off offset:512
	s_waitcnt vmcnt(18)
	v_pk_fma_f32 v[238:239], v[116:117], v[144:145], v[238:239]
	v_pk_fma_f32 v[236:237], v[114:115], v[142:143], v[236:237]
	s_mov_b64 s[2:3], 0x20000
	v_lshl_add_u64 v[242:243], v[168:169], 0, s[2:3]
	global_store_dwordx4 v[242:243], v[236:239], off sc1
	s_nop 1
	global_load_dwordx4 v[236:239], v[240:241], off offset:576
	s_waitcnt vmcnt(19)
	v_pk_fma_f32 v[172:173], v[112:113], v[140:141], v[172:173]
	v_pk_fma_f32 v[170:171], v[110:111], v[138:139], v[170:171]
	global_store_dwordx4 v[242:243], v[170:173], off offset:64 sc1
	s_mov_b64 s[2:3], 0x120000
	v_lshl_add_u64 v[240:241], v[166:167], 0, s[2:3]
	global_load_dwordx4 v[170:173], v[240:241], off
	s_waitcnt vmcnt(20)
	v_pk_fma_f32 v[176:177], v[104:105], v[136:137], v[176:177]
	v_pk_fma_f32 v[174:175], v[102:103], v[134:135], v[174:175]
	global_store_dwordx4 v[242:243], v[174:177], off offset:512 sc1
	s_nop 1
	global_load_dwordx4 v[174:177], v[240:241], off offset:64
	s_waitcnt vmcnt(21)
	v_pk_fma_f32 v[180:181], v[90:91], v[132:133], v[180:181]
	v_pk_fma_f32 v[178:179], v[88:89], v[130:131], v[178:179]
	global_store_dwordx4 v[242:243], v[178:181], off offset:576 sc1
	s_nop 1
	global_load_dwordx4 v[178:181], v[240:241], off offset:512
	s_waitcnt vmcnt(22)
	v_pk_fma_f32 v[184:185], v[100:101], v[144:145], v[184:185]
	v_pk_fma_f32 v[182:183], v[98:99], v[142:143], v[182:183]
	s_mov_b64 s[2:3], 0x40000
	v_lshl_add_u64 v[242:243], v[168:169], 0, s[2:3]
	global_store_dwordx4 v[242:243], v[182:185], off sc1
	s_nop 1
	global_load_dwordx4 v[182:185], v[240:241], off offset:576
	s_waitcnt vmcnt(23)
	v_pk_fma_f32 v[188:189], v[94:95], v[140:141], v[188:189]
	v_pk_fma_f32 v[186:187], v[92:93], v[138:139], v[186:187]
	global_store_dwordx4 v[242:243], v[186:189], off offset:64 sc1
	s_mov_b64 s[2:3], 0x140000
	v_lshl_add_u64 v[240:241], v[166:167], 0, s[2:3]
	global_load_dwordx4 v[186:189], v[240:241], off
	s_waitcnt vmcnt(24)
	v_pk_fma_f32 v[192:193], v[86:87], v[136:137], v[192:193]
	v_pk_fma_f32 v[190:191], v[84:85], v[134:135], v[190:191]
	global_store_dwordx4 v[242:243], v[190:193], off offset:512 sc1
	s_nop 1
	global_load_dwordx4 v[190:193], v[240:241], off offset:64
	s_waitcnt vmcnt(25)
	v_pk_fma_f32 v[204:205], v[74:75], v[132:133], v[204:205]
	v_pk_fma_f32 v[202:203], v[72:73], v[130:131], v[202:203]
	global_store_dwordx4 v[242:243], v[202:205], off offset:576 sc1
	s_nop 1
	global_load_dwordx4 v[202:205], v[240:241], off offset:512
	s_waitcnt vmcnt(26)
	v_pk_fma_f32 v[208:209], v[82:83], v[144:145], v[208:209]
	v_pk_fma_f32 v[206:207], v[80:81], v[142:143], v[206:207]
	s_mov_b64 s[2:3], 0x60000
	v_lshl_add_u64 v[242:243], v[168:169], 0, s[2:3]
	global_store_dwordx4 v[242:243], v[206:209], off sc1
	s_nop 1
	global_load_dwordx4 v[206:209], v[240:241], off offset:576
	s_waitcnt vmcnt(27)
	v_pk_fma_f32 v[216:217], v[78:79], v[140:141], v[216:217]
	v_pk_fma_f32 v[214:215], v[76:77], v[138:139], v[214:215]
	global_store_dwordx4 v[242:243], v[214:217], off offset:64 sc1
	s_mov_b64 s[2:3], 0x160000
	v_lshl_add_u64 v[240:241], v[166:167], 0, s[2:3]
	global_load_dwordx4 v[214:217], v[240:241], off
	s_waitcnt vmcnt(28)
	v_pk_fma_f32 v[160:161], v[70:71], v[136:137], v[160:161]
	v_pk_fma_f32 v[158:159], v[68:69], v[134:135], v[158:159]
	global_store_dwordx4 v[242:243], v[158:161], off offset:512 sc1
	s_nop 1
	global_load_dwordx4 v[158:161], v[240:241], off offset:64
	s_waitcnt vmcnt(28)
	v_pk_fma_f32 v[222:223], v[66:67], v[132:133], v[222:223]
	v_pk_fma_f32 v[220:221], v[64:65], v[130:131], v[220:221]
	global_store_dwordx4 v[242:243], v[220:223], off offset:576 sc1
	s_nop 1
	global_load_dwordx4 v[220:223], v[240:241], off offset:512
	s_waitcnt vmcnt(28)
	v_pk_fma_f32 v[226:227], v[62:63], v[144:145], v[226:227]
	v_pk_fma_f32 v[224:225], v[60:61], v[142:143], v[224:225]
	s_mov_b64 s[2:3], 0x100000
	v_lshl_add_u64 v[242:243], v[168:169], 0, s[2:3]
	global_store_dwordx4 v[242:243], v[224:227], off sc1
	s_nop 1
	global_load_dwordx4 v[224:227], v[240:241], off offset:576
	s_waitcnt vmcnt(28)
	v_pk_fma_f32 v[230:231], v[58:59], v[140:141], v[230:231]
	v_pk_fma_f32 v[228:229], v[56:57], v[138:139], v[228:229]
	global_store_dwordx4 v[242:243], v[228:231], off offset:64 sc1
	s_waitcnt vmcnt(27)
	v_pk_fma_f32 v[234:235], v[54:55], v[136:137], v[234:235]
	v_pk_fma_f32 v[232:233], v[52:53], v[134:135], v[232:233]
	global_store_dwordx4 v[242:243], v[232:235], off offset:512 sc1
	s_waitcnt vmcnt(26)
	v_pk_fma_f32 v[238:239], v[42:43], v[132:133], v[238:239]
	v_pk_fma_f32 v[236:237], v[40:41], v[130:131], v[236:237]
	global_store_dwordx4 v[242:243], v[236:239], off offset:576 sc1
	s_waitcnt vmcnt(25)
	v_pk_fma_f32 v[172:173], v[50:51], v[144:145], v[172:173]
	v_pk_fma_f32 v[170:171], v[48:49], v[142:143], v[170:171]
	s_mov_b64 s[2:3], 0x120000
	v_lshl_add_u64 v[242:243], v[168:169], 0, s[2:3]
	global_store_dwordx4 v[242:243], v[170:173], off sc1
	s_waitcnt vmcnt(24)
	v_pk_fma_f32 v[176:177], v[46:47], v[140:141], v[176:177]
	v_pk_fma_f32 v[174:175], v[44:45], v[138:139], v[174:175]
	global_store_dwordx4 v[242:243], v[174:177], off offset:64 sc1
	s_waitcnt vmcnt(23)
	v_pk_fma_f32 v[180:181], v[38:39], v[136:137], v[180:181]
	v_pk_fma_f32 v[178:179], v[36:37], v[134:135], v[178:179]
	global_store_dwordx4 v[242:243], v[178:181], off offset:512 sc1
	s_waitcnt vmcnt(22)
	v_pk_fma_f32 v[184:185], v[26:27], v[132:133], v[184:185]
	v_pk_fma_f32 v[182:183], v[24:25], v[130:131], v[182:183]
	global_store_dwordx4 v[242:243], v[182:185], off offset:576 sc1
	s_waitcnt vmcnt(21)
	v_pk_fma_f32 v[188:189], v[34:35], v[144:145], v[188:189]
	v_pk_fma_f32 v[186:187], v[32:33], v[142:143], v[186:187]
	s_mov_b64 s[2:3], 0x140000
	v_lshl_add_u64 v[242:243], v[168:169], 0, s[2:3]
	global_store_dwordx4 v[242:243], v[186:189], off sc1
	s_waitcnt vmcnt(20)
	v_pk_fma_f32 v[192:193], v[30:31], v[140:141], v[192:193]
	v_pk_fma_f32 v[190:191], v[28:29], v[138:139], v[190:191]
	global_store_dwordx4 v[242:243], v[190:193], off offset:64 sc1
	s_waitcnt vmcnt(19)
	v_pk_fma_f32 v[204:205], v[22:23], v[136:137], v[204:205]
	v_pk_fma_f32 v[202:203], v[20:21], v[134:135], v[202:203]
	global_store_dwordx4 v[242:243], v[202:205], off offset:512 sc1
	s_waitcnt vmcnt(18)
	v_pk_fma_f32 v[208:209], v[10:11], v[132:133], v[208:209]
	v_pk_fma_f32 v[206:207], v[8:9], v[130:131], v[206:207]
	global_store_dwordx4 v[242:243], v[206:209], off offset:576 sc1
	s_waitcnt vmcnt(17)
	v_pk_fma_f32 v[216:217], v[18:19], v[144:145], v[216:217]
	v_pk_fma_f32 v[214:215], v[16:17], v[142:143], v[214:215]
	s_mov_b64 s[2:3], 0x160000
	v_lshl_add_u64 v[242:243], v[168:169], 0, s[2:3]
	global_store_dwordx4 v[242:243], v[214:217], off sc1
	s_waitcnt vmcnt(16)
	v_pk_fma_f32 v[160:161], v[14:15], v[140:141], v[160:161]
	v_pk_fma_f32 v[158:159], v[12:13], v[138:139], v[158:159]
	global_store_dwordx4 v[242:243], v[158:161], off offset:64 sc1
	s_waitcnt vmcnt(15)
	v_pk_fma_f32 v[222:223], v[6:7], v[136:137], v[222:223]
	v_pk_fma_f32 v[220:221], v[4:5], v[134:135], v[220:221]
	global_store_dwordx4 v[242:243], v[220:223], off offset:512 sc1
	s_waitcnt vmcnt(14)
	v_pk_fma_f32 v[226:227], v[2:3], v[132:133], v[226:227]
	v_pk_fma_f32 v[224:225], v[0:1], v[130:131], v[224:225]
	global_store_dwordx4 v[242:243], v[224:227], off offset:576 sc1
	s_mov_b64 s[2:3], 0x160000
	s_cbranch_vccnz .LBB0_1401
	s_andn2_b64 vcc, exec, s[8:9]
	s_cbranch_vccnz .LBB0_1400
	s_barrier
	s_branch .LBB0_1400
